# k21 + st_wt: write-through (sc1) stores for row-norm, residual-GEMM and gate/up outputs so the seam leader's L2 write-back is nearly empty
# baseline (speedup 1.0000x reference)
; __device__ __forceinline__ unsigned pk2(float lo, float hi) { return cvtpk(lo, hi); }
; __device__ void phase_hrows(const Params& p, const float* srcp, const float* srcs, const float* gamma, int sh_off, int sc_off, bf16_t* h, int wave) {
;     ...
;         for (int u = 0; u < 2; ++u) { const int g = g0 + u * stride;
;             if (g < NTOK) {
; #pragma unroll
;                 for (int i = 0; i < 4; ++i) ss[u] += v[u][i][0] * v[u][i][0] + v[u][i][1] * v[u][i][1] + v[u][i][2] * v[u][i][2] + v[u][i][3] * v[u][i][3];
; #pragma unroll
;                 for (int o = 32; o >= 1; o >>= 1) ss[u] += __shfl_xor(ss[u], o);
;                 const float r = rsqrtf(ss[u] * (1.f / D) + EPS); const int b = batch_of(g);
; #pragma unroll
;                 for (int i2 = 0; i2 < 2; ++i2) { const int c = lane * 8 + 512 * i2; u32x4 w;
; #pragma unroll
;                     for (int hf = 0; hf < 2; ++hf) { const int cc = c + 4 * hf;
;                         const f32x4 gm = *(const f32x4*)(gamma + cc), sc = *(const f32x4*)(mod + b * MODW + sc_off + cc), sh = *(const f32x4*)(mod + b * MODW + sh_off + cc);
;                         const f32x4 y = v[u][2 * i2 + hf] * r * gm * (sc + 1.f) + sh;
;                         w[2 * hf] = pk2(y[0], y[1]); w[2 * hf + 1] = pk2(y[2], y[3]); }
;                     *(u32x4*)(h + (size_t)g * D + c) = w; } } }
.LBB0_154:
	s_or_b64 exec, exec, s[4:5]
	s_waitcnt vmcnt(2)
	v_mov_b32_e32 v64, v29
	v_mov_b32_e32 v65, v25
	v_min_i32_e32 v47, 0x10000, v59
	v_mov_b32_e32 v62, v28
	v_mov_b32_e32 v63, v24
	v_pk_mul_f32 v[64:65], v[64:65], v[64:65]
	v_ashrrev_i32_e32 v47, 11, v47
	v_pk_fma_f32 v[86:87], v[62:63], v[62:63], v[64:65]
	v_mul_i32_i24_e32 v62, 0x1800, v47
	v_ashrrev_i32_e32 v63, 31, v62
	v_lshl_add_u64 v[78:79], v[62:63], 2, s[10:11]
	v_lshl_add_u64 v[88:89], v[78:79], 0, s[18:19]
	v_lshl_add_u64 v[74:75], v[88:89], 0, v[34:35]
	global_load_dwordx4 v[62:65], v[36:37], off offset:16
	global_load_dwordx4 v[66:69], v[36:37], off
	global_load_dwordx4 v[70:73], v[74:75], off offset:16
	s_nop 0
	global_load_dwordx4 v[74:77], v[74:75], off
	v_lshl_add_u64 v[92:93], v[78:79], 0, v[34:35]
	global_load_dwordx4 v[78:81], v[92:93], off offset:16
	global_load_dwordx4 v[82:85], v[92:93], off
	v_mov_b32_e32 v90, v30
	v_mov_b32_e32 v91, v26
	v_pk_fma_f32 v[86:87], v[90:91], v[90:91], v[86:87]
	v_mov_b32_e32 v90, v31
	v_mov_b32_e32 v91, v27
	s_waitcnt vmcnt(6)
	v_mov_b32_e32 v94, v21
	v_mov_b32_e32 v95, v17
	v_pk_fma_f32 v[86:87], v[90:91], v[90:91], v[86:87]
	v_mov_b32_e32 v90, v20
	v_mov_b32_e32 v91, v16
	v_pk_mul_f32 v[94:95], v[94:95], v[94:95]
	v_add_f32_e32 v47, v86, v87
	v_pk_fma_f32 v[90:91], v[90:91], v[90:91], v[94:95]
	v_mov_b32_e32 v94, v22
	v_mov_b32_e32 v95, v18
	v_pk_fma_f32 v[90:91], v[94:95], v[94:95], v[90:91]
	v_mov_b32_e32 v94, v23
	v_mov_b32_e32 v95, v19
	v_pk_fma_f32 v[90:91], v[94:95], v[94:95], v[90:91]
	v_lshl_add_u64 v[86:87], v[44:45], 0, v[38:39]
	v_add_f32_e32 v47, v47, v90
	v_add_f32_e32 v47, v47, v91
	ds_bpermute_b32 v61, v48, v47
	v_add_co_u32_e64 v86, s[4:5], s25, v86
	s_waitcnt lgkmcnt(0)
	v_add_f32_e32 v47, v47, v61
	ds_bpermute_b32 v61, v49, v47
	v_addc_co_u32_e64 v87, s[4:5], 0, v87, s[4:5]
	s_waitcnt lgkmcnt(0)
	v_add_f32_e32 v47, v47, v61
	ds_bpermute_b32 v61, v50, v47
	s_waitcnt lgkmcnt(0)
	v_add_f32_e32 v47, v47, v61
	ds_bpermute_b32 v61, v51, v47
	s_waitcnt lgkmcnt(0)
	v_add_f32_e32 v47, v47, v61
	ds_bpermute_b32 v61, v52, v47
	s_waitcnt lgkmcnt(0)
	v_add_f32_e32 v61, v47, v61
	ds_bpermute_b32 v90, v53, v61
	v_mov_b32_e32 v47, v35
	s_waitcnt lgkmcnt(0)
	v_add_f32_e32 v61, v61, v90
	v_fmamk_f32 v61, v61, 0x3a800000, v58
	v_mul_f32_e32 v90, 0x4b800000, v61
	v_cmp_gt_f32_e64 s[0:1], s24, v61
	s_nop 1
	v_cndmask_b32_e64 v61, v61, v90, s[0:1]
	v_rsq_f32_e32 v61, v61
	s_nop 0
	v_mul_f32_e32 v90, 0x45800000, v61
	v_cndmask_b32_e64 v90, v61, v90, s[0:1]
	v_pk_mul_f32 v[30:31], v[30:31], v[90:91] op_sel_hi:[1,0]
	v_pk_mul_f32 v[28:29], v[28:29], v[90:91] op_sel_hi:[1,0]
	v_pk_mul_f32 v[26:27], v[26:27], v[90:91] op_sel_hi:[1,0]
	v_pk_mul_f32 v[24:25], v[24:25], v[90:91] op_sel_hi:[1,0]
	v_pk_mul_f32 v[22:23], v[22:23], v[90:91] op_sel_hi:[1,0]
	s_waitcnt vmcnt(5)
	v_pk_mul_f32 v[24:25], v[62:63], v[24:25]
	s_waitcnt vmcnt(4)
	v_pk_mul_f32 v[28:29], v[66:67], v[28:29]
	v_pk_mul_f32 v[30:31], v[68:69], v[30:31]
	v_pk_mul_f32 v[26:27], v[64:65], v[26:27]
	s_waitcnt vmcnt(2)
	v_pk_add_f32 v[62:63], v[76:77], 1.0 op_sel_hi:[1,0]
	v_pk_add_f32 v[64:65], v[74:75], 1.0 op_sel_hi:[1,0]
	v_pk_add_f32 v[66:67], v[72:73], 1.0 op_sel_hi:[1,0]
	v_pk_add_f32 v[68:69], v[70:71], 1.0 op_sel_hi:[1,0]
	s_waitcnt vmcnt(0)
	v_pk_fma_f32 v[30:31], v[62:63], v[30:31], v[84:85]
	v_pk_fma_f32 v[28:29], v[64:65], v[28:29], v[82:83]
	v_pk_fma_f32 v[62:63], v[66:67], v[26:27], v[80:81]
	v_pk_fma_f32 v[26:27], v[68:69], v[24:25], v[78:79]
	v_cvt_pk_bf16_f32 v24, v28, v29
	v_cvt_pk_bf16_f32 v25, v30, v31
	v_cvt_pk_bf16_f32 v26, v26, v27
	v_cvt_pk_bf16_f32 v27, v62, v63
	global_store_dwordx4 v[86:87], v[24:27], off sc1
	global_load_dwordx4 v[24:27], v[36:37], off offset:2048
	v_lshl_add_u64 v[66:67], v[88:89], 0, v[46:47]
	global_load_dwordx4 v[28:31], v[66:67], off
	global_load_dwordx4 v[62:65], v[36:37], off offset:2064
	s_nop 0
	global_load_dwordx4 v[66:69], v[66:67], off offset:16
	s_nop 0
	global_load_dwordx4 v[70:73], v[92:93], off offset:2048
	global_load_dwordx4 v[74:77], v[92:93], off offset:2064
	v_pk_mul_f32 v[20:21], v[20:21], v[90:91] op_sel_hi:[1,0]
	v_pk_mul_f32 v[18:19], v[18:19], v[90:91] op_sel_hi:[1,0]
	v_pk_mul_f32 v[16:17], v[16:17], v[90:91] op_sel_hi:[1,0]
	s_waitcnt vmcnt(3)
	v_pk_mul_f32 v[18:19], v[64:65], v[18:19]
	v_pk_mul_f32 v[20:21], v[24:25], v[20:21]
	v_pk_mul_f32 v[22:23], v[26:27], v[22:23]
	v_pk_add_f32 v[24:25], v[30:31], 1.0 op_sel_hi:[1,0]
	v_pk_add_f32 v[26:27], v[28:29], 1.0 op_sel_hi:[1,0]
	v_pk_mul_f32 v[16:17], v[62:63], v[16:17]
	s_waitcnt vmcnt(2)
	v_pk_add_f32 v[28:29], v[68:69], 1.0 op_sel_hi:[1,0]
	v_pk_add_f32 v[30:31], v[66:67], 1.0 op_sel_hi:[1,0]
	s_waitcnt vmcnt(1)
	v_pk_fma_f32 v[22:23], v[24:25], v[22:23], v[72:73]
	v_pk_fma_f32 v[20:21], v[26:27], v[20:21], v[70:71]
	s_waitcnt vmcnt(0)
	v_pk_fma_f32 v[24:25], v[28:29], v[18:19], v[76:77]
	v_pk_fma_f32 v[18:19], v[30:31], v[16:17], v[74:75]
	v_cvt_pk_bf16_f32 v16, v20, v21
	v_cvt_pk_bf16_f32 v17, v22, v23
	v_cvt_pk_bf16_f32 v18, v18, v19
	v_cvt_pk_bf16_f32 v19, v24, v25
	global_store_dwordx4 v[86:87], v[16:19], off offset:1024 sc1
	s_and_saveexec_b64 s[4:5], vcc
	s_cbranch_execz .LBB0_151
; __device__ __forceinline__ unsigned pk2(float lo, float hi) { return cvtpk(lo, hi); }
; __device__ void phase_hrows(const Params& p, const float* srcp, const float* srcs, const float* gamma, int sh_off, int sc_off, bf16_t* h, int wave) {
;     ...
;         for (int u = 0; u < 2; ++u) { const int g = g0 + u * stride;
;             if (g < NTOK) {
; #pragma unroll
;                 for (int i = 0; i < 4; ++i) ss[u] += v[u][i][0] * v[u][i][0] + v[u][i][1] * v[u][i][1] + v[u][i][2] * v[u][i][2] + v[u][i][3] * v[u][i][3];
; #pragma unroll
;                 for (int o = 32; o >= 1; o >>= 1) ss[u] += __shfl_xor(ss[u], o);
;                 const float r = rsqrtf(ss[u] * (1.f / D) + EPS); const int b = batch_of(g);
; #pragma unroll
;                 for (int i2 = 0; i2 < 2; ++i2) { const int c = lane * 8 + 512 * i2; u32x4 w;
; #pragma unroll
;                     for (int hf = 0; hf < 2; ++hf) { const int cc = c + 4 * hf;
;                         const f32x4 gm = *(const f32x4*)(gamma + cc), sc = *(const f32x4*)(mod + b * MODW + sc_off + cc), sh = *(const f32x4*)(mod + b * MODW + sh_off + cc);
;                         const f32x4 y = v[u][2 * i2 + hf] * r * gm * (sc + 1.f) + sh;
;                         w[2 * hf] = pk2(y[0], y[1]); w[2 * hf + 1] = pk2(y[2], y[3]); }
;                     *(u32x4*)(h + (size_t)g * D + c) = w; } } }
	v_mov_b32_e32 v18, v1
	v_mov_b32_e32 v19, v5
	v_mov_b32_e32 v16, v0
	v_mov_b32_e32 v17, v4
	v_pk_mul_f32 v[18:19], v[18:19], v[18:19]
	v_mov_b32_e32 v72, v2
	v_pk_fma_f32 v[68:69], v[16:17], v[16:17], v[18:19]
	v_min_i32_e32 v16, 0x10000, v60
	v_ashrrev_i32_e32 v16, 11, v16
	v_mul_i32_i24_e32 v16, 0x1800, v16
	v_ashrrev_i32_e32 v17, 31, v16
	v_lshl_add_u64 v[60:61], v[16:17], 2, s[10:11]
	v_lshl_add_u64 v[70:71], v[60:61], 0, s[18:19]
	v_lshl_add_u64 v[28:29], v[70:71], 0, v[34:35]
	global_load_dwordx4 v[16:19], v[36:37], off offset:16
	global_load_dwordx4 v[20:23], v[36:37], off
	global_load_dwordx4 v[24:27], v[28:29], off offset:16
	s_nop 0
	global_load_dwordx4 v[28:31], v[28:29], off
	v_lshl_add_u64 v[74:75], v[60:61], 0, v[34:35]
	global_load_dwordx4 v[60:63], v[74:75], off offset:16
	global_load_dwordx4 v[64:67], v[74:75], off
	v_mov_b32_e32 v73, v6
	v_pk_fma_f32 v[68:69], v[72:73], v[72:73], v[68:69]
	v_mov_b32_e32 v72, v3
	v_mov_b32_e32 v73, v7
	v_mov_b32_e32 v76, v9
	v_mov_b32_e32 v77, v13
	v_pk_fma_f32 v[68:69], v[72:73], v[72:73], v[68:69]
	v_mov_b32_e32 v72, v8
	v_mov_b32_e32 v73, v12
	v_pk_mul_f32 v[76:77], v[76:77], v[76:77]
	v_add_f32_e32 v68, v68, v69
	v_pk_fma_f32 v[72:73], v[72:73], v[72:73], v[76:77]
	v_mov_b32_e32 v76, v10
	v_mov_b32_e32 v77, v14
	v_pk_fma_f32 v[72:73], v[76:77], v[76:77], v[72:73]
	v_mov_b32_e32 v76, v11
	v_mov_b32_e32 v77, v15
	v_pk_fma_f32 v[72:73], v[76:77], v[76:77], v[72:73]
	s_waitcnt vmcnt(3)
	v_pk_add_f32 v[26:27], v[26:27], 1.0 op_sel_hi:[1,0]
	v_add_f32_e32 v68, v73, v68
	v_add_f32_e32 v68, v72, v68
	ds_bpermute_b32 v69, v48, v68
	s_waitcnt vmcnt(2)
	v_pk_add_f32 v[30:31], v[30:31], 1.0 op_sel_hi:[1,0]
	v_pk_add_f32 v[28:29], v[28:29], 1.0 op_sel_hi:[1,0]
	v_pk_add_f32 v[24:25], v[24:25], 1.0 op_sel_hi:[1,0]
	s_waitcnt lgkmcnt(0)
	v_add_f32_e32 v68, v68, v69
	ds_bpermute_b32 v69, v49, v68
	s_waitcnt lgkmcnt(0)
	v_add_f32_e32 v68, v68, v69
	ds_bpermute_b32 v69, v50, v68
	s_waitcnt lgkmcnt(0)
	v_add_f32_e32 v68, v68, v69
	ds_bpermute_b32 v69, v51, v68
	s_waitcnt lgkmcnt(0)
	v_add_f32_e32 v68, v68, v69
	ds_bpermute_b32 v69, v52, v68
	s_waitcnt lgkmcnt(0)
	v_add_f32_e32 v72, v68, v69
	ds_bpermute_b32 v73, v53, v72
	v_lshl_add_u64 v[68:69], v[42:43], 0, v[38:39]
	v_add_co_u32_e64 v68, s[0:1], s25, v68
	s_waitcnt lgkmcnt(0)
	v_add_f32_e32 v72, v72, v73
	v_fmamk_f32 v72, v72, 0x3a800000, v58
	v_mul_f32_e32 v73, 0x4b800000, v72
	v_cmp_gt_f32_e32 vcc, s24, v72
	v_addc_co_u32_e64 v69, s[0:1], 0, v69, s[0:1]
	s_nop 0
	v_cndmask_b32_e32 v72, v72, v73, vcc
	v_rsq_f32_e32 v72, v72
	s_nop 0
	v_mul_f32_e32 v73, 0x45800000, v72
	v_cndmask_b32_e32 v72, v72, v73, vcc
	v_pk_mul_f32 v[76:77], v[6:7], v[72:73] op_sel_hi:[1,0]
	v_pk_mul_f32 v[78:79], v[4:5], v[72:73] op_sel_hi:[1,0]
	v_pk_mul_f32 v[80:81], v[2:3], v[72:73] op_sel_hi:[1,0]
	v_pk_mul_f32 v[82:83], v[0:1], v[72:73] op_sel_hi:[1,0]
	v_pk_mul_f32 v[20:21], v[20:21], v[78:79]
	v_pk_mul_f32 v[22:23], v[22:23], v[76:77]
	v_pk_mul_f32 v[16:17], v[16:17], v[82:83]
	v_pk_mul_f32 v[18:19], v[18:19], v[80:81]
	s_waitcnt vmcnt(0)
	v_pk_fma_f32 v[22:23], v[30:31], v[22:23], v[66:67]
	v_pk_fma_f32 v[20:21], v[28:29], v[20:21], v[64:65]
	v_pk_fma_f32 v[26:27], v[26:27], v[18:19], v[62:63]
	v_pk_fma_f32 v[18:19], v[24:25], v[16:17], v[60:61]
	v_cvt_pk_bf16_f32 v16, v20, v21
	v_cvt_pk_bf16_f32 v17, v22, v23
	v_cvt_pk_bf16_f32 v18, v18, v19
	v_cvt_pk_bf16_f32 v19, v26, v27
	global_store_dwordx4 v[68:69], v[16:19], off sc1
	global_load_dwordx4 v[16:19], v[36:37], off offset:2048
	v_lshl_add_u64 v[28:29], v[70:71], 0, v[46:47]
	global_load_dwordx4 v[20:23], v[28:29], off
	global_load_dwordx4 v[24:27], v[36:37], off offset:2064
	s_nop 0
	global_load_dwordx4 v[28:31], v[28:29], off offset:16
	s_nop 0
	global_load_dwordx4 v[60:63], v[74:75], off offset:2048
	global_load_dwordx4 v[64:67], v[74:75], off offset:2064
	v_pk_mul_f32 v[70:71], v[14:15], v[72:73] op_sel_hi:[1,0]
	v_pk_mul_f32 v[74:75], v[12:13], v[72:73] op_sel_hi:[1,0]
	v_pk_mul_f32 v[76:77], v[10:11], v[72:73] op_sel_hi:[1,0]
	v_pk_mul_f32 v[72:73], v[8:9], v[72:73] op_sel_hi:[1,0]
	s_waitcnt vmcnt(4)
	v_pk_add_f32 v[22:23], v[22:23], 1.0 op_sel_hi:[1,0]
	v_pk_add_f32 v[20:21], v[20:21], 1.0 op_sel_hi:[1,0]
	v_pk_mul_f32 v[16:17], v[16:17], v[74:75]
	v_pk_mul_f32 v[18:19], v[18:19], v[70:71]
	s_waitcnt vmcnt(3)
	v_pk_mul_f32 v[24:25], v[24:25], v[72:73]
	v_pk_mul_f32 v[26:27], v[26:27], v[76:77]
	s_waitcnt vmcnt(2)
	v_pk_add_f32 v[30:31], v[30:31], 1.0 op_sel_hi:[1,0]
	v_pk_add_f32 v[28:29], v[28:29], 1.0 op_sel_hi:[1,0]
	s_waitcnt vmcnt(1)
	v_pk_fma_f32 v[18:19], v[22:23], v[18:19], v[62:63]
	v_pk_fma_f32 v[16:17], v[20:21], v[16:17], v[60:61]
	s_waitcnt vmcnt(0)
	v_pk_fma_f32 v[20:21], v[30:31], v[26:27], v[66:67]
	v_pk_fma_f32 v[22:23], v[28:29], v[24:25], v[64:65]
	v_cvt_pk_bf16_f32 v16, v16, v17
	v_cvt_pk_bf16_f32 v17, v18, v19
	v_cvt_pk_bf16_f32 v18, v22, v23
	v_cvt_pk_bf16_f32 v19, v20, v21
	global_store_dwordx4 v[68:69], v[16:19], off offset:1024 sc1
	s_branch .LBB0_151

; #define PG8_STAGE(bufoff, gbase, voff) do { _Pragma("unroll") for (int _i = 0; _i < 2; ++_i) \
;         __builtin_amdgcn_global_load_lds((const unsigned*)((const char*)(gbase) + (voff)[_i]), (LAS unsigned*)(lds + (bufoff) + ldsw + _i * 8192), 16, 0, 0); } while (0)
; #define PG8_LDA(dst, b, h) do { _Pragma("unroll") for (int m = 0; m < 4; ++m) _Pragma("unroll") for (int k = 0; k < 2; ++k) dst[m][k] = *(const LAS bf16x8*)(lds + PG8_SA(b, h) + aoff + m * 2048 + k * 1024); } while (0)
; #define PG8_LDB(dst, b, h) do { _Pragma("unroll") for (int n = 0; n < 2; ++n) _Pragma("unroll") for (int k = 0; k < 2; ++k) dst[n][k] = *(const LAS bf16x8*)(lds + PG8_SB(b, h) + boff + n * 2048 + k * 1024); } while (0)
; #define PG8_MMA(ai, bj, At, Bt) do { __builtin_amdgcn_s_setprio(1); _Pragma("unroll") for (int m = 0; m < 4; ++m) _Pragma("unroll") for (int n = 0; n < 2; ++n) _Pragma("unroll") for (int k = 0; k < 2; ++k) \
;         acc[ai][bj][m][n] = __builtin_amdgcn_mfma_f32_16x16x32_bf16(Bt[n][k], At[m][k], acc[ai][bj][m][n], 0, 0, 0); __builtin_amdgcn_s_setprio(0); } while (0)
; #define PG8_WAIT_V(n) asm volatile("s_waitcnt vmcnt(" #n ")" ::: "memory")
; #define PG8_WAIT_L(n) asm volatile("s_waitcnt lgkmcnt(" #n ")" ::: "memory")
; #define PG8_BAR __builtin_amdgcn_s_barrier()
; #define PG8_SCHED __builtin_amdgcn_sched_barrier(0)
; template <class Epi>
; __device__ __forceinline__ void gemm_phase(LAS unsigned char* lds, const Gemm g, const StaticOrder& S, const Epi& E, int wave) {
;     ...
;             PG8_LDB(B0, 0, 0); PG8_SCHED; PG8_LDA(At, 0, 0); PG8_STAGE(PG8_SA(1, 1), a1 + hstep, voffA);
;             PG8_WAIT_L(8); PG8_BAR; PG8_WAIT_L(0); PG8_MMA(0, 0, At, B0); PG8_BAR; PG8_SCHED;
;             PG8_LDB(B1, 0, 1); PG8_STAGE(PG8_SB(0, 0), b2, voffB);
;             PG8_BAR; PG8_WAIT_L(0); PG8_MMA(0, 1, At, B1); PG8_BAR;
;             PG8_LDA(At, 0, 1); PG8_STAGE(PG8_SA(0, 0), a2, voffA);
;             PG8_BAR; PG8_WAIT_L(0); PG8_MMA(1, 0, At, B0); PG8_BAR; PG8_SCHED;
;             PG8_STAGE(PG8_SB(0, 1), b2 + hstep, voffB);
;             PG8_WAIT_V(6); PG8_BAR; PG8_MMA(1, 1, At, B1); PG8_BAR;
.LBB0_767:
	ds_read_b128 v[128:131], v163
	ds_read_b128 v[132:135], v163 offset:1024
	ds_read_b128 v[136:139], v163 offset:2048
	ds_read_b128 v[140:143], v163 offset:3072
	s_add_u32 s28, s26, 0x100
	s_addc_u32 s29, s27, 0
	s_cmp_eq_u32 s62, 12
	s_cselect_b32 s35, s19, s29
	s_cselect_b32 s34, s58, s28
	s_cselect_b32 s31, s17, s61
	s_cselect_b32 s30, s59, s60
	v_lshl_add_u64 v[160:161], s[26:27], 0, v[148:149]
	s_add_i32 m0, s25, 0xc000
	ds_read_b128 v[156:159], v164
	ds_read_b128 v[166:169], v164 offset:1024
	ds_read_b128 v[170:173], v164 offset:2048
	ds_read_b128 v[174:177], v164 offset:3072
	ds_read_b128 v[178:181], v164 offset:4096
	ds_read_b128 v[182:185], v164 offset:5120
	ds_read_b128 v[186:189], v164 offset:6144
	ds_read_b128 v[190:193], v164 offset:7168
	global_load_lds_dwordx4 v[160:161], off
	v_lshl_add_u64 v[160:161], s[26:27], 0, v[150:151]
	s_add_i32 m0, s25, 0xe000
	s_nop 0
	global_load_lds_dwordx4 v[160:161], off
	s_waitcnt lgkmcnt(8)
	s_barrier
	s_waitcnt lgkmcnt(0)
	s_setprio 1
	s_waitcnt lgkmcnt(0)
	v_mfma_f32_16x16x32_bf16 v[124:127], v[128:131], v[156:159], v[124:127]
	v_mfma_f32_16x16x32_bf16 v[120:123], v[136:139], v[156:159], v[120:123]
	v_mfma_f32_16x16x32_bf16 v[116:119], v[128:131], v[170:173], v[116:119]
	v_mfma_f32_16x16x32_bf16 v[112:115], v[136:139], v[170:173], v[112:115]
	v_mfma_f32_16x16x32_bf16 v[108:111], v[128:131], v[178:181], v[108:111]
	v_mfma_f32_16x16x32_bf16 v[96:99], v[136:139], v[178:181], v[96:99]
	v_mfma_f32_16x16x32_bf16 v[84:87], v[128:131], v[186:189], v[84:87]
	v_mfma_f32_16x16x32_bf16 v[72:75], v[136:139], v[186:189], v[72:75]
	v_mfma_f32_16x16x32_bf16 v[124:127], v[132:135], v[166:169], v[124:127]
	v_mfma_f32_16x16x32_bf16 v[120:123], v[140:143], v[166:169], v[120:123]
	v_mfma_f32_16x16x32_bf16 v[116:119], v[132:135], v[174:177], v[116:119]
	v_mfma_f32_16x16x32_bf16 v[112:115], v[140:143], v[174:177], v[112:115]
	v_mfma_f32_16x16x32_bf16 v[108:111], v[132:135], v[182:185], v[108:111]
	v_mfma_f32_16x16x32_bf16 v[96:99], v[140:143], v[182:185], v[96:99]
	v_mfma_f32_16x16x32_bf16 v[84:87], v[132:135], v[190:193], v[84:87]
	v_mfma_f32_16x16x32_bf16 v[72:75], v[140:143], v[190:193], v[72:75]
	s_setprio 0
	s_barrier
	s_add_i32 s26, s55, s39
	v_lshl_add_u64 v[160:161], s[30:31], 0, v[146:147]
	s_mov_b32 m0, s26
	ds_read_b128 v[194:197], v165
	ds_read_b128 v[198:201], v165 offset:1024
	ds_read_b128 v[202:205], v165 offset:2048
	ds_read_b128 v[206:209], v165 offset:3072
	global_load_lds_dwordx4 v[160:161], off
	v_lshl_add_u64 v[210:211], s[30:31], 0, v[144:145]
	s_add_i32 m0, s26, 0x2000
	s_nop 0
	global_load_lds_dwordx4 v[210:211], off
	s_barrier
	s_waitcnt lgkmcnt(0)
	s_setprio 1
	s_waitcnt lgkmcnt(0)
	v_mfma_f32_16x16x32_bf16 v[104:107], v[194:197], v[156:159], v[104:107]
	v_mfma_f32_16x16x32_bf16 v[100:103], v[202:205], v[156:159], v[100:103]
	v_mfma_f32_16x16x32_bf16 v[92:95], v[194:197], v[170:173], v[92:95]
	v_mfma_f32_16x16x32_bf16 v[88:91], v[202:205], v[170:173], v[88:91]
	v_mfma_f32_16x16x32_bf16 v[80:83], v[194:197], v[178:181], v[80:83]
	v_mfma_f32_16x16x32_bf16 v[76:79], v[202:205], v[178:181], v[76:79]
	v_mfma_f32_16x16x32_bf16 v[68:71], v[194:197], v[186:189], v[68:71]
	v_mfma_f32_16x16x32_bf16 v[64:67], v[202:205], v[186:189], v[64:67]
	v_mfma_f32_16x16x32_bf16 v[104:107], v[198:201], v[166:169], v[104:107]
	v_mfma_f32_16x16x32_bf16 v[100:103], v[206:209], v[166:169], v[100:103]
	v_mfma_f32_16x16x32_bf16 v[92:95], v[198:201], v[174:177], v[92:95]
	v_mfma_f32_16x16x32_bf16 v[88:91], v[206:209], v[174:177], v[88:91]
	v_mfma_f32_16x16x32_bf16 v[80:83], v[198:201], v[182:185], v[80:83]
	v_mfma_f32_16x16x32_bf16 v[76:79], v[206:209], v[182:185], v[76:79]
	v_mfma_f32_16x16x32_bf16 v[68:71], v[198:201], v[190:193], v[68:71]
	v_mfma_f32_16x16x32_bf16 v[64:67], v[206:209], v[190:193], v[64:67]
	s_setprio 0
	s_mov_b32 m0, s25
	v_lshl_add_u64 v[212:213], s[34:35], 0, v[146:147]
	s_barrier
	ds_read_b128 v[156:159], v164 offset:16384
	ds_read_b128 v[166:169], v164 offset:17408
	ds_read_b128 v[170:173], v164 offset:18432
	ds_read_b128 v[174:177], v164 offset:19456
	ds_read_b128 v[178:181], v164 offset:20480
	ds_read_b128 v[182:185], v164 offset:21504
	ds_read_b128 v[186:189], v164 offset:22528
	ds_read_b128 v[190:193], v164 offset:23552
	global_load_lds_dwordx4 v[212:213], off
	v_lshl_add_u64 v[214:215], s[34:35], 0, v[144:145]
	s_mov_b32 m0, s42
	s_nop 0
	global_load_lds_dwordx4 v[214:215], off
	s_barrier
	s_waitcnt lgkmcnt(0)
	s_setprio 1
	s_waitcnt lgkmcnt(0)
	v_mfma_f32_16x16x32_bf16 v[60:63], v[128:131], v[156:159], v[60:63]
	v_mfma_f32_16x16x32_bf16 v[56:59], v[136:139], v[156:159], v[56:59]
	v_mfma_f32_16x16x32_bf16 v[52:55], v[128:131], v[170:173], v[52:55]
	v_mfma_f32_16x16x32_bf16 v[48:51], v[136:139], v[170:173], v[48:51]
	v_mfma_f32_16x16x32_bf16 v[44:47], v[128:131], v[178:181], v[44:47]
	v_mfma_f32_16x16x32_bf16 v[32:35], v[136:139], v[178:181], v[32:35]
	v_mfma_f32_16x16x32_bf16 v[20:23], v[128:131], v[186:189], v[20:23]
	v_mfma_f32_16x16x32_bf16 v[8:11], v[136:139], v[186:189], v[8:11]
	v_mfma_f32_16x16x32_bf16 v[60:63], v[132:135], v[166:169], v[60:63]
	v_mfma_f32_16x16x32_bf16 v[56:59], v[140:143], v[166:169], v[56:59]
	v_mfma_f32_16x16x32_bf16 v[52:55], v[132:135], v[174:177], v[52:55]
	v_mfma_f32_16x16x32_bf16 v[48:51], v[140:143], v[174:177], v[48:51]
	v_mfma_f32_16x16x32_bf16 v[44:47], v[132:135], v[182:185], v[44:47]
	v_mfma_f32_16x16x32_bf16 v[32:35], v[140:143], v[182:185], v[32:35]
	v_mfma_f32_16x16x32_bf16 v[20:23], v[132:135], v[190:193], v[20:23]
	v_mfma_f32_16x16x32_bf16 v[8:11], v[140:143], v[190:193], v[8:11]
	s_setprio 0
	s_barrier
; #define PG8_STAGE(bufoff, gbase, voff) do { _Pragma("unroll") for (int _i = 0; _i < 2; ++_i) \
;         __builtin_amdgcn_global_load_lds((const unsigned*)((const char*)(gbase) + (voff)[_i]), (LAS unsigned*)(lds + (bufoff) + ldsw + _i * 8192), 16, 0, 0); } while (0)
; #define PG8_LDA(dst, b, h) do { _Pragma("unroll") for (int m = 0; m < 4; ++m) _Pragma("unroll") for (int k = 0; k < 2; ++k) dst[m][k] = *(const LAS bf16x8*)(lds + PG8_SA(b, h) + aoff + m * 2048 + k * 1024); } while (0)
; #define PG8_LDB(dst, b, h) do { _Pragma("unroll") for (int n = 0; n < 2; ++n) _Pragma("unroll") for (int k = 0; k < 2; ++k) dst[n][k] = *(const LAS bf16x8*)(lds + PG8_SB(b, h) + boff + n * 2048 + k * 1024); } while (0)
; #define PG8_MMA(ai, bj, At, Bt) do { __builtin_amdgcn_s_setprio(1); _Pragma("unroll") for (int m = 0; m < 4; ++m) _Pragma("unroll") for (int n = 0; n < 2; ++n) _Pragma("unroll") for (int k = 0; k < 2; ++k) \
;         acc[ai][bj][m][n] = __builtin_amdgcn_mfma_f32_16x16x32_bf16(Bt[n][k], At[m][k], acc[ai][bj][m][n], 0, 0, 0); __builtin_amdgcn_s_setprio(0); } while (0)
; #define PG8_WAIT_V(n) asm volatile("s_waitcnt vmcnt(" #n ")" ::: "memory")
; #define PG8_WAIT_L(n) asm volatile("s_waitcnt lgkmcnt(" #n ")" ::: "memory")
; #define PG8_BAR __builtin_amdgcn_s_barrier()
; #define PG8_SCHED __builtin_amdgcn_sched_barrier(0)
; template <class Epi>
; __device__ __forceinline__ void gemm_phase(LAS unsigned char* lds, const Gemm g, const StaticOrder& S, const Epi& E, int wave) {
;     ...
;             PG8_WAIT_V(6); PG8_BAR; PG8_MMA(1, 1, At, B1); PG8_BAR;
;             PG8_LDB(B0, 1, 0); PG8_SCHED; PG8_LDA(At, 1, 0); PG8_STAGE(PG8_SA(0, 1), a2 + hstep, voffA);
;             PG8_WAIT_L(8); PG8_BAR; PG8_WAIT_L(0); PG8_MMA(0, 0, At, B0); PG8_BAR; PG8_SCHED;
;             PG8_LDB(B1, 1, 1); PG8_STAGE(PG8_SB(1, 0), b3, voffB);
;             PG8_BAR; PG8_WAIT_L(0); PG8_MMA(0, 1, At, B1); PG8_BAR;
;             PG8_LDA(At, 1, 1); PG8_STAGE(PG8_SA(1, 0), a3, voffA);
;             PG8_BAR; PG8_WAIT_L(0); PG8_MMA(1, 0, At, B0); PG8_BAR; PG8_SCHED;
	s_add_u32 s26, s30, 0x40000
	s_addc_u32 s27, s31, 0
	s_add_i32 s63, s56, s39
	v_lshl_add_u64 v[128:129], s[26:27], 0, v[146:147]
	s_mov_b32 m0, s63
	s_nop 0
	global_load_lds_dwordx4 v[128:129], off
	v_lshl_add_u64 v[128:129], s[26:27], 0, v[144:145]
	s_add_i32 m0, s63, 0x2000
	s_nop 0
	global_load_lds_dwordx4 v[128:129], off
	s_waitcnt vmcnt(6)
	s_barrier
	s_setprio 1
	v_mfma_f32_16x16x32_bf16 v[40:43], v[194:197], v[156:159], v[40:43]
	v_mfma_f32_16x16x32_bf16 v[36:39], v[202:205], v[156:159], v[36:39]
	v_mfma_f32_16x16x32_bf16 v[28:31], v[194:197], v[170:173], v[28:31]
	v_mfma_f32_16x16x32_bf16 v[24:27], v[202:205], v[170:173], v[24:27]
	v_mfma_f32_16x16x32_bf16 v[16:19], v[194:197], v[178:181], v[16:19]
	v_mfma_f32_16x16x32_bf16 v[12:15], v[202:205], v[178:181], v[12:15]
	v_mfma_f32_16x16x32_bf16 v[4:7], v[194:197], v[186:189], v[4:7]
	v_mfma_f32_16x16x32_bf16 v[0:3], v[202:205], v[186:189], v[0:3]
	v_mfma_f32_16x16x32_bf16 v[40:43], v[198:201], v[166:169], v[40:43]
	v_mfma_f32_16x16x32_bf16 v[36:39], v[206:209], v[166:169], v[36:39]
	v_mfma_f32_16x16x32_bf16 v[28:31], v[198:201], v[174:177], v[28:31]
	v_mfma_f32_16x16x32_bf16 v[24:27], v[206:209], v[174:177], v[24:27]
	v_mfma_f32_16x16x32_bf16 v[16:19], v[198:201], v[182:185], v[16:19]
	v_mfma_f32_16x16x32_bf16 v[12:15], v[206:209], v[182:185], v[12:15]
	v_mfma_f32_16x16x32_bf16 v[4:7], v[198:201], v[190:193], v[4:7]
	v_mfma_f32_16x16x32_bf16 v[0:3], v[206:209], v[190:193], v[0:3]
	s_setprio 0
	s_add_i32 s63, 0, 0x18000
	v_add_u32_e32 v140, s63, v162
	s_barrier
	ds_read_b128 v[128:131], v140
	ds_read_b128 v[132:135], v140 offset:1024
	ds_read_b128 v[136:139], v140 offset:2048
	ds_read_b128 v[140:143], v140 offset:3072
	s_add_u32 s26, s34, 0x40000
	s_addc_u32 s27, s35, 0
	s_mov_b32 m0, s43
	v_lshl_add_u64 v[194:195], s[26:27], 0, v[146:147]
	ds_read_b128 v[156:159], v164 offset:32768
	ds_read_b128 v[166:169], v164 offset:33792
	ds_read_b128 v[170:173], v164 offset:34816
	ds_read_b128 v[174:177], v164 offset:35840
	ds_read_b128 v[178:181], v164 offset:36864
	ds_read_b128 v[182:185], v164 offset:37888
	ds_read_b128 v[186:189], v164 offset:38912
	ds_read_b128 v[190:193], v164 offset:39936
	global_load_lds_dwordx4 v[194:195], off
	v_lshl_add_u64 v[194:195], s[26:27], 0, v[144:145]
	s_mov_b32 m0, s44
	s_nop 0
	global_load_lds_dwordx4 v[194:195], off
	s_waitcnt lgkmcnt(8)
	s_barrier
	s_waitcnt lgkmcnt(0)
	s_setprio 1
	s_waitcnt lgkmcnt(0)
	v_mfma_f32_16x16x32_bf16 v[124:127], v[128:131], v[156:159], v[124:127]
	v_mfma_f32_16x16x32_bf16 v[120:123], v[136:139], v[156:159], v[120:123]
	v_mfma_f32_16x16x32_bf16 v[116:119], v[128:131], v[170:173], v[116:119]
	v_mfma_f32_16x16x32_bf16 v[112:115], v[136:139], v[170:173], v[112:115]
	v_mfma_f32_16x16x32_bf16 v[108:111], v[128:131], v[178:181], v[108:111]
	v_mfma_f32_16x16x32_bf16 v[96:99], v[136:139], v[178:181], v[96:99]
	v_mfma_f32_16x16x32_bf16 v[84:87], v[128:131], v[186:189], v[84:87]
	v_mfma_f32_16x16x32_bf16 v[72:75], v[136:139], v[186:189], v[72:75]
	v_mfma_f32_16x16x32_bf16 v[124:127], v[132:135], v[166:169], v[124:127]
	v_mfma_f32_16x16x32_bf16 v[120:123], v[140:143], v[166:169], v[120:123]
	v_mfma_f32_16x16x32_bf16 v[116:119], v[132:135], v[174:177], v[116:119]
	v_mfma_f32_16x16x32_bf16 v[112:115], v[140:143], v[174:177], v[112:115]
	v_mfma_f32_16x16x32_bf16 v[108:111], v[132:135], v[182:185], v[108:111]
	v_mfma_f32_16x16x32_bf16 v[96:99], v[140:143], v[182:185], v[96:99]
	v_mfma_f32_16x16x32_bf16 v[84:87], v[132:135], v[190:193], v[84:87]
	v_mfma_f32_16x16x32_bf16 v[72:75], v[140:143], v[190:193], v[72:75]
	s_setprio 0
	s_barrier
	s_add_i32 s34, 0, 0x1c000
	s_add_i32 s26, s63, s39
	v_add_u32_e32 v206, s34, v162
	v_lshl_add_u64 v[160:161], v[160:161], 0, s[6:7]
	s_mov_b32 m0, s26
	ds_read_b128 v[194:197], v206
	ds_read_b128 v[198:201], v206 offset:1024
	ds_read_b128 v[202:205], v206 offset:2048
	ds_read_b128 v[206:209], v206 offset:3072
	global_load_lds_dwordx4 v[160:161], off
	v_lshl_add_u64 v[160:161], v[210:211], 0, s[6:7]
	s_add_i32 m0, s26, 0x2000
	s_nop 0
	global_load_lds_dwordx4 v[160:161], off
	s_barrier
	s_waitcnt lgkmcnt(0)
	s_setprio 1
	s_waitcnt lgkmcnt(0)
	v_mfma_f32_16x16x32_bf16 v[104:107], v[194:197], v[156:159], v[104:107]
	v_mfma_f32_16x16x32_bf16 v[100:103], v[202:205], v[156:159], v[100:103]
	v_mfma_f32_16x16x32_bf16 v[92:95], v[194:197], v[170:173], v[92:95]
	v_mfma_f32_16x16x32_bf16 v[88:91], v[202:205], v[170:173], v[88:91]
	v_mfma_f32_16x16x32_bf16 v[80:83], v[194:197], v[178:181], v[80:83]
	v_mfma_f32_16x16x32_bf16 v[76:79], v[202:205], v[178:181], v[76:79]
	v_mfma_f32_16x16x32_bf16 v[68:71], v[194:197], v[186:189], v[68:71]
	v_mfma_f32_16x16x32_bf16 v[64:67], v[202:205], v[186:189], v[64:67]
	v_mfma_f32_16x16x32_bf16 v[104:107], v[198:201], v[166:169], v[104:107]
	v_mfma_f32_16x16x32_bf16 v[100:103], v[206:209], v[166:169], v[100:103]
	v_mfma_f32_16x16x32_bf16 v[92:95], v[198:201], v[174:177], v[92:95]
	v_mfma_f32_16x16x32_bf16 v[88:91], v[206:209], v[174:177], v[88:91]
	v_mfma_f32_16x16x32_bf16 v[80:83], v[198:201], v[182:185], v[80:83]
	v_mfma_f32_16x16x32_bf16 v[76:79], v[206:209], v[182:185], v[76:79]
	v_mfma_f32_16x16x32_bf16 v[68:71], v[198:201], v[190:193], v[68:71]
	v_mfma_f32_16x16x32_bf16 v[64:67], v[206:209], v[190:193], v[64:67]
	s_setprio 0
	s_mov_b32 m0, s53
	v_lshl_add_u64 v[160:161], v[212:213], 0, s[6:7]
	s_barrier
	ds_read_b128 v[156:159], v164 offset:49152
	ds_read_b128 v[166:169], v164 offset:50176
	ds_read_b128 v[170:173], v164 offset:51200
	ds_read_b128 v[174:177], v164 offset:52224
	ds_read_b128 v[178:181], v164 offset:53248
	ds_read_b128 v[182:185], v164 offset:54272
	ds_read_b128 v[186:189], v164 offset:55296
	ds_read_b128 v[190:193], v164 offset:56320
	global_load_lds_dwordx4 v[160:161], off
	v_lshl_add_u64 v[160:161], v[214:215], 0, s[6:7]
	s_mov_b32 m0, s54
	s_nop 0
	global_load_lds_dwordx4 v[160:161], off
	s_barrier
; #define PG8_STAGE(bufoff, gbase, voff) do { _Pragma("unroll") for (int _i = 0; _i < 2; ++_i) \
;         __builtin_amdgcn_global_load_lds((const unsigned*)((const char*)(gbase) + (voff)[_i]), (LAS unsigned*)(lds + (bufoff) + ldsw + _i * 8192), 16, 0, 0); } while (0)
; #define PG8_MMA(ai, bj, At, Bt) do { __builtin_amdgcn_s_setprio(1); _Pragma("unroll") for (int m = 0; m < 4; ++m) _Pragma("unroll") for (int n = 0; n < 2; ++n) _Pragma("unroll") for (int k = 0; k < 2; ++k) \
;         acc[ai][bj][m][n] = __builtin_amdgcn_mfma_f32_16x16x32_bf16(Bt[n][k], At[m][k], acc[ai][bj][m][n], 0, 0, 0); __builtin_amdgcn_s_setprio(0); } while (0)
; #define PG8_WAIT_V(n) asm volatile("s_waitcnt vmcnt(" #n ")" ::: "memory")
; #define PG8_WAIT_L(n) asm volatile("s_waitcnt lgkmcnt(" #n ")" ::: "memory")
; #define PG8_BAR __builtin_amdgcn_s_barrier()
; #define PG8_SCHED __builtin_amdgcn_sched_barrier(0)
; template <class Epi>
; __device__ __forceinline__ void gemm_phase(LAS unsigned char* lds, const Gemm g, const StaticOrder& S, const Epi& E, int wave) {
;     ...
;             PG8_BAR; PG8_WAIT_L(0); PG8_MMA(1, 0, At, B0); PG8_BAR; PG8_SCHED;
;             PG8_STAGE(PG8_SB(1, 1), b3 + hstep, voffB);
;             PG8_WAIT_V(6); PG8_BAR; PG8_MMA(1, 1, At, B1); PG8_BAR;
;     __device__ __forceinline__ void operator()(const f32x4 (&acc)[2][2][4][2], const pg8::Unit& u, int wr, int wc, int, int) const {
;     ...
;         const int row0 = u.pm * 256 + wr * 64 + fr, col0 = u.pn * 256 + wc * 32 + 4 * fq;
;         const int bi = batch_of(u.pm * 256);
;         const float* base = (u.pm * 256 < NPTOK) ? basep : bases - (size_t)NPTOK * D;
;         f32x4 gv[2][2];
; #pragma unroll
;         for (int bj = 0; bj < 2; ++bj)
; #pragma unroll
;             for (int n = 0; n < 2; ++n) gv[bj][n] = *(const f32x4*)(gate + (size_t)bi * MODW + col0 + bj * HALF + n * 16);
; #pragma unroll
;         for (int ai = 0; ai < 2; ++ai) {
;             f32x4 bv[4][2][2];
; #pragma unroll
;             for (int m = 0; m < 4; ++m) { const size_t off = (size_t)(row0 + ai * HALF + m * 16) * D + col0;
; #pragma unroll
;                 for (int bj = 0; bj < 2; ++bj)
; #pragma unroll
;                     for (int n = 0; n < 2; ++n) bv[m][bj][n] = *(const f32x4*)(base + off + bj * HALF + n * 16); }
	s_waitcnt lgkmcnt(0)
	s_setprio 1
	s_waitcnt lgkmcnt(0)
	v_mfma_f32_16x16x32_bf16 v[60:63], v[128:131], v[156:159], v[60:63]
	v_mfma_f32_16x16x32_bf16 v[56:59], v[136:139], v[156:159], v[56:59]
	v_mfma_f32_16x16x32_bf16 v[52:55], v[128:131], v[170:173], v[52:55]
	v_mfma_f32_16x16x32_bf16 v[48:51], v[136:139], v[170:173], v[48:51]
	v_mfma_f32_16x16x32_bf16 v[44:47], v[128:131], v[178:181], v[44:47]
	v_mfma_f32_16x16x32_bf16 v[32:35], v[136:139], v[178:181], v[32:35]
	v_mfma_f32_16x16x32_bf16 v[20:23], v[128:131], v[186:189], v[20:23]
	v_mfma_f32_16x16x32_bf16 v[8:11], v[136:139], v[186:189], v[8:11]
	v_mfma_f32_16x16x32_bf16 v[60:63], v[132:135], v[166:169], v[60:63]
	v_mfma_f32_16x16x32_bf16 v[56:59], v[140:143], v[166:169], v[56:59]
	v_mfma_f32_16x16x32_bf16 v[52:55], v[132:135], v[174:177], v[52:55]
	v_mfma_f32_16x16x32_bf16 v[48:51], v[140:143], v[174:177], v[48:51]
	v_mfma_f32_16x16x32_bf16 v[44:47], v[132:135], v[182:185], v[44:47]
	v_mfma_f32_16x16x32_bf16 v[32:35], v[140:143], v[182:185], v[32:35]
	v_mfma_f32_16x16x32_bf16 v[20:23], v[132:135], v[190:193], v[20:23]
	v_mfma_f32_16x16x32_bf16 v[8:11], v[140:143], v[190:193], v[8:11]
	s_setprio 0
	s_barrier
	s_add_u32 s26, s30, 0x40080
	s_addc_u32 s27, s31, 0
	s_add_i32 s30, s34, s39
	v_lshl_add_u64 v[128:129], s[26:27], 0, v[146:147]
	s_mov_b32 m0, s30
	s_nop 0
	global_load_lds_dwordx4 v[128:129], off
	v_lshl_add_u64 v[128:129], s[26:27], 0, v[144:145]
	s_add_i32 m0, s30, 0x2000
	s_nop 0
	global_load_lds_dwordx4 v[128:129], off
	s_waitcnt vmcnt(6)
	s_barrier
	s_setprio 1
	v_mfma_f32_16x16x32_bf16 v[40:43], v[194:197], v[156:159], v[40:43]
	v_mfma_f32_16x16x32_bf16 v[36:39], v[202:205], v[156:159], v[36:39]
	v_mfma_f32_16x16x32_bf16 v[28:31], v[194:197], v[170:173], v[28:31]
	v_mfma_f32_16x16x32_bf16 v[24:27], v[202:205], v[170:173], v[24:27]
	v_mfma_f32_16x16x32_bf16 v[16:19], v[194:197], v[178:181], v[16:19]
	v_mfma_f32_16x16x32_bf16 v[12:15], v[202:205], v[178:181], v[12:15]
	v_mfma_f32_16x16x32_bf16 v[4:7], v[194:197], v[186:189], v[4:7]
	v_mfma_f32_16x16x32_bf16 v[0:3], v[202:205], v[186:189], v[0:3]
	v_mfma_f32_16x16x32_bf16 v[40:43], v[198:201], v[166:169], v[40:43]
	v_mfma_f32_16x16x32_bf16 v[36:39], v[206:209], v[166:169], v[36:39]
	v_mfma_f32_16x16x32_bf16 v[28:31], v[198:201], v[174:177], v[28:31]
	v_mfma_f32_16x16x32_bf16 v[24:27], v[206:209], v[174:177], v[24:27]
	v_mfma_f32_16x16x32_bf16 v[16:19], v[198:201], v[182:185], v[16:19]
	v_mfma_f32_16x16x32_bf16 v[12:15], v[206:209], v[182:185], v[12:15]
	v_mfma_f32_16x16x32_bf16 v[4:7], v[198:201], v[190:193], v[4:7]
	v_mfma_f32_16x16x32_bf16 v[0:3], v[206:209], v[190:193], v[0:3]
	s_setprio 0
	s_add_i32 s62, s62, 2
	s_add_u32 s60, s60, 0x100
	s_addc_u32 s61, s61, 0
	s_cmp_gt_u32 s62, 13
	s_mov_b64 s[26:27], s[28:29]
	s_barrier
	s_cbranch_scc0 .LBB0_767
	s_lshl_b32 s17, s24, 8
	s_add_i32 s19, s17, s51
	s_min_i32 s17, s17, 0x10000
	v_mbcnt_lo_u32_b32 v158, -1, 0
	v_mbcnt_hi_u32_b32 v158, -1, v158
	s_lshl_b32 s26, s57, 8
	v_ashrrev_i32_e32 v128, 2, v158
	s_ashr_i32 s17, s17, 11
	s_or_b32 s26, s26, s52
	v_and_b32_e32 v128, -4, v128
	s_mul_hi_i32 s27, s17, 0x6000
	s_mulk_i32 s17, 0x6000
	v_add_u32_e32 v128, s26, v128
	s_add_u32 s26, s46, s17
	v_readlane_b32 s76, v253, 12
	s_addc_u32 s27, s47, s27
	v_ashrrev_i32_e32 v129, 31, v128
	v_and_or_b32 v214, v158, 15, s19
	v_readlane_b32 s77, v253, 13
	v_lshlrev_b64 v[156:157], 2, v[128:129]
	s_cmpk_lt_i32 s24, 0x100
	s_mov_b64 s[60:61], s[76:77]
	v_ashrrev_i32_e32 v215, 31, v214
	v_or_b32_e32 v182, 16, v214
	v_or_b32_e32 v198, 32, v214
	v_lshl_add_u64 v[128:129], s[26:27], 0, v[156:157]
	s_cselect_b32 s27, s61, s50
	s_cselect_b32 s26, s60, s49
	v_lshlrev_b64 v[160:161], 12, v[214:215]
	v_ashrrev_i32_e32 v183, 31, v182
	v_ashrrev_i32_e32 v199, 31, v198
	v_or_b32_e32 v214, 48, v214
	v_lshl_add_u64 v[158:159], s[26:27], 0, v[156:157]
	v_lshlrev_b64 v[230:231], 12, v[182:183]
	v_lshlrev_b64 v[232:233], 12, v[198:199]
	v_ashrrev_i32_e32 v215, 31, v214
	v_lshl_add_u64 v[178:179], v[158:159], 0, v[160:161]
	v_lshl_add_u64 v[194:195], v[158:159], 0, v[230:231]
	v_lshl_add_u64 v[210:211], v[158:159], 0, v[232:233]
	v_lshlrev_b64 v[234:235], 12, v[214:215]
	global_load_dwordx4 v[140:143], v[128:129], off
	global_load_dwordx4 v[136:139], v[128:129], off offset:64
	global_load_dwordx4 v[132:135], v[128:129], off offset:512
	s_nop 0
	global_load_dwordx4 v[128:131], v[128:129], off offset:576
	s_nop 0
	global_load_dwordx4 v[166:169], v[178:179], off
	global_load_dwordx4 v[170:173], v[178:179], off offset:64
	global_load_dwordx4 v[174:177], v[178:179], off offset:512
	s_nop 0
	global_load_dwordx4 v[178:181], v[178:179], off offset:576
	s_nop 0
	global_load_dwordx4 v[182:185], v[194:195], off
	global_load_dwordx4 v[186:189], v[194:195], off offset:64
	global_load_dwordx4 v[190:193], v[194:195], off offset:512
	s_nop 0
	global_load_dwordx4 v[194:197], v[194:195], off offset:576
	s_nop 0
	global_load_dwordx4 v[198:201], v[210:211], off
	global_load_dwordx4 v[202:205], v[210:211], off offset:64
	global_load_dwordx4 v[206:209], v[210:211], off offset:512
	s_nop 0
	global_load_dwordx4 v[210:213], v[210:211], off offset:576
	v_lshl_add_u64 v[226:227], v[158:159], 0, v[234:235]
	global_load_dwordx4 v[214:217], v[226:227], off
	global_load_dwordx4 v[218:221], v[226:227], off offset:64
	global_load_dwordx4 v[222:225], v[226:227], off offset:512
	s_nop 0
	global_load_dwordx4 v[226:229], v[226:227], off offset:576
	v_readlane_b32 s28, v253, 8
	v_readlane_b32 s29, v253, 9
	s_and_b64 vcc, exec, s[0:1]
	s_mov_b32 s57, s16
	v_lshl_add_u64 v[236:237], s[28:29], 0, v[160:161]
	v_lshl_add_u64 v[232:233], s[28:29], 0, v[232:233]
	v_lshl_add_u64 v[236:237], v[236:237], 0, v[156:157]
	v_lshl_add_u64 v[230:231], s[28:29], 0, v[230:231]
	v_lshl_add_u64 v[232:233], v[232:233], 0, v[156:157]
	v_lshl_add_u64 v[230:231], v[230:231], 0, v[156:157]
	s_mov_b32 s24, s18
	s_mov_b64 s[26:27], s[20:21]
	v_readlane_b32 s78, v253, 14
	v_readlane_b32 s79, v253, 15
	v_readlane_b32 s80, v253, 16
	v_readlane_b32 s81, v253, 17
	v_readlane_b32 s82, v253, 18
	v_readlane_b32 s83, v253, 19
	v_readlane_b32 s84, v253, 20
	v_readlane_b32 s85, v253, 21
	v_readlane_b32 s86, v253, 22
	v_readlane_b32 s87, v253, 23
	v_readlane_b32 s88, v253, 24
	v_readlane_b32 s89, v253, 25
	v_readlane_b32 s90, v253, 26
	v_readlane_b32 s91, v253, 27
	v_readlane_b32 s30, v253, 10
	v_readlane_b32 s31, v253, 11
	s_waitcnt vmcnt(0)
;     __device__ __forceinline__ void operator()(const f32x4 (&acc)[2][2][4][2], const pg8::Unit& u, int wr, int wc, int, int) const {
;     ...
;         for (int ai = 0; ai < 2; ++ai) {
;             f32x4 bv[4][2][2];
; #pragma unroll
;             for (int m = 0; m < 4; ++m) { const size_t off = (size_t)(row0 + ai * HALF + m * 16) * D + col0;
; #pragma unroll
;                 for (int bj = 0; bj < 2; ++bj)
; #pragma unroll
;                     for (int n = 0; n < 2; ++n) bv[m][bj][n] = *(const f32x4*)(base + off + bj * HALF + n * 16); }
; #pragma unroll
;             for (int m = 0; m < 4; ++m) { const size_t off = (size_t)(row0 + ai * HALF + m * 16) * D + col0;
; #pragma unroll
;                 for (int bj = 0; bj < 2; ++bj)
; #pragma unroll
;                     for (int n = 0; n < 2; ++n) *(f32x4*)(out + off + bj * HALF + n * 16) = bv[m][bj][n] + gv[bj][n] * acc[ai][bj][m][n]; }
	v_pk_fma_f32 v[126:127], v[126:127], v[142:143], v[168:169]
	v_pk_fma_f32 v[124:125], v[124:125], v[140:141], v[166:167]
	v_pk_fma_f32 v[122:123], v[122:123], v[138:139], v[172:173]
	v_pk_fma_f32 v[120:121], v[120:121], v[136:137], v[170:171]
	v_pk_fma_f32 v[82:83], v[82:83], v[134:135], v[208:209]
	v_pk_fma_f32 v[80:81], v[80:81], v[132:133], v[206:207]
	v_pk_fma_f32 v[106:107], v[106:107], v[134:135], v[176:177]
	v_pk_fma_f32 v[104:105], v[104:105], v[132:133], v[174:175]
	v_pk_fma_f32 v[102:103], v[102:103], v[130:131], v[180:181]
	v_pk_fma_f32 v[100:101], v[100:101], v[128:129], v[178:179]
	v_pk_fma_f32 v[118:119], v[118:119], v[142:143], v[184:185]
	v_pk_fma_f32 v[116:117], v[116:117], v[140:141], v[182:183]
	v_pk_fma_f32 v[114:115], v[114:115], v[138:139], v[188:189]
	v_pk_fma_f32 v[112:113], v[112:113], v[136:137], v[186:187]
	v_pk_fma_f32 v[94:95], v[94:95], v[134:135], v[192:193]
	v_pk_fma_f32 v[92:93], v[92:93], v[132:133], v[190:191]
	v_pk_fma_f32 v[90:91], v[90:91], v[130:131], v[196:197]
	v_pk_fma_f32 v[88:89], v[88:89], v[128:129], v[194:195]
	v_pk_fma_f32 v[110:111], v[110:111], v[142:143], v[200:201]
	v_pk_fma_f32 v[108:109], v[108:109], v[140:141], v[198:199]
	v_pk_fma_f32 v[98:99], v[98:99], v[138:139], v[204:205]
	v_pk_fma_f32 v[96:97], v[96:97], v[136:137], v[202:203]
	global_store_dwordx4 v[236:237], v[124:127], off sc1
	global_store_dwordx4 v[236:237], v[120:123], off offset:64 sc1
	global_store_dwordx4 v[236:237], v[104:107], off offset:512 sc1
	global_store_dwordx4 v[236:237], v[100:103], off offset:576 sc1
	global_store_dwordx4 v[230:231], v[116:119], off sc1
	global_store_dwordx4 v[230:231], v[112:115], off offset:64 sc1
	global_store_dwordx4 v[230:231], v[92:95], off offset:512 sc1
	global_store_dwordx4 v[230:231], v[88:91], off offset:576 sc1
	global_store_dwordx4 v[232:233], v[108:111], off sc1
	global_store_dwordx4 v[232:233], v[96:99], off offset:64 sc1
	global_store_dwordx4 v[232:233], v[80:83], off offset:512 sc1
	v_pk_fma_f32 v[78:79], v[78:79], v[130:131], v[212:213]
	v_pk_fma_f32 v[76:77], v[76:77], v[128:129], v[210:211]
	v_lshl_add_u64 v[80:81], s[28:29], 0, v[234:235]
	global_store_dwordx4 v[232:233], v[76:79], off offset:576 sc1
	v_lshl_add_u64 v[80:81], v[80:81], 0, v[156:157]
	v_pk_fma_f32 v[74:75], v[74:75], v[138:139], v[220:221]
	v_pk_fma_f32 v[78:79], v[86:87], v[142:143], v[216:217]
	v_pk_fma_f32 v[76:77], v[84:85], v[140:141], v[214:215]
	v_pk_fma_f32 v[72:73], v[72:73], v[136:137], v[218:219]
	v_pk_fma_f32 v[70:71], v[70:71], v[134:135], v[224:225]
	v_pk_fma_f32 v[68:69], v[68:69], v[132:133], v[222:223]
	v_pk_fma_f32 v[66:67], v[66:67], v[130:131], v[228:229]
	v_pk_fma_f32 v[64:65], v[64:65], v[128:129], v[226:227]
	v_lshl_add_u64 v[166:167], v[160:161], 0, s[8:9]
	v_lshl_add_u64 v[168:169], v[160:161], 0, s[10:11]
	v_lshl_add_u64 v[170:171], v[160:161], 0, s[12:13]
	global_store_dwordx4 v[80:81], v[76:79], off sc1
	global_store_dwordx4 v[80:81], v[72:75], off offset:64 sc1
	global_store_dwordx4 v[80:81], v[68:71], off offset:512 sc1
	global_store_dwordx4 v[80:81], v[64:67], off offset:576 sc1
	v_lshl_add_u64 v[76:77], v[158:159], 0, v[166:167]
	v_lshl_add_u64 v[92:93], v[158:159], 0, v[168:169]
	v_lshl_add_u64 v[108:109], v[158:159], 0, v[170:171]
	v_lshl_add_u64 v[160:161], v[160:161], 0, s[14:15]
	global_load_dwordx4 v[64:67], v[76:77], off
	global_load_dwordx4 v[68:71], v[76:77], off offset:64
	global_load_dwordx4 v[72:75], v[76:77], off offset:512
	s_nop 0
	global_load_dwordx4 v[76:79], v[76:77], off offset:576
	s_nop 0
	global_load_dwordx4 v[80:83], v[92:93], off
	global_load_dwordx4 v[84:87], v[92:93], off offset:64
	global_load_dwordx4 v[88:91], v[92:93], off offset:512
	s_nop 0
	global_load_dwordx4 v[92:95], v[92:93], off offset:576
	s_nop 0
	global_load_dwordx4 v[96:99], v[108:109], off
	global_load_dwordx4 v[100:103], v[108:109], off offset:64
	global_load_dwordx4 v[104:107], v[108:109], off offset:512
	s_nop 0
	global_load_dwordx4 v[108:111], v[108:109], off offset:576
	v_lshl_add_u64 v[124:125], v[158:159], 0, v[160:161]
	global_load_dwordx4 v[112:115], v[124:125], off
	global_load_dwordx4 v[116:119], v[124:125], off offset:64
	global_load_dwordx4 v[120:123], v[124:125], off offset:512
	s_nop 0
	global_load_dwordx4 v[124:127], v[124:125], off offset:576
	v_lshl_add_u64 v[158:159], s[28:29], 0, v[166:167]
	v_lshl_add_u64 v[166:167], s[28:29], 0, v[168:169]
	v_lshl_add_u64 v[168:169], s[28:29], 0, v[170:171]
	v_lshl_add_u64 v[158:159], v[158:159], 0, v[156:157]
	v_lshl_add_u64 v[168:169], v[168:169], 0, v[156:157]
	v_lshl_add_u64 v[166:167], v[166:167], 0, v[156:157]
	s_waitcnt vmcnt(0)
; #define PG8_WAIT_V(n) asm volatile("s_waitcnt vmcnt(" #n ")" ::: "memory")
; #define PG8_BAR __builtin_amdgcn_s_barrier()
; template <class Epi>
; __device__ __forceinline__ void gemm_phase(LAS unsigned char* lds, const Gemm g, const StaticOrder& S, const Epi& E, int wave) {
;     ...
;         if (!has_next) break;
; #pragma unroll
;         for (int a = 0; a < 2; ++a)
; #pragma unroll
;             for (int b = 0; b < 2; ++b)
; #pragma unroll
;                 for (int m = 0; m < 4; ++m)
; #pragma unroll
;                     for (int n = 0; n < 2; ++n) acc[a][b][m][n] = (f32x4){0.f, 0.f, 0.f, 0.f};
;         cur = nxt; cA = nA; cB = nB; ++ui;
;     }
;     PG8_WAIT_V(0);
;     if (wr == 0) PG8_BAR;
;     PG8_BAR;
;     __device__ __forceinline__ void operator()(const f32x4 (&acc)[2][2][4][2], const pg8::Unit& u, int wr, int wc, int, int) const {
;     ...
;             for (int m = 0; m < 4; ++m) { const size_t off = (size_t)(row0 + ai * HALF + m * 16) * D + col0;
; #pragma unroll
;                 for (int bj = 0; bj < 2; ++bj)
; #pragma unroll
;                     for (int n = 0; n < 2; ++n) *(f32x4*)(out + off + bj * HALF + n * 16) = bv[m][bj][n] + gv[bj][n] * acc[ai][bj][m][n]; }
	v_pk_fma_f32 v[62:63], v[62:63], v[142:143], v[66:67]
	v_pk_fma_f32 v[60:61], v[60:61], v[140:141], v[64:65]
	v_pk_fma_f32 v[58:59], v[58:59], v[138:139], v[70:71]
	v_pk_fma_f32 v[56:57], v[56:57], v[136:137], v[68:69]
	v_pk_fma_f32 v[18:19], v[18:19], v[134:135], v[106:107]
	v_pk_fma_f32 v[16:17], v[16:17], v[132:133], v[104:105]
	v_pk_fma_f32 v[42:43], v[42:43], v[134:135], v[74:75]
	v_pk_fma_f32 v[40:41], v[40:41], v[132:133], v[72:73]
	v_pk_fma_f32 v[38:39], v[38:39], v[130:131], v[78:79]
	v_pk_fma_f32 v[36:37], v[36:37], v[128:129], v[76:77]
	v_pk_fma_f32 v[54:55], v[54:55], v[142:143], v[82:83]
	v_pk_fma_f32 v[52:53], v[52:53], v[140:141], v[80:81]
	v_pk_fma_f32 v[50:51], v[50:51], v[138:139], v[86:87]
	v_pk_fma_f32 v[48:49], v[48:49], v[136:137], v[84:85]
	v_pk_fma_f32 v[30:31], v[30:31], v[134:135], v[90:91]
	v_pk_fma_f32 v[28:29], v[28:29], v[132:133], v[88:89]
	v_pk_fma_f32 v[26:27], v[26:27], v[130:131], v[94:95]
	v_pk_fma_f32 v[24:25], v[24:25], v[128:129], v[92:93]
	v_pk_fma_f32 v[46:47], v[46:47], v[142:143], v[98:99]
	v_pk_fma_f32 v[44:45], v[44:45], v[140:141], v[96:97]
	v_pk_fma_f32 v[34:35], v[34:35], v[138:139], v[102:103]
	v_pk_fma_f32 v[32:33], v[32:33], v[136:137], v[100:101]
	global_store_dwordx4 v[158:159], v[60:63], off sc1
	global_store_dwordx4 v[158:159], v[56:59], off offset:64 sc1
	global_store_dwordx4 v[158:159], v[40:43], off offset:512 sc1
	global_store_dwordx4 v[158:159], v[36:39], off offset:576 sc1
	global_store_dwordx4 v[166:167], v[52:55], off sc1
	global_store_dwordx4 v[166:167], v[48:51], off offset:64 sc1
	global_store_dwordx4 v[166:167], v[28:31], off offset:512 sc1
	global_store_dwordx4 v[166:167], v[24:27], off offset:576 sc1
	global_store_dwordx4 v[168:169], v[44:47], off sc1
	global_store_dwordx4 v[168:169], v[32:35], off offset:64 sc1
	global_store_dwordx4 v[168:169], v[16:19], off offset:512 sc1
	v_pk_fma_f32 v[14:15], v[14:15], v[130:131], v[110:111]
	v_pk_fma_f32 v[12:13], v[12:13], v[128:129], v[108:109]
	v_lshl_add_u64 v[16:17], s[28:29], 0, v[160:161]
	global_store_dwordx4 v[168:169], v[12:15], off offset:576 sc1
	v_lshl_add_u64 v[16:17], v[16:17], 0, v[156:157]
	v_pk_fma_f32 v[10:11], v[10:11], v[138:139], v[118:119]
	v_pk_fma_f32 v[14:15], v[22:23], v[142:143], v[114:115]
	v_pk_fma_f32 v[12:13], v[20:21], v[140:141], v[112:113]
	v_pk_fma_f32 v[8:9], v[8:9], v[136:137], v[116:117]
	v_pk_fma_f32 v[6:7], v[6:7], v[134:135], v[122:123]
	v_pk_fma_f32 v[4:5], v[4:5], v[132:133], v[120:121]
	v_pk_fma_f32 v[2:3], v[2:3], v[130:131], v[126:127]
	v_pk_fma_f32 v[0:1], v[0:1], v[128:129], v[124:125]
	s_mov_b64 s[28:29], s[22:23]
	global_store_dwordx4 v[16:17], v[12:15], off sc1
	global_store_dwordx4 v[16:17], v[8:11], off offset:64 sc1
	global_store_dwordx4 v[16:17], v[4:7], off offset:512 sc1
	global_store_dwordx4 v[16:17], v[0:3], off offset:576 sc1
	s_cbranch_vccz .LBB0_764
	s_waitcnt vmcnt(0)
	s_cmpk_gt_u32 s3, 0xff
	s_cbranch_scc1 .LBB0_771
	s_barrier

; __device__ __forceinline__ unsigned pk2(float lo, float hi) { return cvtpk(lo, hi); }
; __device__ void phase_hrows(const Params& p, const float* srcp, const float* srcs, const float* gamma, int sh_off, int sc_off, bf16_t* h, int wave) {
;     ...
;         for (int u = 0; u < 2; ++u) { const int g = g0 + u * stride;
;             if (g < NTOK) {
; #pragma unroll
;                 for (int i = 0; i < 4; ++i) ss[u] += v[u][i][0] * v[u][i][0] + v[u][i][1] * v[u][i][1] + v[u][i][2] * v[u][i][2] + v[u][i][3] * v[u][i][3];
; #pragma unroll
;                 for (int o = 32; o >= 1; o >>= 1) ss[u] += __shfl_xor(ss[u], o);
;                 const float r = rsqrtf(ss[u] * (1.f / D) + EPS); const int b = batch_of(g);
; #pragma unroll
;                 for (int i2 = 0; i2 < 2; ++i2) { const int c = lane * 8 + 512 * i2; u32x4 w;
; #pragma unroll
;                     for (int hf = 0; hf < 2; ++hf) { const int cc = c + 4 * hf;
;                         const f32x4 gm = *(const f32x4*)(gamma + cc), sc = *(const f32x4*)(mod + b * MODW + sc_off + cc), sh = *(const f32x4*)(mod + b * MODW + sh_off + cc);
;                         const f32x4 y = v[u][2 * i2 + hf] * r * gm * (sc + 1.f) + sh;
;                         w[2 * hf] = pk2(y[0], y[1]); w[2 * hf + 1] = pk2(y[2], y[3]); }
;                     *(u32x4*)(h + (size_t)g * D + c) = w; } } }
.LBB0_788:
	s_or_b64 exec, exec, s[16:17]
	s_waitcnt vmcnt(0)
	v_mov_b32_e32 v58, v29
	v_mov_b32_e32 v59, v25
	v_min_i32_e32 v39, 0x10000, v42
	v_mov_b32_e32 v56, v28
	v_mov_b32_e32 v57, v24
	v_pk_mul_f32 v[58:59], v[58:59], v[58:59]
	v_ashrrev_i32_e32 v39, 11, v39
	v_pk_fma_f32 v[80:81], v[56:57], v[56:57], v[58:59]
	v_mul_i32_i24_e32 v56, 0x1800, v39
	v_ashrrev_i32_e32 v57, 31, v56
	v_lshl_add_u64 v[72:73], v[56:57], 2, s[8:9]
	v_lshl_add_u64 v[82:83], v[72:73], 0, s[12:13]
	v_lshl_add_u64 v[74:75], v[82:83], 0, v[32:33]
	v_lshl_add_u64 v[84:85], v[72:73], 0, s[14:15]
	global_load_dwordx4 v[56:59], v[34:35], off offset:16
	global_load_dwordx4 v[60:63], v[34:35], off
	global_load_dwordx4 v[64:67], v[74:75], off offset:16
	global_load_dwordx4 v[68:71], v[74:75], off
	v_lshl_add_u64 v[86:87], v[84:85], 0, v[32:33]
	global_load_dwordx4 v[72:75], v[86:87], off offset:16
	global_load_dwordx4 v[76:79], v[86:87], off
	v_mov_b32_e32 v86, v30
	v_mov_b32_e32 v87, v26
	v_pk_fma_f32 v[80:81], v[86:87], v[86:87], v[80:81]
	v_mov_b32_e32 v86, v31
	v_mov_b32_e32 v87, v27
	v_mov_b32_e32 v88, v21
	v_mov_b32_e32 v89, v17
	v_pk_fma_f32 v[80:81], v[86:87], v[86:87], v[80:81]
	v_mov_b32_e32 v86, v20
	v_mov_b32_e32 v87, v16
	v_pk_mul_f32 v[88:89], v[88:89], v[88:89]
	v_add_f32_e32 v39, v80, v81
	v_pk_fma_f32 v[86:87], v[86:87], v[86:87], v[88:89]
	v_mov_b32_e32 v88, v22
	v_mov_b32_e32 v89, v18
	v_pk_fma_f32 v[86:87], v[88:89], v[88:89], v[86:87]
	v_mov_b32_e32 v88, v23
	v_mov_b32_e32 v89, v19
	v_pk_fma_f32 v[86:87], v[88:89], v[88:89], v[86:87]
	v_lshlrev_b64 v[42:43], 11, v[42:43]
	v_add_f32_e32 v39, v39, v86
	v_add_f32_e32 v39, v39, v87
	ds_bpermute_b32 v41, v44, v39
	v_lshl_add_u64 v[42:43], v[36:37], 0, v[42:43]
	s_waitcnt lgkmcnt(0)
	v_add_f32_e32 v39, v39, v41
	ds_bpermute_b32 v41, v45, v39
	s_waitcnt lgkmcnt(0)
	v_add_f32_e32 v39, v39, v41
	ds_bpermute_b32 v41, v46, v39
	s_waitcnt lgkmcnt(0)
	v_add_f32_e32 v39, v39, v41
	ds_bpermute_b32 v41, v47, v39
	s_waitcnt lgkmcnt(0)
	v_add_f32_e32 v39, v39, v41
	ds_bpermute_b32 v41, v48, v39
	s_waitcnt lgkmcnt(0)
	v_add_f32_e32 v39, v39, v41
	ds_bpermute_b32 v41, v49, v39
	s_waitcnt lgkmcnt(0)
	v_add_f32_e32 v39, v39, v41
	v_fmamk_f32 v39, v39, 0x3a800000, v54
	v_mul_f32_e32 v41, 0x4b800000, v39
	v_cmp_gt_f32_e64 s[0:1], s22, v39
	s_nop 1
	v_cndmask_b32_e64 v39, v39, v41, s[0:1]
	v_rsq_f32_e32 v41, v39
	v_mov_b32_e32 v39, v33
	v_mul_f32_e32 v55, 0x45800000, v41
	v_cndmask_b32_e64 v80, v41, v55, s[0:1]
	v_pk_mul_f32 v[30:31], v[30:31], v[80:81] op_sel_hi:[1,0]
	v_pk_mul_f32 v[28:29], v[28:29], v[80:81] op_sel_hi:[1,0]
	v_pk_mul_f32 v[26:27], v[26:27], v[80:81] op_sel_hi:[1,0]
	v_pk_mul_f32 v[24:25], v[24:25], v[80:81] op_sel_hi:[1,0]
	v_pk_mul_f32 v[22:23], v[22:23], v[80:81] op_sel_hi:[1,0]
	s_waitcnt vmcnt(5)
	v_pk_mul_f32 v[24:25], v[56:57], v[24:25]
	s_waitcnt vmcnt(4)
	v_pk_mul_f32 v[28:29], v[60:61], v[28:29]
	v_pk_mul_f32 v[30:31], v[62:63], v[30:31]
	v_pk_mul_f32 v[26:27], v[58:59], v[26:27]
	s_waitcnt vmcnt(2)
	v_pk_add_f32 v[56:57], v[70:71], 1.0 op_sel_hi:[1,0]
	v_pk_add_f32 v[58:59], v[68:69], 1.0 op_sel_hi:[1,0]
	v_pk_add_f32 v[60:61], v[66:67], 1.0 op_sel_hi:[1,0]
	v_pk_add_f32 v[62:63], v[64:65], 1.0 op_sel_hi:[1,0]
	s_waitcnt vmcnt(0)
	v_pk_fma_f32 v[30:31], v[56:57], v[30:31], v[78:79]
	v_pk_fma_f32 v[28:29], v[58:59], v[28:29], v[76:77]
	v_pk_fma_f32 v[56:57], v[60:61], v[26:27], v[74:75]
	v_pk_fma_f32 v[26:27], v[62:63], v[24:25], v[72:73]
	v_cvt_pk_bf16_f32 v24, v28, v29
	v_cvt_pk_bf16_f32 v25, v30, v31
	v_cvt_pk_bf16_f32 v26, v26, v27
	v_cvt_pk_bf16_f32 v27, v56, v57
	global_store_dwordx4 v[42:43], v[24:27], off sc1
	v_lshl_add_u64 v[64:65], v[82:83], 0, v[38:39]
	global_load_dwordx4 v[24:27], v[34:35], off offset:2048
	global_load_dwordx4 v[28:31], v[64:65], off
	global_load_dwordx4 v[56:59], v[34:35], off offset:2064
	global_load_dwordx4 v[60:63], v[64:65], off offset:16
	v_lshl_add_u64 v[72:73], v[84:85], 0, v[38:39]
	global_load_dwordx4 v[64:67], v[72:73], off
	global_load_dwordx4 v[68:71], v[72:73], off offset:16
	v_pk_mul_f32 v[20:21], v[20:21], v[80:81] op_sel_hi:[1,0]
	v_pk_mul_f32 v[18:19], v[18:19], v[80:81] op_sel_hi:[1,0]
	v_pk_mul_f32 v[16:17], v[16:17], v[80:81] op_sel_hi:[1,0]
	s_waitcnt vmcnt(3)
	v_pk_mul_f32 v[18:19], v[58:59], v[18:19]
	v_pk_mul_f32 v[20:21], v[24:25], v[20:21]
	v_pk_mul_f32 v[22:23], v[26:27], v[22:23]
	v_pk_add_f32 v[24:25], v[30:31], 1.0 op_sel_hi:[1,0]
	v_pk_add_f32 v[26:27], v[28:29], 1.0 op_sel_hi:[1,0]
	v_pk_mul_f32 v[16:17], v[56:57], v[16:17]
	s_waitcnt vmcnt(2)
	v_pk_add_f32 v[28:29], v[62:63], 1.0 op_sel_hi:[1,0]
	v_pk_add_f32 v[30:31], v[60:61], 1.0 op_sel_hi:[1,0]
	s_waitcnt vmcnt(1)
	v_pk_fma_f32 v[22:23], v[24:25], v[22:23], v[66:67]
	v_pk_fma_f32 v[20:21], v[26:27], v[20:21], v[64:65]
	s_waitcnt vmcnt(0)
	v_pk_fma_f32 v[24:25], v[28:29], v[18:19], v[70:71]
	v_pk_fma_f32 v[18:19], v[30:31], v[16:17], v[68:69]
	v_cvt_pk_bf16_f32 v16, v20, v21
	v_cvt_pk_bf16_f32 v17, v22, v23
	v_cvt_pk_bf16_f32 v18, v18, v19
	v_cvt_pk_bf16_f32 v19, v24, v25
	global_store_dwordx4 v[42:43], v[16:19], off offset:1024 sc1
	s_and_saveexec_b64 s[0:1], vcc
	s_cbranch_execz .LBB0_785
; __device__ __forceinline__ unsigned pk2(float lo, float hi) { return cvtpk(lo, hi); }
; __device__ void phase_hrows(const Params& p, const float* srcp, const float* srcs, const float* gamma, int sh_off, int sc_off, bf16_t* h, int wave) {
;     ...
;     for (int g0 = blockIdx.x * 8 + wv; g0 < NTOK; g0 += 2 * stride) {
;         f32x4 v[2][4]; float ss[2];
; #pragma unroll
;         for (int u = 0; u < 2; ++u) { const int g = g0 + u * stride; ss[u] = 0.f;
;             if (g < NTOK) { const float* x = g < NPTOK ? srcp + (size_t)g * D : srcs + (size_t)(g - NPTOK) * D;
; #pragma unroll
;                 for (int i = 0; i < 4; ++i) v[u][i] = *(const f32x4*)(x + lane * 8 + 512 * (i >> 1) + 4 * (i & 1)); } }
; #pragma unroll
;         for (int u = 0; u < 2; ++u) { const int g = g0 + u * stride;
;             if (g < NTOK) {
; #pragma unroll
;                 for (int i = 0; i < 4; ++i) ss[u] += v[u][i][0] * v[u][i][0] + v[u][i][1] * v[u][i][1] + v[u][i][2] * v[u][i][2] + v[u][i][3] * v[u][i][3];
; #pragma unroll
;                 for (int o = 32; o >= 1; o >>= 1) ss[u] += __shfl_xor(ss[u], o);
;                 const float r = rsqrtf(ss[u] * (1.f / D) + EPS); const int b = batch_of(g);
; #pragma unroll
;                 for (int i2 = 0; i2 < 2; ++i2) { const int c = lane * 8 + 512 * i2; u32x4 w;
; #pragma unroll
;                     for (int hf = 0; hf < 2; ++hf) { const int cc = c + 4 * hf;
;                         const f32x4 gm = *(const f32x4*)(gamma + cc), sc = *(const f32x4*)(mod + b * MODW + sc_off + cc), sh = *(const f32x4*)(mod + b * MODW + sh_off + cc);
;                         const f32x4 y = v[u][2 * i2 + hf] * r * gm * (sc + 1.f) + sh;
;                         w[2 * hf] = pk2(y[0], y[1]); w[2 * hf + 1] = pk2(y[2], y[3]); }
;                     *(u32x4*)(h + (size_t)g * D + c) = w; } } }
	v_mov_b32_e32 v18, v1
	v_mov_b32_e32 v19, v5
	v_mov_b32_e32 v16, v0
	v_mov_b32_e32 v17, v4
	v_pk_mul_f32 v[18:19], v[18:19], v[18:19]
	v_mov_b32_e32 v70, v9
	v_pk_fma_f32 v[42:43], v[16:17], v[16:17], v[18:19]
	v_min_i32_e32 v16, 0x10000, v40
	v_ashrrev_i32_e32 v16, 11, v16
	v_mul_i32_i24_e32 v16, 0x1800, v16
	v_ashrrev_i32_e32 v17, 31, v16
	v_lshl_add_u64 v[56:57], v[16:17], 2, s[8:9]
	v_lshl_add_u64 v[64:65], v[56:57], 0, s[12:13]
	v_lshl_add_u64 v[58:59], v[64:65], 0, v[32:33]
	v_lshl_add_u64 v[66:67], v[56:57], 0, s[14:15]
	global_load_dwordx4 v[16:19], v[34:35], off offset:16
	global_load_dwordx4 v[20:23], v[34:35], off
	global_load_dwordx4 v[24:27], v[58:59], off offset:16
	global_load_dwordx4 v[28:31], v[58:59], off
	v_lshl_add_u64 v[68:69], v[66:67], 0, v[32:33]
	global_load_dwordx4 v[56:59], v[68:69], off offset:16
	global_load_dwordx4 v[60:63], v[68:69], off
	v_mov_b32_e32 v68, v2
	v_mov_b32_e32 v69, v6
	v_pk_fma_f32 v[42:43], v[68:69], v[68:69], v[42:43]
	v_mov_b32_e32 v68, v3
	v_mov_b32_e32 v69, v7
	v_mov_b32_e32 v71, v13
	v_pk_fma_f32 v[42:43], v[68:69], v[68:69], v[42:43]
	v_mov_b32_e32 v68, v8
	v_mov_b32_e32 v69, v12
	v_pk_mul_f32 v[70:71], v[70:71], v[70:71]
	v_add_f32_e32 v41, v42, v43
	v_pk_fma_f32 v[68:69], v[68:69], v[68:69], v[70:71]
	v_mov_b32_e32 v70, v10
	v_mov_b32_e32 v71, v14
	v_pk_fma_f32 v[68:69], v[70:71], v[70:71], v[68:69]
	v_mov_b32_e32 v70, v11
	v_mov_b32_e32 v71, v15
	v_pk_fma_f32 v[68:69], v[70:71], v[70:71], v[68:69]
	s_waitcnt vmcnt(3)
	v_pk_add_f32 v[26:27], v[26:27], 1.0 op_sel_hi:[1,0]
	v_add_f32_e32 v41, v69, v41
	v_add_f32_e32 v41, v68, v41
	ds_bpermute_b32 v42, v44, v41
	s_waitcnt vmcnt(2)
	v_pk_add_f32 v[30:31], v[30:31], 1.0 op_sel_hi:[1,0]
	v_pk_add_f32 v[28:29], v[28:29], 1.0 op_sel_hi:[1,0]
	v_pk_add_f32 v[24:25], v[24:25], 1.0 op_sel_hi:[1,0]
	s_waitcnt lgkmcnt(0)
	v_add_f32_e32 v41, v41, v42
	ds_bpermute_b32 v42, v45, v41
	s_waitcnt lgkmcnt(0)
	v_add_f32_e32 v41, v41, v42
	ds_bpermute_b32 v42, v46, v41
	s_waitcnt lgkmcnt(0)
	v_add_f32_e32 v41, v41, v42
	ds_bpermute_b32 v42, v47, v41
	s_waitcnt lgkmcnt(0)
	v_add_f32_e32 v41, v41, v42
	ds_bpermute_b32 v42, v48, v41
	s_waitcnt lgkmcnt(0)
	v_add_f32_e32 v41, v41, v42
	ds_bpermute_b32 v42, v49, v41
	s_waitcnt lgkmcnt(0)
	v_add_f32_e32 v41, v41, v42
	v_fmamk_f32 v41, v41, 0x3a800000, v54
	v_mul_f32_e32 v42, 0x4b800000, v41
	v_cmp_gt_f32_e32 vcc, s22, v41
	s_nop 1
	v_cndmask_b32_e32 v41, v41, v42, vcc
	v_rsq_f32_e32 v55, v41
	v_ashrrev_i32_e32 v41, 31, v40
	v_lshlrev_b64 v[42:43], 11, v[40:41]
	v_lshl_add_u64 v[42:43], v[36:37], 0, v[42:43]
	v_mul_f32_e32 v41, 0x45800000, v55
	v_cndmask_b32_e32 v68, v55, v41, vcc
	v_pk_mul_f32 v[70:71], v[6:7], v[68:69] op_sel_hi:[1,0]
	v_pk_mul_f32 v[72:73], v[4:5], v[68:69] op_sel_hi:[1,0]
	v_pk_mul_f32 v[74:75], v[2:3], v[68:69] op_sel_hi:[1,0]
	v_pk_mul_f32 v[76:77], v[0:1], v[68:69] op_sel_hi:[1,0]
	v_pk_mul_f32 v[20:21], v[20:21], v[72:73]
	v_pk_mul_f32 v[22:23], v[22:23], v[70:71]
	v_pk_mul_f32 v[16:17], v[16:17], v[76:77]
	v_pk_mul_f32 v[18:19], v[18:19], v[74:75]
	s_waitcnt vmcnt(0)
	v_pk_fma_f32 v[22:23], v[30:31], v[22:23], v[62:63]
	v_pk_fma_f32 v[20:21], v[28:29], v[20:21], v[60:61]
	v_pk_fma_f32 v[26:27], v[26:27], v[18:19], v[58:59]
	v_pk_fma_f32 v[18:19], v[24:25], v[16:17], v[56:57]
	v_cvt_pk_bf16_f32 v16, v20, v21
	v_cvt_pk_bf16_f32 v17, v22, v23
	v_cvt_pk_bf16_f32 v18, v18, v19
	v_cvt_pk_bf16_f32 v19, v26, v27
	global_store_dwordx4 v[42:43], v[16:19], off sc1
	v_lshl_add_u64 v[56:57], v[64:65], 0, v[38:39]
	global_load_dwordx4 v[16:19], v[34:35], off offset:2048
	global_load_dwordx4 v[20:23], v[56:57], off
	global_load_dwordx4 v[24:27], v[34:35], off offset:2064
	global_load_dwordx4 v[28:31], v[56:57], off offset:16
	v_lshl_add_u64 v[64:65], v[66:67], 0, v[38:39]
	global_load_dwordx4 v[56:59], v[64:65], off
	global_load_dwordx4 v[60:63], v[64:65], off offset:16
	v_pk_mul_f32 v[64:65], v[14:15], v[68:69] op_sel_hi:[1,0]
	v_pk_mul_f32 v[66:67], v[12:13], v[68:69] op_sel_hi:[1,0]
	v_pk_mul_f32 v[70:71], v[10:11], v[68:69] op_sel_hi:[1,0]
	v_pk_mul_f32 v[68:69], v[8:9], v[68:69] op_sel_hi:[1,0]
	s_waitcnt vmcnt(4)
	v_pk_add_f32 v[22:23], v[22:23], 1.0 op_sel_hi:[1,0]
	v_pk_mul_f32 v[16:17], v[16:17], v[66:67]
	v_pk_mul_f32 v[18:19], v[18:19], v[64:65]
	v_pk_add_f32 v[20:21], v[20:21], 1.0 op_sel_hi:[1,0]
	s_waitcnt vmcnt(3)
	v_pk_mul_f32 v[24:25], v[24:25], v[68:69]
	v_pk_mul_f32 v[26:27], v[26:27], v[70:71]
	s_waitcnt vmcnt(2)
	v_pk_add_f32 v[30:31], v[30:31], 1.0 op_sel_hi:[1,0]
	v_pk_add_f32 v[28:29], v[28:29], 1.0 op_sel_hi:[1,0]
	s_waitcnt vmcnt(1)
	v_pk_fma_f32 v[18:19], v[22:23], v[18:19], v[58:59]
	v_pk_fma_f32 v[16:17], v[20:21], v[16:17], v[56:57]
	s_waitcnt vmcnt(0)
	v_pk_fma_f32 v[20:21], v[30:31], v[26:27], v[62:63]
	v_pk_fma_f32 v[22:23], v[28:29], v[24:25], v[60:61]
	v_cvt_pk_bf16_f32 v16, v16, v17
	v_cvt_pk_bf16_f32 v17, v18, v19
	v_cvt_pk_bf16_f32 v18, v22, v23
	v_cvt_pk_bf16_f32 v19, v20, v21
	global_store_dwordx4 v[42:43], v[16:19], off offset:1024 sc1
	s_branch .LBB0_785

;     __device__ __forceinline__ void operator()(f32x4 (&acc)[2][2][4][2], const pg8::Unit& u, int wr, int wc, int, int) const {
;     ...
;                 for (int j = 0; j < 4; ++j) {
;                     const int lc = 8 * fq + 4 * n + j; const float w0 = lwv[lc], w1 = lwv[32 + lc], w2 = lwv[64 + lc], bb = lwv[96 + lc];
;                     float gp[4], gn[4];
; #pragma unroll
;                     for (int m = 0; m < 4; ++m) { const int gi_ = __float_as_int(acc[ai][0][m][n][j]); gp[m] = __int_as_float(__builtin_amdgcn_ds_bpermute(lprev4, gi_)); gn[m] = __int_as_float(__builtin_amdgcn_ds_bpermute(lnext4, gi_)); }
;                     float pre0 = 0.f, pre3 = 0.f;
; #pragma unroll
;                     for (int m = 0; m < 4; ++m) {
;                         const float g = acc[ai][0][m][n][j], uv = acc[ai][1][m][n][j];
;                         const float pv = (fr == 0) ? (m > 0 ? gp[m > 0 ? m - 1 : 0] : 0.f) : gp[m];
;                         const float nv = (fr == 15) ? (m < 3 ? gn[m < 3 ? m + 1 : 3] : 0.f) : gn[m];
;                         const float pre = w0 * pv + w1 * g + w2 * nv + bb;
;                         if (m == 0) pre0 = pre;
;                         if (m == 3) pre3 = pre;
;                         acc[ai][1][m][n][j] = gelu_tanh(pre) * uv;
;                     }
.LBB0_806:
	s_or_b64 exec, exec, s[6:7]
	v_pk_mul_f32 v[48:49], v[106:107], v[106:107]
	v_cndmask_b32_e64 v53, v171, v167, s[4:5]
	v_fmamk_f32 v48, v48, 0x3dd2d3e8, v192
	v_fmamk_f32 v49, v49, 0x3dd2d3e8, v192
	v_cndmask_b32_e64 v52, v169, v163, s[4:5]
	v_mul_f32_e32 v48, v106, v48
	v_mul_f32_e32 v49, v107, v49
	v_pk_mul_f32 v[52:53], v[92:93], v[52:53]
	v_exp_f32_e32 v48, v48
	v_exp_f32_e32 v49, v49
	v_cndmask_b32_e32 v55, v166, v170, vcc
	v_cndmask_b32_e32 v54, v162, v168, vcc
	v_pk_fma_f32 v[44:45], v[44:45], v[100:101], v[52:53]
	v_add_f32_e32 v48, 1.0, v48
	v_pk_fma_f32 v[44:45], v[94:95], v[54:55], v[44:45]
	v_add_f32_e32 v49, 1.0, v49
	v_pk_add_f32 v[44:45], v[98:99], v[44:45]
	v_rcp_f32_e32 v48, v48
	v_pk_mul_f32 v[52:53], v[44:45], v[44:45]
	v_rcp_f32_e32 v49, v49
	v_fmamk_f32 v52, v52, 0x3dd2d3e8, v192
	v_fmamk_f32 v53, v53, 0x3dd2d3e8, v192
	v_mul_f32_e32 v52, v44, v52
	v_mul_f32_e32 v53, v45, v53
	v_exp_f32_e32 v52, v52
	v_exp_f32_e32 v53, v53
	v_pk_fma_f32 v[48:49], v[106:107], v[48:49], v[106:107] neg_lo:[1,0,0] neg_hi:[1,0,0]
	v_cndmask_b32_e32 v55, v164, v166, vcc
	v_pk_mul_f32 v[36:37], v[36:37], v[48:49]
	v_add_f32_e32 v48, 1.0, v52
	v_add_f32_e32 v49, 1.0, v53
	v_cndmask_b32_e64 v53, v167, v165, s[4:5]
	v_cndmask_b32_e64 v52, v163, v161, s[4:5]
	v_pk_mul_f32 v[52:53], v[92:93], v[52:53]
	v_cndmask_b32_e32 v54, v160, v162, vcc
	v_pk_fma_f32 v[40:41], v[40:41], v[100:101], v[52:53]
	v_pk_mul_f32 v[50:51], v[104:105], v[104:105]
	v_pk_fma_f32 v[40:41], v[94:95], v[54:55], v[40:41]
	v_fmamk_f32 v50, v50, 0x3dd2d3e8, v192
	v_pk_add_f32 v[40:41], v[98:99], v[40:41]
	v_fmamk_f32 v51, v51, 0x3dd2d3e8, v192
	v_pk_mul_f32 v[52:53], v[40:41], v[40:41]
	v_mul_f32_e32 v50, v104, v50
	v_fmamk_f32 v52, v52, 0x3dd2d3e8, v192
	v_fmamk_f32 v53, v53, 0x3dd2d3e8, v192
	v_mul_f32_e32 v52, v40, v52
	v_mul_f32_e32 v53, v41, v53
	v_rcp_f32_e32 v48, v48
	v_exp_f32_e32 v52, v52
	v_exp_f32_e32 v53, v53
	v_rcp_f32_e32 v49, v49
	v_mul_f32_e32 v51, v105, v51
	v_exp_f32_e32 v50, v50
	v_exp_f32_e32 v51, v51
	v_add_f32_e32 v52, 1.0, v52
	v_add_f32_e32 v53, 1.0, v53
	v_pk_fma_f32 v[44:45], v[44:45], v[48:49], v[44:45] neg_lo:[1,0,0] neg_hi:[1,0,0]
	v_add_f32_e32 v50, 1.0, v50
	v_rcp_f32_e32 v52, v52
	v_rcp_f32_e32 v53, v53
	v_pk_mul_f32 v[32:33], v[32:33], v[44:45]
	v_add_f32_e32 v44, 1.0, v51
	v_rcp_f32_e32 v50, v50
	v_rcp_f32_e32 v51, v44
	v_cndmask_b32_e64 v49, v159, v155, s[4:5]
	v_cndmask_b32_e64 v48, v157, v151, s[4:5]
	v_pk_fma_f32 v[40:41], v[40:41], v[52:53], v[40:41] neg_lo:[1,0,0] neg_hi:[1,0,0]
	v_pk_mul_f32 v[48:49], v[56:57], v[48:49]
	v_pk_mul_f32 v[28:29], v[28:29], v[40:41]
	v_pk_fma_f32 v[40:41], v[104:105], v[50:51], v[104:105] neg_lo:[1,0,0] neg_hi:[1,0,0]
	v_cndmask_b32_e32 v51, v154, v158, vcc
	v_cndmask_b32_e32 v50, v150, v156, vcc
	v_pk_fma_f32 v[46:47], v[46:47], v[62:63], v[48:49]
	v_pk_mul_f32 v[44:45], v[102:103], v[102:103]
	v_pk_fma_f32 v[46:47], v[58:59], v[50:51], v[46:47]
	v_fmamk_f32 v44, v44, 0x3dd2d3e8, v192
	v_pk_add_f32 v[46:47], v[60:61], v[46:47]
	v_fmamk_f32 v45, v45, 0x3dd2d3e8, v192
	v_pk_mul_f32 v[48:49], v[46:47], v[46:47]
	v_mul_f32_e32 v44, v102, v44
	v_mul_f32_e32 v45, v103, v45
	v_fmamk_f32 v48, v48, 0x3dd2d3e8, v192
	v_fmamk_f32 v49, v49, 0x3dd2d3e8, v192
	v_exp_f32_e32 v44, v44
	v_exp_f32_e32 v45, v45
	v_mul_f32_e32 v48, v46, v48
	v_mul_f32_e32 v49, v47, v49
	v_exp_f32_e32 v48, v48
	v_exp_f32_e32 v49, v49
	v_add_f32_e32 v44, 1.0, v44
	v_add_f32_e32 v45, 1.0, v45
	v_rcp_f32_e32 v44, v44
	v_rcp_f32_e32 v45, v45
	v_add_f32_e32 v48, 1.0, v48
	v_add_f32_e32 v49, 1.0, v49
	v_cndmask_b32_e64 v51, v155, v153, s[4:5]
	v_cndmask_b32_e64 v50, v151, v149, s[4:5]
	v_rcp_f32_e32 v48, v48
	v_rcp_f32_e32 v49, v49
	v_pk_mul_f32 v[50:51], v[56:57], v[50:51]
	v_cndmask_b32_e32 v53, v152, v154, vcc
	v_cndmask_b32_e32 v52, v148, v150, vcc
	v_pk_fma_f32 v[42:43], v[42:43], v[62:63], v[50:51]
	v_pk_fma_f32 v[44:45], v[102:103], v[44:45], v[102:103] neg_lo:[1,0,0] neg_hi:[1,0,0]
	v_pk_fma_f32 v[42:43], v[58:59], v[52:53], v[42:43]
	v_pk_mul_f32 v[38:39], v[38:39], v[44:45]
	v_pk_add_f32 v[42:43], v[60:61], v[42:43]
	v_pk_fma_f32 v[44:45], v[46:47], v[48:49], v[46:47] neg_lo:[1,0,0] neg_hi:[1,0,0]
	v_pk_mul_f32 v[50:51], v[42:43], v[42:43]
	v_pk_mul_f32 v[34:35], v[34:35], v[44:45]
	v_fmamk_f32 v50, v50, 0x3dd2d3e8, v192
	v_fmamk_f32 v45, v51, 0x3dd2d3e8, v192
	v_mul_f32_e32 v50, v42, v50
	v_mul_f32_e32 v45, v43, v45
	v_exp_f32_e32 v50, v50
	v_exp_f32_e32 v45, v45
	v_pk_mul_f32 v[24:25], v[24:25], v[40:41]
	v_pk_mul_f32 v[40:41], v[96:97], v[96:97]
	v_pk_mul_f32 v[46:47], v[88:89], v[88:89]
	v_fmamk_f32 v40, v40, 0x3dd2d3e8, v192
	v_add_f32_e32 v44, 1.0, v50
	v_fmamk_f32 v41, v41, 0x3dd2d3e8, v192
	v_add_f32_e32 v45, 1.0, v45
	v_fmamk_f32 v46, v46, 0x3dd2d3e8, v192
	v_mul_f32_e32 v40, v96, v40
	v_mul_f32_e32 v41, v97, v41
	v_rcp_f32_e32 v44, v44
	v_rcp_f32_e32 v45, v45
	v_mul_f32_e32 v46, v88, v46
	v_exp_f32_e32 v40, v40
	v_exp_f32_e32 v41, v41
	v_exp_f32_e32 v46, v46
	v_pk_fma_f32 v[42:43], v[42:43], v[44:45], v[42:43] neg_lo:[1,0,0] neg_hi:[1,0,0]
	v_pk_mul_f32 v[44:45], v[86:87], v[86:87]
	v_add_f32_e32 v40, 1.0, v40
	v_add_f32_e32 v41, 1.0, v41
	v_pk_mul_f32 v[30:31], v[30:31], v[42:43]
	v_add_f32_e32 v42, 1.0, v46
	v_fmamk_f32 v43, v47, 0x3dd2d3e8, v192
	v_fmamk_f32 v44, v44, 0x3dd2d3e8, v192
	v_cndmask_b32_e64 v47, v147, v127, s[4:5]
	v_cndmask_b32_e64 v46, v145, v123, s[4:5]
	v_rcp_f32_e32 v40, v40
	v_rcp_f32_e32 v41, v41
	v_mul_f32_e32 v43, v89, v43
	v_mul_f32_e32 v44, v86, v44
	v_pk_mul_f32 v[46:47], v[74:75], v[46:47]
	v_exp_f32_e32 v43, v43
	v_exp_f32_e32 v44, v44
	v_cndmask_b32_e32 v49, v126, v146, vcc
; __device__ __forceinline__ unsigned pk2(float lo, float hi) { return cvtpk(lo, hi); }
;     __device__ __forceinline__ void operator()(f32x4 (&acc)[2][2][4][2], const pg8::Unit& u, int wr, int wc, int, int) const {
;     ...
;                 for (int j = 0; j < 4; ++j) {
;                     const int lc = 8 * fq + 4 * n + j; const float w0 = lwv[lc], w1 = lwv[32 + lc], w2 = lwv[64 + lc], bb = lwv[96 + lc];
;                     float gp[4], gn[4];
; #pragma unroll
;                     for (int m = 0; m < 4; ++m) { const int gi_ = __float_as_int(acc[ai][0][m][n][j]); gp[m] = __int_as_float(__builtin_amdgcn_ds_bpermute(lprev4, gi_)); gn[m] = __int_as_float(__builtin_amdgcn_ds_bpermute(lnext4, gi_)); }
;                     float pre0 = 0.f, pre3 = 0.f;
; #pragma unroll
;                     for (int m = 0; m < 4; ++m) {
;                         const float g = acc[ai][0][m][n][j], uv = acc[ai][1][m][n][j];
;                         const float pv = (fr == 0) ? (m > 0 ? gp[m > 0 ? m - 1 : 0] : 0.f) : gp[m];
;                         const float nv = (fr == 15) ? (m < 3 ? gn[m < 3 ? m + 1 : 3] : 0.f) : gn[m];
;                         const float pre = w0 * pv + w1 * g + w2 * nv + bb;
;                         if (m == 0) pre0 = pre;
;                         if (m == 3) pre3 = pre;
;                         acc[ai][1][m][n][j] = gelu_tanh(pre) * uv;
;                     }
;                     eP[j] = efirst ? pre0 : pre3;
;                     __builtin_amdgcn_sched_barrier(0);
;                 }
; #pragma unroll
;                 for (int j = 0; j < 4; ++j) eG[j] = efirst ? acc[ai][0][0][n][j] : acc[ai][0][3][n][j];
;                 if (efirst || elast) { *(f32x4*)(sbp + eo) = eP; *(f32x4*)(sbg + eo) = eG; }
;             }
; #pragma unroll
;             for (int m = 0; m < 4; ++m) { bf16_t* rowp = act + (size_t)(rband + m * 16 + fr) * DFF + f0;
;                 const f32x4 v0 = acc[ai][1][m][0], v1 = acc[ai][1][m][1];
;                 u32x4 w; w.x = pk2(v0[0], v0[1]); w.y = pk2(v0[2], v0[3]); w.z = pk2(v1[0], v1[1]); w.w = pk2(v1[2], v1[3]);
;                 *(u32x4*)rowp = w; }
	v_cndmask_b32_e32 v48, v122, v144, vcc
	v_pk_fma_f32 v[20:21], v[20:21], v[82:83], v[46:47]
	v_pk_fma_f32 v[40:41], v[96:97], v[40:41], v[96:97] neg_lo:[1,0,0] neg_hi:[1,0,0]
	v_pk_fma_f32 v[20:21], v[76:77], v[48:49], v[20:21]
	v_add_f32_e32 v43, 1.0, v43
	v_pk_add_f32 v[20:21], v[80:81], v[20:21]
	v_pk_mul_f32 v[26:27], v[26:27], v[40:41]
	v_pk_mul_f32 v[46:47], v[20:21], v[20:21]
	v_add_f32_e32 v40, 1.0, v44
	v_fmamk_f32 v41, v46, 0x3dd2d3e8, v192
	v_fmamk_f32 v44, v47, 0x3dd2d3e8, v192
	v_cndmask_b32_e64 v47, v127, v125, s[4:5]
	v_cndmask_b32_e64 v46, v123, v121, s[4:5]
	v_rcp_f32_e32 v42, v42
	v_rcp_f32_e32 v43, v43
	v_pk_mul_f32 v[46:47], v[74:75], v[46:47]
	v_mul_f32_e32 v41, v20, v41
	v_cndmask_b32_e32 v49, v124, v126, vcc
	v_cndmask_b32_e32 v48, v120, v122, vcc
	v_pk_fma_f32 v[16:17], v[16:17], v[82:83], v[46:47]
	v_exp_f32_e32 v41, v41
	v_mul_f32_e32 v44, v21, v44
	v_pk_fma_f32 v[16:17], v[76:77], v[48:49], v[16:17]
	v_exp_f32_e32 v44, v44
	v_pk_add_f32 v[16:17], v[80:81], v[16:17]
	v_pk_fma_f32 v[42:43], v[88:89], v[42:43], v[88:89] neg_lo:[1,0,0] neg_hi:[1,0,0]
	v_pk_mul_f32 v[46:47], v[16:17], v[16:17]
	v_pk_mul_f32 v[12:13], v[12:13], v[42:43]
	v_fmamk_f32 v43, v46, 0x3dd2d3e8, v192
	v_add_f32_e32 v41, 1.0, v41
	v_mul_f32_e32 v43, v16, v43
	v_rcp_f32_e32 v42, v41
	v_add_f32_e32 v41, 1.0, v44
	v_exp_f32_e32 v44, v43
	v_fmamk_f32 v43, v47, 0x3dd2d3e8, v192
	v_mul_f32_e32 v43, v17, v43
	v_exp_f32_e32 v47, v43
	v_rcp_f32_e32 v43, v41
	v_add_f32_e32 v41, 1.0, v44
	v_rcp_f32_e32 v46, v41
	v_add_f32_e32 v41, 1.0, v47
	v_rcp_f32_e32 v47, v41
	v_fmamk_f32 v41, v45, 0x3dd2d3e8, v192
	v_mul_f32_e32 v41, v87, v41
	v_exp_f32_e32 v41, v41
	v_pk_fma_f32 v[20:21], v[20:21], v[42:43], v[20:21] neg_lo:[1,0,0] neg_hi:[1,0,0]
	v_rcp_f32_e32 v40, v40
	v_pk_mul_f32 v[4:5], v[4:5], v[20:21]
	v_add_f32_e32 v20, 1.0, v41
	v_rcp_f32_e32 v41, v20
	v_pk_fma_f32 v[16:17], v[16:17], v[46:47], v[16:17] neg_lo:[1,0,0] neg_hi:[1,0,0]
	v_cndmask_b32_e32 v43, v114, v118, vcc
	v_pk_mul_f32 v[8:9], v[8:9], v[16:17]
	v_pk_fma_f32 v[16:17], v[86:87], v[40:41], v[86:87] neg_lo:[1,0,0] neg_hi:[1,0,0]
	v_cndmask_b32_e64 v41, v119, v115, s[4:5]
	v_cndmask_b32_e64 v40, v117, v111, s[4:5]
	v_pk_mul_f32 v[40:41], v[66:67], v[40:41]
	v_cndmask_b32_e32 v42, v110, v116, vcc
	v_pk_fma_f32 v[22:23], v[22:23], v[72:73], v[40:41]
	v_pk_mul_f32 v[20:21], v[84:85], v[84:85]
	v_pk_fma_f32 v[22:23], v[68:69], v[42:43], v[22:23]
	v_fmamk_f32 v20, v20, 0x3dd2d3e8, v192
	v_pk_add_f32 v[22:23], v[70:71], v[22:23]
	v_fmamk_f32 v21, v21, 0x3dd2d3e8, v192
	v_pk_mul_f32 v[40:41], v[22:23], v[22:23]
	v_mul_f32_e32 v20, v84, v20
	v_mul_f32_e32 v21, v85, v21
	v_fmamk_f32 v40, v40, 0x3dd2d3e8, v192
	v_fmamk_f32 v41, v41, 0x3dd2d3e8, v192
	v_exp_f32_e32 v20, v20
	v_exp_f32_e32 v21, v21
	v_mul_f32_e32 v40, v22, v40
	v_mul_f32_e32 v41, v23, v41
	v_exp_f32_e32 v40, v40
	v_exp_f32_e32 v41, v41
	v_add_f32_e32 v20, 1.0, v20
	v_add_f32_e32 v21, 1.0, v21
	v_cndmask_b32_e64 v43, v115, v113, s[4:5]
	v_cndmask_b32_e64 v42, v111, v109, s[4:5]
	v_rcp_f32_e32 v20, v20
	v_rcp_f32_e32 v21, v21
	v_add_f32_e32 v40, 1.0, v40
	v_add_f32_e32 v41, 1.0, v41
	v_pk_mul_f32 v[42:43], v[66:67], v[42:43]
	v_rcp_f32_e32 v40, v40
	v_rcp_f32_e32 v41, v41
	v_cndmask_b32_e32 v45, v112, v114, vcc
	v_cndmask_b32_e32 v44, v108, v110, vcc
	v_pk_fma_f32 v[18:19], v[18:19], v[72:73], v[42:43]
	v_pk_mul_f32 v[16:17], v[0:1], v[16:17]
	v_pk_fma_f32 v[18:19], v[68:69], v[44:45], v[18:19]
	v_pk_mul_f32 v[0:1], v[78:79], v[78:79]
	v_pk_add_f32 v[18:19], v[70:71], v[18:19]
	v_pk_fma_f32 v[20:21], v[84:85], v[20:21], v[84:85] neg_lo:[1,0,0] neg_hi:[1,0,0]
	v_pk_mul_f32 v[42:43], v[18:19], v[18:19]
	v_fmamk_f32 v0, v0, 0x3dd2d3e8, v192
	v_fmamk_f32 v42, v42, 0x3dd2d3e8, v192
	v_pk_mul_f32 v[14:15], v[14:15], v[20:21]
	v_pk_fma_f32 v[20:21], v[22:23], v[40:41], v[22:23] neg_lo:[1,0,0] neg_hi:[1,0,0]
	v_fmamk_f32 v23, v43, 0x3dd2d3e8, v192
	v_fmamk_f32 v1, v1, 0x3dd2d3e8, v192
	v_mul_f32_e32 v0, v78, v0
	v_mul_f32_e32 v42, v18, v42
	v_mul_f32_e32 v23, v19, v23
	v_mul_f32_e32 v1, v79, v1
	v_exp_f32_e32 v0, v0
	v_exp_f32_e32 v42, v42
	v_exp_f32_e32 v23, v23
	v_exp_f32_e32 v1, v1
	v_add_f32_e32 v0, 1.0, v0
	v_add_f32_e32 v22, 1.0, v42
	v_add_f32_e32 v23, 1.0, v23
	v_add_f32_e32 v1, 1.0, v1
	v_rcp_f32_e32 v0, v0
	v_rcp_f32_e32 v22, v22
	v_rcp_f32_e32 v23, v23
	v_rcp_f32_e32 v1, v1
	v_pk_mul_f32 v[6:7], v[6:7], v[20:21]
	v_or_b32_e32 v40, s3, v193
	v_pk_fma_f32 v[18:19], v[18:19], v[22:23], v[18:19] neg_lo:[1,0,0] neg_hi:[1,0,0]
	v_pk_fma_f32 v[0:1], v[78:79], v[0:1], v[78:79] neg_lo:[1,0,0] neg_hi:[1,0,0]
	v_mov_b64_e32 v[20:21], s[96:97]
	v_pk_mul_f32 v[10:11], v[10:11], v[18:19]
	v_pk_mul_f32 v[18:19], v[2:3], v[0:1]
	v_mad_i64_i32 v[0:1], s[4:5], v40, s53, v[20:21]
	v_lshl_add_u64 v[22:23], v[0:1], 0, v[64:65]
	v_cvt_pk_bf16_f32 v0, v12, v13
	v_cvt_pk_bf16_f32 v1, v14, v15
	v_cvt_pk_bf16_f32 v2, v36, v37
	v_cvt_pk_bf16_f32 v3, v38, v39
	global_store_dwordx4 v[22:23], v[0:3], off sc1
	s_and_b64 vcc, exec, s[0:1]
	s_mov_b32 s3, s18
	v_or_b32_e32 v0, 16, v40
	v_mad_i64_i32 v[0:1], s[4:5], v0, s53, v[20:21]
	v_lshl_add_u64 v[12:13], v[0:1], 0, v[64:65]
	v_cvt_pk_bf16_f32 v0, v8, v9
	v_cvt_pk_bf16_f32 v1, v10, v11
	v_cvt_pk_bf16_f32 v2, v28, v29
	v_cvt_pk_bf16_f32 v3, v30, v31
	global_store_dwordx4 v[12:13], v[0:3], off sc1
	s_mov_b32 s26, s20
	s_mov_b64 s[6:7], s[24:25]
	v_or_b32_e32 v0, 32, v40
	v_mad_i64_i32 v[0:1], s[4:5], v0, s53, v[20:21]
	v_lshl_add_u64 v[8:9], v[0:1], 0, v[64:65]
	v_cvt_pk_bf16_f32 v0, v4, v5
	v_cvt_pk_bf16_f32 v1, v6, v7
	v_cvt_pk_bf16_f32 v2, v32, v33
	v_cvt_pk_bf16_f32 v3, v34, v35
	global_store_dwordx4 v[8:9], v[0:3], off sc1
	s_nop 1
	v_or_b32_e32 v0, 48, v40
	v_mad_i64_i32 v[0:1], s[4:5], v0, s53, v[20:21]
	v_lshl_add_u64 v[4:5], v[0:1], 0, v[64:65]
	v_cvt_pk_bf16_f32 v0, v16, v17
	v_cvt_pk_bf16_f32 v1, v18, v19
	v_cvt_pk_bf16_f32 v2, v24, v25
	v_cvt_pk_bf16_f32 v3, v26, v27
	s_mov_b64 s[4:5], s[22:23]
	global_store_dwordx4 v[4:5], v[0:3], off sc1
	s_cbranch_vccnz .LBB0_843

; #define PG8_STAGE(bufoff, gbase, voff) do { _Pragma("unroll") for (int _i = 0; _i < 2; ++_i) \
;         __builtin_amdgcn_global_load_lds((const unsigned*)((const char*)(gbase) + (voff)[_i]), (LAS unsigned*)(lds + (bufoff) + ldsw + _i * 8192), 16, 0, 0); } while (0)
; #define PG8_LDA(dst, b, h) do { _Pragma("unroll") for (int m = 0; m < 4; ++m) _Pragma("unroll") for (int k = 0; k < 2; ++k) dst[m][k] = *(const LAS bf16x8*)(lds + PG8_SA(b, h) + aoff + m * 2048 + k * 1024); } while (0)
; #define PG8_LDB(dst, b, h) do { _Pragma("unroll") for (int n = 0; n < 2; ++n) _Pragma("unroll") for (int k = 0; k < 2; ++k) dst[n][k] = *(const LAS bf16x8*)(lds + PG8_SB(b, h) + boff + n * 2048 + k * 1024); } while (0)
; #define PG8_MMA(ai, bj, At, Bt) do { __builtin_amdgcn_s_setprio(1); _Pragma("unroll") for (int m = 0; m < 4; ++m) _Pragma("unroll") for (int n = 0; n < 2; ++n) _Pragma("unroll") for (int k = 0; k < 2; ++k) \
;         acc[ai][bj][m][n] = __builtin_amdgcn_mfma_f32_16x16x32_bf16(Bt[n][k], At[m][k], acc[ai][bj][m][n], 0, 0, 0); __builtin_amdgcn_s_setprio(0); } while (0)
; #define PG8_WAIT_V(n) asm volatile("s_waitcnt vmcnt(" #n ")" ::: "memory")
; #define PG8_WAIT_L(n) asm volatile("s_waitcnt lgkmcnt(" #n ")" ::: "memory")
; #define PG8_BAR __builtin_amdgcn_s_barrier()
; #define PG8_SCHED __builtin_amdgcn_sched_barrier(0)
; template <class Epi>
; __device__ __forceinline__ void gemm_phase(LAS unsigned char* lds, const Gemm g, const StaticOrder& S, const Epi& E, int wave) {
;     ...
;             PG8_LDB(B0, 0, 0); PG8_SCHED; PG8_LDA(At, 0, 0); PG8_STAGE(PG8_SA(1, 1), a1 + hstep, voffA);
;             PG8_WAIT_L(8); PG8_BAR; PG8_WAIT_L(0); PG8_MMA(0, 0, At, B0); PG8_BAR; PG8_SCHED;
;             PG8_LDB(B1, 0, 1); PG8_STAGE(PG8_SB(0, 0), b2, voffB);
;             PG8_BAR; PG8_WAIT_L(0); PG8_MMA(0, 1, At, B1); PG8_BAR;
;             PG8_LDA(At, 0, 1); PG8_STAGE(PG8_SA(0, 0), a2, voffA);
;             PG8_BAR; PG8_WAIT_L(0); PG8_MMA(1, 0, At, B0); PG8_BAR; PG8_SCHED;
;             PG8_STAGE(PG8_SB(0, 1), b2 + hstep, voffB);
;             PG8_WAIT_V(6); PG8_BAR; PG8_MMA(1, 1, At, B1); PG8_BAR;
.LBB0_810:
	ds_read_b128 v[144:147], v189
	ds_read_b128 v[148:151], v189 offset:1024
	ds_read_b128 v[152:155], v189 offset:2048
	ds_read_b128 v[156:159], v189 offset:3072
	s_add_u32 s6, s4, 0xfffc0080
	s_addc_u32 s7, s5, -1
	s_cmp_eq_u32 s55, 12
	s_cselect_b32 s29, s21, s7
	s_cselect_b32 s28, s27, s6
	s_cselect_b32 s7, s19, s54
	s_cselect_b32 s6, s30, s31
	v_lshl_add_u64 v[198:199], s[4:5], 0, v[136:137]
	s_add_i32 m0, s39, 0xc000
	ds_read_b128 v[160:163], v190
	ds_read_b128 v[164:167], v190 offset:1024
	ds_read_b128 v[168:171], v190 offset:2048
	ds_read_b128 v[172:175], v190 offset:3072
	ds_read_b128 v[176:179], v190 offset:4096
	ds_read_b128 v[180:183], v190 offset:5120
	ds_read_b128 v[184:187], v190 offset:6144
	ds_read_b128 v[194:197], v190 offset:7168
	global_load_lds_dwordx4 v[198:199], off
	v_lshl_add_u64 v[198:199], s[4:5], 0, v[138:139]
	s_add_i32 m0, s39, 0xe000
	s_nop 0
	global_load_lds_dwordx4 v[198:199], off
	s_waitcnt lgkmcnt(8)
	s_barrier
	s_waitcnt lgkmcnt(0)
	s_setprio 1
	s_waitcnt lgkmcnt(0)
	v_mfma_f32_16x16x32_bf16 v[124:127], v[144:147], v[160:163], v[124:127]
	v_mfma_f32_16x16x32_bf16 v[116:119], v[152:155], v[160:163], v[116:119]
	v_mfma_f32_16x16x32_bf16 v[80:83], v[144:147], v[168:171], v[80:83]
	v_mfma_f32_16x16x32_bf16 v[104:107], v[152:155], v[168:171], v[104:107]
	v_mfma_f32_16x16x32_bf16 v[84:87], v[144:147], v[176:179], v[84:87]
	v_mfma_f32_16x16x32_bf16 v[108:111], v[152:155], v[176:179], v[108:111]
	v_mfma_f32_16x16x32_bf16 v[120:123], v[144:147], v[184:187], v[120:123]
	v_mfma_f32_16x16x32_bf16 v[112:115], v[152:155], v[184:187], v[112:115]
	v_mfma_f32_16x16x32_bf16 v[124:127], v[148:151], v[164:167], v[124:127]
	v_mfma_f32_16x16x32_bf16 v[116:119], v[156:159], v[164:167], v[116:119]
	v_mfma_f32_16x16x32_bf16 v[80:83], v[148:151], v[172:175], v[80:83]
	v_mfma_f32_16x16x32_bf16 v[104:107], v[156:159], v[172:175], v[104:107]
	v_mfma_f32_16x16x32_bf16 v[84:87], v[148:151], v[180:183], v[84:87]
	v_mfma_f32_16x16x32_bf16 v[108:111], v[156:159], v[180:183], v[108:111]
	v_mfma_f32_16x16x32_bf16 v[120:123], v[148:151], v[194:197], v[120:123]
	v_mfma_f32_16x16x32_bf16 v[112:115], v[156:159], v[194:197], v[112:115]
	s_setprio 0
	s_barrier
	s_add_i32 s56, s50, s36
	v_lshl_add_u64 v[214:215], s[6:7], 0, v[132:133]
	s_mov_b32 m0, s56
	ds_read_b128 v[198:201], v191
	ds_read_b128 v[202:205], v191 offset:1024
	ds_read_b128 v[206:209], v191 offset:2048
	ds_read_b128 v[210:213], v191 offset:3072
	global_load_lds_dwordx4 v[214:215], off
	v_lshl_add_u64 v[216:217], s[6:7], 0, v[128:129]
	s_add_i32 m0, s56, 0x2000
	s_nop 0
	global_load_lds_dwordx4 v[216:217], off
	s_barrier
	s_waitcnt lgkmcnt(0)
	s_setprio 1
	s_waitcnt lgkmcnt(0)
	v_mfma_f32_16x16x32_bf16 v[76:79], v[198:201], v[160:163], v[76:79]
	v_mfma_f32_16x16x32_bf16 v[100:103], v[206:209], v[160:163], v[100:103]
	v_mfma_f32_16x16x32_bf16 v[72:75], v[198:201], v[168:171], v[72:75]
	v_mfma_f32_16x16x32_bf16 v[92:95], v[206:209], v[168:171], v[92:95]
	v_mfma_f32_16x16x32_bf16 v[68:71], v[198:201], v[176:179], v[68:71]
	v_mfma_f32_16x16x32_bf16 v[96:99], v[206:209], v[176:179], v[96:99]
	v_mfma_f32_16x16x32_bf16 v[64:67], v[198:201], v[184:187], v[64:67]
	v_mfma_f32_16x16x32_bf16 v[88:91], v[206:209], v[184:187], v[88:91]
	v_mfma_f32_16x16x32_bf16 v[76:79], v[202:205], v[164:167], v[76:79]
	v_mfma_f32_16x16x32_bf16 v[100:103], v[210:213], v[164:167], v[100:103]
	v_mfma_f32_16x16x32_bf16 v[72:75], v[202:205], v[172:175], v[72:75]
	v_mfma_f32_16x16x32_bf16 v[92:95], v[210:213], v[172:175], v[92:95]
	v_mfma_f32_16x16x32_bf16 v[68:71], v[202:205], v[180:183], v[68:71]
	v_mfma_f32_16x16x32_bf16 v[96:99], v[210:213], v[180:183], v[96:99]
	v_mfma_f32_16x16x32_bf16 v[64:67], v[202:205], v[194:197], v[64:67]
	v_mfma_f32_16x16x32_bf16 v[88:91], v[210:213], v[194:197], v[88:91]
	s_setprio 0
	s_mov_b32 m0, s39
	v_lshl_add_u64 v[218:219], s[28:29], 0, v[134:135]
	s_barrier
	ds_read_b128 v[160:163], v190 offset:16384
	ds_read_b128 v[164:167], v190 offset:17408
	ds_read_b128 v[168:171], v190 offset:18432
	ds_read_b128 v[172:175], v190 offset:19456
	ds_read_b128 v[176:179], v190 offset:20480
	ds_read_b128 v[180:183], v190 offset:21504
	ds_read_b128 v[184:187], v190 offset:22528
	ds_read_b128 v[194:197], v190 offset:23552
	global_load_lds_dwordx4 v[218:219], off
	v_lshl_add_u64 v[220:221], s[28:29], 0, v[130:131]
	s_mov_b32 m0, s40
	s_nop 0
	global_load_lds_dwordx4 v[220:221], off
	s_barrier
	s_waitcnt lgkmcnt(0)
	s_setprio 1
	s_waitcnt lgkmcnt(0)
	v_mfma_f32_16x16x32_bf16 v[60:63], v[144:147], v[160:163], v[60:63]
	v_mfma_f32_16x16x32_bf16 v[52:55], v[152:155], v[160:163], v[52:55]
	v_mfma_f32_16x16x32_bf16 v[16:19], v[144:147], v[168:171], v[16:19]
	v_mfma_f32_16x16x32_bf16 v[40:43], v[152:155], v[168:171], v[40:43]
	v_mfma_f32_16x16x32_bf16 v[20:23], v[144:147], v[176:179], v[20:23]
	v_mfma_f32_16x16x32_bf16 v[44:47], v[152:155], v[176:179], v[44:47]
	v_mfma_f32_16x16x32_bf16 v[56:59], v[144:147], v[184:187], v[56:59]
	v_mfma_f32_16x16x32_bf16 v[48:51], v[152:155], v[184:187], v[48:51]
	v_mfma_f32_16x16x32_bf16 v[60:63], v[148:151], v[164:167], v[60:63]
	v_mfma_f32_16x16x32_bf16 v[52:55], v[156:159], v[164:167], v[52:55]
	v_mfma_f32_16x16x32_bf16 v[16:19], v[148:151], v[172:175], v[16:19]
	v_mfma_f32_16x16x32_bf16 v[40:43], v[156:159], v[172:175], v[40:43]
	v_mfma_f32_16x16x32_bf16 v[20:23], v[148:151], v[180:183], v[20:23]
	v_mfma_f32_16x16x32_bf16 v[44:47], v[156:159], v[180:183], v[44:47]
	v_mfma_f32_16x16x32_bf16 v[56:59], v[148:151], v[194:197], v[56:59]
	v_mfma_f32_16x16x32_bf16 v[48:51], v[156:159], v[194:197], v[48:51]
	s_setprio 0
	s_barrier
; #define PG8_STAGE(bufoff, gbase, voff) do { _Pragma("unroll") for (int _i = 0; _i < 2; ++_i) \
;         __builtin_amdgcn_global_load_lds((const unsigned*)((const char*)(gbase) + (voff)[_i]), (LAS unsigned*)(lds + (bufoff) + ldsw + _i * 8192), 16, 0, 0); } while (0)
; #define PG8_LDA(dst, b, h) do { _Pragma("unroll") for (int m = 0; m < 4; ++m) _Pragma("unroll") for (int k = 0; k < 2; ++k) dst[m][k] = *(const LAS bf16x8*)(lds + PG8_SA(b, h) + aoff + m * 2048 + k * 1024); } while (0)
; #define PG8_LDB(dst, b, h) do { _Pragma("unroll") for (int n = 0; n < 2; ++n) _Pragma("unroll") for (int k = 0; k < 2; ++k) dst[n][k] = *(const LAS bf16x8*)(lds + PG8_SB(b, h) + boff + n * 2048 + k * 1024); } while (0)
; #define PG8_MMA(ai, bj, At, Bt) do { __builtin_amdgcn_s_setprio(1); _Pragma("unroll") for (int m = 0; m < 4; ++m) _Pragma("unroll") for (int n = 0; n < 2; ++n) _Pragma("unroll") for (int k = 0; k < 2; ++k) \
;         acc[ai][bj][m][n] = __builtin_amdgcn_mfma_f32_16x16x32_bf16(Bt[n][k], At[m][k], acc[ai][bj][m][n], 0, 0, 0); __builtin_amdgcn_s_setprio(0); } while (0)
; #define PG8_WAIT_V(n) asm volatile("s_waitcnt vmcnt(" #n ")" ::: "memory")
; #define PG8_WAIT_L(n) asm volatile("s_waitcnt lgkmcnt(" #n ")" ::: "memory")
; #define PG8_BAR __builtin_amdgcn_s_barrier()
; #define PG8_SCHED __builtin_amdgcn_sched_barrier(0)
; template <class Epi>
; __device__ __forceinline__ void gemm_phase(LAS unsigned char* lds, const Gemm g, const StaticOrder& S, const Epi& E, int wave) {
;     ...
;             PG8_WAIT_V(6); PG8_BAR; PG8_MMA(1, 1, At, B1); PG8_BAR;
;             PG8_LDB(B0, 1, 0); PG8_SCHED; PG8_LDA(At, 1, 0); PG8_STAGE(PG8_SA(0, 1), a2 + hstep, voffA);
;             PG8_WAIT_L(8); PG8_BAR; PG8_WAIT_L(0); PG8_MMA(0, 0, At, B0); PG8_BAR; PG8_SCHED;
;             PG8_LDB(B1, 1, 1); PG8_STAGE(PG8_SB(1, 0), b3, voffB);
;             PG8_BAR; PG8_WAIT_L(0); PG8_MMA(0, 1, At, B1); PG8_BAR;
;             PG8_LDA(At, 1, 1); PG8_STAGE(PG8_SA(1, 0), a3, voffA);
;             PG8_BAR; PG8_WAIT_L(0); PG8_MMA(1, 0, At, B0); PG8_BAR; PG8_SCHED;
	s_add_u32 s56, s6, 0x40000
	s_addc_u32 s57, s7, 0
	s_add_i32 s58, s51, s36
	v_lshl_add_u64 v[144:145], s[56:57], 0, v[132:133]
	s_mov_b32 m0, s58
	s_nop 0
	global_load_lds_dwordx4 v[144:145], off
	v_lshl_add_u64 v[144:145], s[56:57], 0, v[128:129]
	s_add_i32 m0, s58, 0x2000
	s_nop 0
	global_load_lds_dwordx4 v[144:145], off
	s_waitcnt vmcnt(6)
	s_barrier
	s_setprio 1
	v_mfma_f32_16x16x32_bf16 v[12:15], v[198:201], v[160:163], v[12:15]
	v_mfma_f32_16x16x32_bf16 v[36:39], v[206:209], v[160:163], v[36:39]
	v_mfma_f32_16x16x32_bf16 v[8:11], v[198:201], v[168:171], v[8:11]
	v_mfma_f32_16x16x32_bf16 v[28:31], v[206:209], v[168:171], v[28:31]
	v_mfma_f32_16x16x32_bf16 v[4:7], v[198:201], v[176:179], v[4:7]
	v_mfma_f32_16x16x32_bf16 v[32:35], v[206:209], v[176:179], v[32:35]
	v_mfma_f32_16x16x32_bf16 v[0:3], v[198:201], v[184:187], v[0:3]
	v_mfma_f32_16x16x32_bf16 v[24:27], v[206:209], v[184:187], v[24:27]
	v_mfma_f32_16x16x32_bf16 v[12:15], v[202:205], v[164:167], v[12:15]
	v_mfma_f32_16x16x32_bf16 v[36:39], v[210:213], v[164:167], v[36:39]
	v_mfma_f32_16x16x32_bf16 v[8:11], v[202:205], v[172:175], v[8:11]
	v_mfma_f32_16x16x32_bf16 v[28:31], v[210:213], v[172:175], v[28:31]
	v_mfma_f32_16x16x32_bf16 v[4:7], v[202:205], v[180:183], v[4:7]
	v_mfma_f32_16x16x32_bf16 v[32:35], v[210:213], v[180:183], v[32:35]
	v_mfma_f32_16x16x32_bf16 v[0:3], v[202:205], v[194:197], v[0:3]
	v_mfma_f32_16x16x32_bf16 v[24:27], v[210:213], v[194:197], v[24:27]
	s_setprio 0
	s_add_i32 s56, 0, 0x18000
	v_add_u32_e32 v156, s56, v188
	s_barrier
	ds_read_b128 v[144:147], v156
	ds_read_b128 v[148:151], v156 offset:1024
	ds_read_b128 v[152:155], v156 offset:2048
	ds_read_b128 v[156:159], v156 offset:3072
	s_add_u32 s28, s28, 0x40000
	s_addc_u32 s29, s29, 0
	s_mov_b32 m0, s41
	v_lshl_add_u64 v[198:199], s[28:29], 0, v[134:135]
	ds_read_b128 v[160:163], v190 offset:32768
	ds_read_b128 v[164:167], v190 offset:33792
	ds_read_b128 v[168:171], v190 offset:34816
	ds_read_b128 v[172:175], v190 offset:35840
	ds_read_b128 v[176:179], v190 offset:36864
	ds_read_b128 v[180:183], v190 offset:37888
	ds_read_b128 v[184:187], v190 offset:38912
	ds_read_b128 v[194:197], v190 offset:39936
	global_load_lds_dwordx4 v[198:199], off
	v_lshl_add_u64 v[198:199], s[28:29], 0, v[130:131]
	s_mov_b32 m0, s42
	s_nop 0
	global_load_lds_dwordx4 v[198:199], off
	s_waitcnt lgkmcnt(8)
	s_barrier
	s_waitcnt lgkmcnt(0)
	s_setprio 1
	s_waitcnt lgkmcnt(0)
	v_mfma_f32_16x16x32_bf16 v[124:127], v[144:147], v[160:163], v[124:127]
	v_mfma_f32_16x16x32_bf16 v[116:119], v[152:155], v[160:163], v[116:119]
	v_mfma_f32_16x16x32_bf16 v[80:83], v[144:147], v[168:171], v[80:83]
	v_mfma_f32_16x16x32_bf16 v[104:107], v[152:155], v[168:171], v[104:107]
	v_mfma_f32_16x16x32_bf16 v[84:87], v[144:147], v[176:179], v[84:87]
	v_mfma_f32_16x16x32_bf16 v[108:111], v[152:155], v[176:179], v[108:111]
	v_mfma_f32_16x16x32_bf16 v[120:123], v[144:147], v[184:187], v[120:123]
	v_mfma_f32_16x16x32_bf16 v[112:115], v[152:155], v[184:187], v[112:115]
	v_mfma_f32_16x16x32_bf16 v[124:127], v[148:151], v[164:167], v[124:127]
	v_mfma_f32_16x16x32_bf16 v[116:119], v[156:159], v[164:167], v[116:119]
	v_mfma_f32_16x16x32_bf16 v[80:83], v[148:151], v[172:175], v[80:83]
	v_mfma_f32_16x16x32_bf16 v[104:107], v[156:159], v[172:175], v[104:107]
	v_mfma_f32_16x16x32_bf16 v[84:87], v[148:151], v[180:183], v[84:87]
	v_mfma_f32_16x16x32_bf16 v[108:111], v[156:159], v[180:183], v[108:111]
	v_mfma_f32_16x16x32_bf16 v[120:123], v[148:151], v[194:197], v[120:123]
	v_mfma_f32_16x16x32_bf16 v[112:115], v[156:159], v[194:197], v[112:115]
	s_setprio 0
	s_barrier
	s_add_i32 s28, 0, 0x1c000
	s_add_i32 s29, s56, s36
	v_add_u32_e32 v193, s28, v188
	v_lshl_add_u64 v[214:215], v[214:215], 0, s[16:17]
	s_mov_b32 m0, s29
	ds_read_b128 v[198:201], v193
	ds_read_b128 v[202:205], v193 offset:1024
	ds_read_b128 v[206:209], v193 offset:2048
	ds_read_b128 v[210:213], v193 offset:3072
	global_load_lds_dwordx4 v[214:215], off
	v_lshl_add_u64 v[214:215], v[216:217], 0, s[16:17]
	s_add_i32 m0, s29, 0x2000
	s_nop 0
	global_load_lds_dwordx4 v[214:215], off
	s_barrier
	s_waitcnt lgkmcnt(0)
	s_setprio 1
	s_waitcnt lgkmcnt(0)
	v_mfma_f32_16x16x32_bf16 v[76:79], v[198:201], v[160:163], v[76:79]
	v_mfma_f32_16x16x32_bf16 v[100:103], v[206:209], v[160:163], v[100:103]
	v_mfma_f32_16x16x32_bf16 v[72:75], v[198:201], v[168:171], v[72:75]
	v_mfma_f32_16x16x32_bf16 v[92:95], v[206:209], v[168:171], v[92:95]
	v_mfma_f32_16x16x32_bf16 v[68:71], v[198:201], v[176:179], v[68:71]
	v_mfma_f32_16x16x32_bf16 v[96:99], v[206:209], v[176:179], v[96:99]
	v_mfma_f32_16x16x32_bf16 v[64:67], v[198:201], v[184:187], v[64:67]
	v_mfma_f32_16x16x32_bf16 v[88:91], v[206:209], v[184:187], v[88:91]
	v_mfma_f32_16x16x32_bf16 v[76:79], v[202:205], v[164:167], v[76:79]
	v_mfma_f32_16x16x32_bf16 v[100:103], v[210:213], v[164:167], v[100:103]
	v_mfma_f32_16x16x32_bf16 v[72:75], v[202:205], v[172:175], v[72:75]
	v_mfma_f32_16x16x32_bf16 v[92:95], v[210:213], v[172:175], v[92:95]
	v_mfma_f32_16x16x32_bf16 v[68:71], v[202:205], v[180:183], v[68:71]
	v_mfma_f32_16x16x32_bf16 v[96:99], v[210:213], v[180:183], v[96:99]
	v_mfma_f32_16x16x32_bf16 v[64:67], v[202:205], v[194:197], v[64:67]
	v_mfma_f32_16x16x32_bf16 v[88:91], v[210:213], v[194:197], v[88:91]
	s_setprio 0
	s_mov_b32 m0, s47
	v_lshl_add_u64 v[214:215], v[218:219], 0, s[16:17]
	s_barrier
	ds_read_b128 v[160:163], v190 offset:49152
	ds_read_b128 v[164:167], v190 offset:50176
	ds_read_b128 v[168:171], v190 offset:51200
	ds_read_b128 v[172:175], v190 offset:52224
	ds_read_b128 v[176:179], v190 offset:53248
	ds_read_b128 v[180:183], v190 offset:54272
	ds_read_b128 v[184:187], v190 offset:55296
	ds_read_b128 v[194:197], v190 offset:56320
	global_load_lds_dwordx4 v[214:215], off
	v_lshl_add_u64 v[214:215], v[220:221], 0, s[16:17]
	s_mov_b32 m0, s48
	s_nop 0
	global_load_lds_dwordx4 v[214:215], off
	s_barrier
; #define PG8_WAIT_V(n) asm volatile("s_waitcnt vmcnt(" #n ")" ::: "memory")
; #define PG8_WAIT_L(n) asm volatile("s_waitcnt lgkmcnt(" #n ")" ::: "memory")
; template <class Epi>
; __device__ __forceinline__ void gemm_phase(LAS unsigned char* lds, const Gemm g, const StaticOrder& S, const Epi& E, int wave) {
;     ...
;             PG8_LDB(B0, 1, 0); PG8_SCHED; PG8_LDA(At, 1, 0); PG8_STAGE(PG8_SA(0, 1), a2 + hstep, voffA);
;             PG8_WAIT_L(8); PG8_BAR; PG8_WAIT_L(0); PG8_MMA(0, 0, At, B0); PG8_BAR; PG8_SCHED;
;             PG8_LDB(B1, 1, 1); PG8_STAGE(PG8_SB(1, 0), b3, voffB);
;             PG8_BAR; PG8_WAIT_L(0); PG8_MMA(0, 1, At, B1); PG8_BAR;
;             PG8_LDA(At, 1, 1); PG8_STAGE(PG8_SA(1, 0), a3, voffA);
;             PG8_BAR; PG8_WAIT_L(0); PG8_MMA(1, 0, At, B0); PG8_BAR; PG8_SCHED;
;             PG8_STAGE(PG8_SB(1, 1), b3 + hstep, voffB);
;             PG8_WAIT_V(6); PG8_BAR; PG8_MMA(1, 1, At, B1); PG8_BAR;
;     __device__ __forceinline__ void operator()(f32x4 (&acc)[2][2][4][2], const pg8::Unit& u, int wr, int wc, int, int) const {
;         int ln_; asm volatile("v_mbcnt_lo_u32_b32 %0, -1, 0\n\tv_mbcnt_hi_u32_b32 %0, -1, %0" : "=v"(ln_)); const int fr = ln_ & 15, fq = ln_ >> 4;
;         const int lprev4 = ((ln_ & 48) | ((fr + 15) & 15)) << 2, lnext4 = ((ln_ & 48) | ((fr + 1) & 15)) << 2;
;         const int f0 = u.pn * 128 + wc * 32 + 8 * fq;
;         float* lwv = lw + (wr * 4 + wc) * 128;
;         { const int p0 = ln_ >> 5, col = ln_ & 31, fb = u.pn * 128 + wc * 32;
;           const float a_ = cw[p0 * DFF + fb + col]; const float b_ = (p0 == 0) ? cw[2 * DFF + fb + col] : cb[fb + col];
;           lwv[p0 * 32 + col] = a_; lwv[(p0 + 2) * 32 + col] = b_; }
;         asm volatile("s_waitcnt lgkmcnt(0)" ::: "memory");
; #pragma unroll
;         for (int ai = 0; ai < 2; ++ai) {
;             const int rband = u.pm * 256 + ai * HALF + wr * 64;
; #pragma unroll
;             for (int n = 0; n < 2; ++n) {
;                 const bool efirst = (fr == 0), elast = (fr == 15);
;                 f32x4 eP, eG;
;                 const size_t eo = (size_t)((rband >> 6) * 2 + (elast ? 1 : 0)) * DFF + f0 + 4 * n;
;                 if (efirst || elast) { f32x4 eU;
; #pragma unroll
;                     for (int j = 0; j < 4; ++j) eU[j] = efirst ? acc[ai][1][0][n][j] : acc[ai][1][3][n][j];
;                     *(f32x4*)(sbu + eo) = eU; }
	s_waitcnt lgkmcnt(0)
	s_setprio 1
	s_waitcnt lgkmcnt(0)
	v_mfma_f32_16x16x32_bf16 v[60:63], v[144:147], v[160:163], v[60:63]
	v_mfma_f32_16x16x32_bf16 v[52:55], v[152:155], v[160:163], v[52:55]
	v_mfma_f32_16x16x32_bf16 v[16:19], v[144:147], v[168:171], v[16:19]
	v_mfma_f32_16x16x32_bf16 v[40:43], v[152:155], v[168:171], v[40:43]
	v_mfma_f32_16x16x32_bf16 v[20:23], v[144:147], v[176:179], v[20:23]
	v_mfma_f32_16x16x32_bf16 v[44:47], v[152:155], v[176:179], v[44:47]
	v_mfma_f32_16x16x32_bf16 v[56:59], v[144:147], v[184:187], v[56:59]
	v_mfma_f32_16x16x32_bf16 v[48:51], v[152:155], v[184:187], v[48:51]
	v_mfma_f32_16x16x32_bf16 v[60:63], v[148:151], v[164:167], v[60:63]
	v_mfma_f32_16x16x32_bf16 v[52:55], v[156:159], v[164:167], v[52:55]
	v_mfma_f32_16x16x32_bf16 v[16:19], v[148:151], v[172:175], v[16:19]
	v_mfma_f32_16x16x32_bf16 v[40:43], v[156:159], v[172:175], v[40:43]
	v_mfma_f32_16x16x32_bf16 v[20:23], v[148:151], v[180:183], v[20:23]
	v_mfma_f32_16x16x32_bf16 v[44:47], v[156:159], v[180:183], v[44:47]
	v_mfma_f32_16x16x32_bf16 v[56:59], v[148:151], v[194:197], v[56:59]
	v_mfma_f32_16x16x32_bf16 v[48:51], v[156:159], v[194:197], v[48:51]
	s_setprio 0
	s_barrier
	s_add_u32 s6, s6, 0x40080
	s_addc_u32 s7, s7, 0
	s_add_i32 s28, s28, s36
	v_lshl_add_u64 v[144:145], s[6:7], 0, v[132:133]
	s_mov_b32 m0, s28
	s_nop 0
	global_load_lds_dwordx4 v[144:145], off
	v_lshl_add_u64 v[144:145], s[6:7], 0, v[128:129]
	s_add_i32 m0, s28, 0x2000
	s_nop 0
	global_load_lds_dwordx4 v[144:145], off
	s_waitcnt vmcnt(6)
	s_barrier
	s_setprio 1
	v_mfma_f32_16x16x32_bf16 v[12:15], v[198:201], v[160:163], v[12:15]
	v_mfma_f32_16x16x32_bf16 v[36:39], v[206:209], v[160:163], v[36:39]
	v_mfma_f32_16x16x32_bf16 v[8:11], v[198:201], v[168:171], v[8:11]
	v_mfma_f32_16x16x32_bf16 v[28:31], v[206:209], v[168:171], v[28:31]
	v_mfma_f32_16x16x32_bf16 v[4:7], v[198:201], v[176:179], v[4:7]
	v_mfma_f32_16x16x32_bf16 v[32:35], v[206:209], v[176:179], v[32:35]
	v_mfma_f32_16x16x32_bf16 v[0:3], v[198:201], v[184:187], v[0:3]
	v_mfma_f32_16x16x32_bf16 v[24:27], v[206:209], v[184:187], v[24:27]
	v_mfma_f32_16x16x32_bf16 v[12:15], v[202:205], v[164:167], v[12:15]
	v_mfma_f32_16x16x32_bf16 v[36:39], v[210:213], v[164:167], v[36:39]
	v_mfma_f32_16x16x32_bf16 v[8:11], v[202:205], v[172:175], v[8:11]
	v_mfma_f32_16x16x32_bf16 v[28:31], v[210:213], v[172:175], v[28:31]
	v_mfma_f32_16x16x32_bf16 v[4:7], v[202:205], v[180:183], v[4:7]
	v_mfma_f32_16x16x32_bf16 v[32:35], v[210:213], v[180:183], v[32:35]
	v_mfma_f32_16x16x32_bf16 v[0:3], v[202:205], v[194:197], v[0:3]
	v_mfma_f32_16x16x32_bf16 v[24:27], v[210:213], v[194:197], v[24:27]
	s_setprio 0
	s_add_i32 s55, s55, 2
	s_add_u32 s4, s4, 0x100
	s_addc_u32 s5, s5, 0
	s_add_u32 s31, s31, 0x100
	s_addc_u32 s54, s54, 0
	s_cmp_gt_u32 s55, 13
	s_barrier
	s_cbranch_scc0 .LBB0_810
	v_mbcnt_lo_u32_b32 v146, -1, 0
	v_mbcnt_hi_u32_b32 v146, -1, v146
	s_lshl_b32 s3, s3, 7
	v_lshrrev_b32_e32 v144, 5, v146
	s_or_b32 s3, s3, s46
	v_mul_lo_u32 v144, v144, s52
	v_and_b32_e32 v147, 31, v146
	v_add_u32_e32 v144, s3, v144
	v_or_b32_e32 v144, v144, v147
	v_readlane_b32 s56, v253, 0
	v_ashrrev_i32_e32 v145, 31, v144
	v_readlane_b32 s57, v253, 1
	s_add_i32 s4, s3, 0x1600
	v_readlane_b32 s59, v253, 3
	v_lshl_add_u64 v[144:145], v[144:145], 2, s[56:57]
	v_or_b32_e32 v144, s3, v147
	v_add_u32_e32 v145, s4, v146
	v_cmp_gt_u32_e32 vcc, 32, v146
	v_readlane_b32 s58, v253, 2
	v_mov_b32_e32 v148, s57
	v_cndmask_b32_e32 v144, v144, v145, vcc
	v_mov_b32_e32 v145, s59
	v_cndmask_b32_e32 v149, v145, v148, vcc
	v_mov_b32_e32 v145, s58
	v_mov_b32_e32 v148, s56
	v_cndmask_b32_e32 v148, v145, v148, vcc
	v_ashrrev_i32_e32 v145, 31, v144
	v_lshl_add_u64 v[144:145], v[144:145], 2, v[148:149]
	v_and_b32_e32 v148, 0x3fffffe0, v146
	v_lshl_add_u32 v145, v146, 2, s49
	v_lshlrev_b32_e32 v148, 2, v148
	v_lshlrev_b32_e32 v147, 2, v147
	v_add3_u32 v147, s49, v148, v147
	v_and_b32_e32 v193, 15, v146
	v_cmp_eq_u32_e64 s[4:5], 0, v193
	v_cmp_eq_u32_e32 vcc, 15, v193
	v_cmp_gt_i32_e64 s[6:7], 15, v193
	s_mov_b64 s[28:29], -1
	v_readlane_b32 s60, v253, 4
	v_readlane_b32 s61, v253, 5
	v_readlane_b32 s62, v253, 6
	v_readlane_b32 s63, v253, 7
	s_waitcnt vmcnt(14)
	ds_write_b32 v145, v252
	ds_write_b32 v147, v255 offset:256
	s_waitcnt lgkmcnt(0)
	s_and_saveexec_b64 s[30:31], s[6:7]
	v_cmp_eq_u32_e64 s[6:7], 0, v193
	s_orn2_b64 s[28:29], s[6:7], exec
	s_or_b64 exec, exec, s[30:31]
	v_ashrrev_i32_e32 v176, 1, v146
	v_and_b32_e32 v147, -8, v176
	v_add_u32_e32 v144, s3, v147
	s_lshl_b32 s3, s26, 8
	s_add_i32 s3, s3, s45
	v_cndmask_b32_e64 v197, 0, 1, vcc
	s_ashr_i32 s6, s3, 5
	v_ashrrev_i32_e32 v145, 31, v144
	v_or_b32_e32 v148, s6, v197
	v_mad_i64_i32 v[170:171], s[6:7], v148, s52, v[144:145]
	s_and_saveexec_b64 s[6:7], s[28:29]
	s_cbranch_execz .LBB0_815
	v_cndmask_b32_e64 v151, v67, v79, s[4:5]
	v_cndmask_b32_e64 v150, v66, v78, s[4:5]
	v_cndmask_b32_e64 v149, v65, v77, s[4:5]
	v_cndmask_b32_e64 v148, v64, v76, s[4:5]
	v_lshl_add_u64 v[152:153], v[170:171], 2, s[12:13]
	global_store_dwordx4 v[152:153], v[148:151], off sc1
;     __device__ __forceinline__ void operator()(f32x4 (&acc)[2][2][4][2], const pg8::Unit& u, int wr, int wc, int, int) const {
;     ...
;                 for (int j = 0; j < 4; ++j) {
;                     const int lc = 8 * fq + 4 * n + j; const float w0 = lwv[lc], w1 = lwv[32 + lc], w2 = lwv[64 + lc], bb = lwv[96 + lc];
;                     float gp[4], gn[4];
; #pragma unroll
;                     for (int m = 0; m < 4; ++m) { const int gi_ = __float_as_int(acc[ai][0][m][n][j]); gp[m] = __int_as_float(__builtin_amdgcn_ds_bpermute(lprev4, gi_)); gn[m] = __int_as_float(__builtin_amdgcn_ds_bpermute(lnext4, gi_)); }
;                     float pre0 = 0.f, pre3 = 0.f;
; #pragma unroll
;                     for (int m = 0; m < 4; ++m) {
;                         const float g = acc[ai][0][m][n][j], uv = acc[ai][1][m][n][j];
;                         const float pv = (fr == 0) ? (m > 0 ? gp[m > 0 ? m - 1 : 0] : 0.f) : gp[m];
;                         const float nv = (fr == 15) ? (m < 3 ? gn[m < 3 ? m + 1 : 3] : 0.f) : gn[m];
;                         const float pre = w0 * pv + w1 * g + w2 * nv + bb;
;                         if (m == 0) pre0 = pre;
;                         if (m == 3) pre3 = pre;
;                         acc[ai][1][m][n][j] = gelu_tanh(pre) * uv;
;                     }
;                     eP[j] = efirst ? pre0 : pre3;
;                     __builtin_amdgcn_sched_barrier(0);
;                 }
; #pragma unroll
;                 for (int j = 0; j < 4; ++j) eG[j] = efirst ? acc[ai][0][0][n][j] : acc[ai][0][3][n][j];
;                 if (efirst || elast) { *(f32x4*)(sbp + eo) = eP; *(f32x4*)(sbg + eo) = eG; }
.LBB0_815:
	s_or_b64 exec, exec, s[6:7]
	s_nop 0
	v_and_b32_e32 v148, 48, v146
	v_add_u32_e32 v149, -1, v146
	v_add_u32_e32 v146, 1, v146
	v_and_or_b32 v149, v149, 15, v148
	v_and_or_b32 v146, v146, 15, v148
	v_lshl_add_u32 v196, v147, 2, s49
	v_lshlrev_b32_e32 v194, 2, v149
	v_lshlrev_b32_e32 v195, 2, v146
	ds_read2_b32 v[154:155], v196 offset1:32
	ds_read2_b32 v[156:157], v196 offset0:64 offset1:96
	v_mov_b32_dpp v212, v124 row_ror:1 row_mask:0xf bank_mask:0xf
	v_mov_b32_dpp v164, v124 row_ror:15 row_mask:0xf bank_mask:0xf
	v_mov_b32_dpp v214, v80 row_ror:1 row_mask:0xf bank_mask:0xf
	v_mov_b32_dpp v211, v80 row_ror:15 row_mask:0xf bank_mask:0xf
	v_mov_b32_dpp v220, v84 row_ror:1 row_mask:0xf bank_mask:0xf
	v_mov_b32_dpp v213, v84 row_ror:15 row_mask:0xf bank_mask:0xf
	v_mov_b32_dpp v158, v120 row_ror:1 row_mask:0xf bank_mask:0xf
	v_mov_b32_dpp v219, v120 row_ror:15 row_mask:0xf bank_mask:0xf
	s_waitcnt lgkmcnt(0)
	v_mov_b32_e32 v162, v155
	v_mov_b32_e32 v160, v157
	ds_read2_b32 v[146:147], v196 offset0:1 offset1:33
	ds_read2_b32 v[148:149], v196 offset0:65 offset1:97
	v_mov_b32_dpp v216, v125 row_ror:1 row_mask:0xf bank_mask:0xf
	v_mov_b32_dpp v167, v125 row_ror:15 row_mask:0xf bank_mask:0xf
	v_mov_b32_dpp v218, v81 row_ror:1 row_mask:0xf bank_mask:0xf
	v_mov_b32_dpp v215, v81 row_ror:15 row_mask:0xf bank_mask:0xf
	v_mov_b32_dpp v222, v85 row_ror:1 row_mask:0xf bank_mask:0xf
	v_mov_b32_dpp v217, v85 row_ror:15 row_mask:0xf bank_mask:0xf
	v_mov_b32_dpp v166, v121 row_ror:1 row_mask:0xf bank_mask:0xf
	v_mov_b32_dpp v221, v121 row_ror:15 row_mask:0xf bank_mask:0xf
	s_waitcnt lgkmcnt(0)
	v_mov_b32_e32 v155, v146
	v_mov_b32_e32 v163, v147
	s_waitcnt lgkmcnt(0)
	v_mov_b32_e32 v157, v148
	v_mov_b32_e32 v161, v149
	ds_read2_b32 v[146:147], v196 offset0:2 offset1:34
	ds_read2_b32 v[148:149], v196 offset0:66 offset1:98
	v_mov_b32_dpp v200, v126 row_ror:1 row_mask:0xf bank_mask:0xf
	v_mov_b32_dpp v165, v126 row_ror:15 row_mask:0xf bank_mask:0xf
	v_mov_b32_dpp v202, v82 row_ror:1 row_mask:0xf bank_mask:0xf
	v_mov_b32_dpp v199, v82 row_ror:15 row_mask:0xf bank_mask:0xf
	v_mov_b32_dpp v208, v86 row_ror:1 row_mask:0xf bank_mask:0xf
	v_mov_b32_dpp v201, v86 row_ror:15 row_mask:0xf bank_mask:0xf
	v_mov_b32_dpp v159, v122 row_ror:1 row_mask:0xf bank_mask:0xf
	v_mov_b32_dpp v207, v122 row_ror:15 row_mask:0xf bank_mask:0xf
	ds_read2_b32 v[168:169], v196 offset0:3 offset1:35
	ds_read2_b32 v[174:175], v196 offset0:67 offset1:99
	v_mov_b32_dpp v204, v127 row_ror:1 row_mask:0xf bank_mask:0xf
	v_mov_b32_dpp v173, v127 row_ror:15 row_mask:0xf bank_mask:0xf
	v_mov_b32_dpp v206, v83 row_ror:1 row_mask:0xf bank_mask:0xf
	v_mov_b32_dpp v203, v83 row_ror:15 row_mask:0xf bank_mask:0xf
	v_mov_b32_dpp v210, v87 row_ror:1 row_mask:0xf bank_mask:0xf
	v_mov_b32_dpp v205, v87 row_ror:15 row_mask:0xf bank_mask:0xf
	v_mov_b32_dpp v172, v123 row_ror:1 row_mask:0xf bank_mask:0xf
	v_mov_b32_dpp v209, v123 row_ror:15 row_mask:0xf bank_mask:0xf
	s_waitcnt lgkmcnt(0)
	v_mov_b32_e32 v152, v147
	v_mov_b32_e32 v150, v149
	s_waitcnt lgkmcnt(0)
	v_mov_b32_e32 v147, v168
	v_mov_b32_e32 v153, v169
	s_waitcnt lgkmcnt(0)
	v_mov_b32_e32 v149, v174
	v_mov_b32_e32 v151, v175
	v_cmp_gt_i32_e64 s[6:7], 15, v193
	s_mov_b64 s[26:27], -1
	s_and_saveexec_b64 s[28:29], s[6:7]
	v_cmp_eq_u32_e64 s[6:7], 0, v193
	s_orn2_b64 s[26:27], s[6:7], exec
	s_or_b64 exec, exec, s[28:29]
	v_cndmask_b32_e64 v169, v216, 0, s[4:5]
	v_cndmask_b32_e64 v168, v212, 0, s[4:5]
	v_cndmask_b32_e32 v175, v167, v215, vcc
	v_pk_mul_f32 v[168:169], v[154:155], v[168:169]
	v_cndmask_b32_e64 v167, v166, v222, s[4:5]
	v_cndmask_b32_e64 v166, v158, v220, s[4:5]
	v_cndmask_b32_e32 v174, v164, v211, vcc
	v_pk_fma_f32 v[168:169], v[124:125], v[162:163], v[168:169]
	v_pk_mul_f32 v[166:167], v[154:155], v[166:167]
	v_pk_fma_f32 v[168:169], v[156:157], v[174:175], v[168:169]
	v_cndmask_b32_e64 v175, v221, 0, vcc
	v_cndmask_b32_e64 v174, v219, 0, vcc
	v_pk_fma_f32 v[166:167], v[120:121], v[162:163], v[166:167]
	s_waitcnt lgkmcnt(0)
	v_cndmask_b32_e32 v179, v173, v203, vcc
	v_pk_fma_f32 v[166:167], v[156:157], v[174:175], v[166:167]
	v_cndmask_b32_e64 v175, v204, 0, s[4:5]
	v_cndmask_b32_e64 v174, v200, 0, s[4:5]
	s_waitcnt lgkmcnt(0)
	v_cndmask_b32_e64 v173, v172, v210, s[4:5]
	v_cndmask_b32_e64 v172, v159, v208, s[4:5]
	v_cndmask_b32_e32 v178, v165, v199, vcc
	v_pk_mul_f32 v[164:165], v[146:147], v[174:175]
	v_pk_mul_f32 v[172:173], v[146:147], v[172:173]
	v_pk_fma_f32 v[164:165], v[126:127], v[152:153], v[164:165]
	s_waitcnt lgkmcnt(0)
	v_cndmask_b32_e64 v159, v209, 0, vcc
	v_cndmask_b32_e64 v158, v207, 0, vcc
	v_pk_fma_f32 v[172:173], v[122:123], v[152:153], v[172:173]
	v_pk_fma_f32 v[164:165], v[148:149], v[178:179], v[164:165]
	v_pk_fma_f32 v[158:159], v[148:149], v[158:159], v[172:173]
	v_pk_add_f32 v[168:169], v[160:161], v[168:169]
	v_pk_add_f32 v[166:167], v[160:161], v[166:167]
	v_pk_add_f32 v[164:165], v[150:151], v[164:165]
	v_pk_add_f32 v[158:159], v[150:151], v[158:159]
	s_and_saveexec_b64 s[6:7], s[26:27]
	s_cbranch_execz .LBB0_819
	v_lshlrev_b64 v[172:173], 2, v[170:171]
	v_cndmask_b32_e64 v123, v123, v127, s[4:5]
	v_cndmask_b32_e64 v122, v122, v126, s[4:5]
	v_cndmask_b32_e64 v121, v121, v125, s[4:5]
	v_cndmask_b32_e64 v120, v120, v124, s[4:5]
	v_cndmask_b32_e64 v127, v159, v165, s[4:5]
	v_cndmask_b32_e64 v126, v158, v164, s[4:5]
	v_cndmask_b32_e64 v125, v167, v169, s[4:5]
	v_cndmask_b32_e64 v124, v166, v168, s[4:5]
	v_lshl_add_u64 v[174:175], s[10:11], 0, v[172:173]
	global_store_dwordx4 v[174:175], v[124:127], off sc1
	s_nop 1
	v_lshl_add_u64 v[124:125], s[14:15], 0, v[172:173]
	global_store_dwordx4 v[124:125], v[120:123], off sc1
;     __device__ __forceinline__ void operator()(f32x4 (&acc)[2][2][4][2], const pg8::Unit& u, int wr, int wc, int, int) const {
;     ...
;             for (int n = 0; n < 2; ++n) {
;                 const bool efirst = (fr == 0), elast = (fr == 15);
;                 f32x4 eP, eG;
;                 const size_t eo = (size_t)((rband >> 6) * 2 + (elast ? 1 : 0)) * DFF + f0 + 4 * n;
;                 if (efirst || elast) { f32x4 eU;
; #pragma unroll
;                     for (int j = 0; j < 4; ++j) eU[j] = efirst ? acc[ai][1][0][n][j] : acc[ai][1][3][n][j];
;                     *(f32x4*)(sbu + eo) = eU; }
; #pragma unroll
;                 for (int j = 0; j < 4; ++j) {
;                     const int lc = 8 * fq + 4 * n + j; const float w0 = lwv[lc], w1 = lwv[32 + lc], w2 = lwv[64 + lc], bb = lwv[96 + lc];
;                     float gp[4], gn[4];
; #pragma unroll
;                     for (int m = 0; m < 4; ++m) { const int gi_ = __float_as_int(acc[ai][0][m][n][j]); gp[m] = __int_as_float(__builtin_amdgcn_ds_bpermute(lprev4, gi_)); gn[m] = __int_as_float(__builtin_amdgcn_ds_bpermute(lnext4, gi_)); }
;                     float pre0 = 0.f, pre3 = 0.f;
; #pragma unroll
;                     for (int m = 0; m < 4; ++m) {
;                         const float g = acc[ai][0][m][n][j], uv = acc[ai][1][m][n][j];
;                         const float pv = (fr == 0) ? (m > 0 ? gp[m > 0 ? m - 1 : 0] : 0.f) : gp[m];
;                         const float nv = (fr == 15) ? (m < 3 ? gn[m < 3 ? m + 1 : 3] : 0.f) : gn[m];
;                         const float pre = w0 * pv + w1 * g + w2 * nv + bb;
;                         if (m == 0) pre0 = pre;
;                         if (m == 3) pre3 = pre;
;                         acc[ai][1][m][n][j] = gelu_tanh(pre) * uv;
;                     }
;                     eP[j] = efirst ? pre0 : pre3;
;                     __builtin_amdgcn_sched_barrier(0);
;                 }
; #pragma unroll
;                 for (int j = 0; j < 4; ++j) eG[j] = efirst ? acc[ai][0][0][n][j] : acc[ai][0][3][n][j];
;                 if (efirst || elast) { *(f32x4*)(sbp + eo) = eP; *(f32x4*)(sbg + eo) = eG; }
.LBB0_819:
	s_or_b64 exec, exec, s[6:7]
	v_cmp_gt_i32_e64 s[6:7], 15, v193
	s_mov_b64 s[26:27], -1
	s_and_saveexec_b64 s[28:29], s[6:7]
	v_cmp_eq_u32_e64 s[6:7], 0, v193
	s_orn2_b64 s[26:27], s[6:7], exec
	s_or_b64 exec, exec, s[28:29]
	v_or_b32_e32 v170, 4, v170
	s_and_saveexec_b64 s[6:7], s[26:27]
	s_cbranch_execz .LBB0_823
	v_cndmask_b32_e64 v123, v91, v103, s[4:5]
	v_cndmask_b32_e64 v122, v90, v102, s[4:5]
	v_cndmask_b32_e64 v121, v89, v101, s[4:5]
	v_cndmask_b32_e64 v120, v88, v100, s[4:5]
	v_lshl_add_u64 v[124:125], v[170:171], 2, s[12:13]
	global_store_dwordx4 v[124:125], v[120:123], off sc1
.LBB0_823:
	s_or_b64 exec, exec, s[6:7]
	ds_read2_b32 v[172:173], v196 offset0:4 offset1:36
	ds_read2_b32 v[174:175], v196 offset0:68 offset1:100
	v_mov_b32_dpp v236, v116 row_ror:1 row_mask:0xf bank_mask:0xf
	v_mov_b32_dpp v182, v116 row_ror:15 row_mask:0xf bank_mask:0xf
	v_mov_b32_dpp v238, v104 row_ror:1 row_mask:0xf bank_mask:0xf
	v_mov_b32_dpp v235, v104 row_ror:15 row_mask:0xf bank_mask:0xf
	v_mov_b32_dpp v244, v108 row_ror:1 row_mask:0xf bank_mask:0xf
	v_mov_b32_dpp v237, v108 row_ror:15 row_mask:0xf bank_mask:0xf
	v_mov_b32_dpp v177, v112 row_ror:1 row_mask:0xf bank_mask:0xf
	v_mov_b32_dpp v243, v112 row_ror:15 row_mask:0xf bank_mask:0xf
	s_waitcnt lgkmcnt(0)
	v_mov_b32_e32 v180, v173
	s_waitcnt lgkmcnt(0)
	v_mov_b32_e32 v178, v175
	ds_read2_b32 v[120:121], v196 offset0:5 offset1:37
	ds_read2_b32 v[122:123], v196 offset0:69 offset1:101
	v_mov_b32_dpp v240, v117 row_ror:1 row_mask:0xf bank_mask:0xf
	v_mov_b32_dpp v185, v117 row_ror:15 row_mask:0xf bank_mask:0xf
	v_mov_b32_dpp v242, v105 row_ror:1 row_mask:0xf bank_mask:0xf
	v_mov_b32_dpp v239, v105 row_ror:15 row_mask:0xf bank_mask:0xf
	v_mov_b32_dpp v246, v109 row_ror:1 row_mask:0xf bank_mask:0xf
	v_mov_b32_dpp v241, v109 row_ror:15 row_mask:0xf bank_mask:0xf
	v_mov_b32_dpp v184, v113 row_ror:1 row_mask:0xf bank_mask:0xf
	v_mov_b32_dpp v245, v113 row_ror:15 row_mask:0xf bank_mask:0xf
	s_waitcnt lgkmcnt(0)
	v_mov_b32_e32 v173, v120
	v_mov_b32_e32 v181, v121
	s_waitcnt lgkmcnt(0)
	v_mov_b32_e32 v175, v122
	v_mov_b32_e32 v179, v123
	ds_read2_b32 v[120:121], v196 offset0:6 offset1:38
	ds_read2_b32 v[122:123], v196 offset0:70 offset1:102
	v_mov_b32_dpp v224, v118 row_ror:1 row_mask:0xf bank_mask:0xf
	v_mov_b32_dpp v183, v118 row_ror:15 row_mask:0xf bank_mask:0xf
	v_mov_b32_dpp v226, v106 row_ror:1 row_mask:0xf bank_mask:0xf
	v_mov_b32_dpp v223, v106 row_ror:15 row_mask:0xf bank_mask:0xf
	v_mov_b32_dpp v232, v110 row_ror:1 row_mask:0xf bank_mask:0xf
	v_mov_b32_dpp v225, v110 row_ror:15 row_mask:0xf bank_mask:0xf
	v_mov_b32_dpp v247, v114 row_ror:1 row_mask:0xf bank_mask:0xf
	v_mov_b32_dpp v231, v114 row_ror:15 row_mask:0xf bank_mask:0xf
	s_waitcnt lgkmcnt(0)
	v_mov_b32_e32 v126, v121
	v_lshl_or_b32 v121, v176, 2, 28
	v_add_u32_e32 v198, s49, v121
	ds_read2_b32 v[186:187], v198 offset1:32
	ds_read2_b32 v[250:251], v198 offset0:64 offset1:96
	v_mov_b32_dpp v228, v119 row_ror:1 row_mask:0xf bank_mask:0xf
	v_mov_b32_dpp v248, v119 row_ror:15 row_mask:0xf bank_mask:0xf
	v_mov_b32_dpp v230, v107 row_ror:1 row_mask:0xf bank_mask:0xf
	v_mov_b32_dpp v227, v107 row_ror:15 row_mask:0xf bank_mask:0xf
	v_mov_b32_dpp v234, v111 row_ror:1 row_mask:0xf bank_mask:0xf
	v_mov_b32_dpp v229, v111 row_ror:15 row_mask:0xf bank_mask:0xf
	v_mov_b32_dpp v176, v115 row_ror:1 row_mask:0xf bank_mask:0xf
	v_mov_b32_dpp v233, v115 row_ror:15 row_mask:0xf bank_mask:0xf
	s_waitcnt lgkmcnt(0)
	v_mov_b32_e32 v124, v123
	s_waitcnt lgkmcnt(0)
	v_mov_b32_e32 v121, v186
	v_mov_b32_e32 v127, v187
	s_waitcnt lgkmcnt(0)
	v_mov_b32_e32 v123, v250
	v_mov_b32_e32 v125, v251
	v_cmp_gt_i32_e64 s[6:7], 15, v193
	s_mov_b64 s[26:27], -1
	s_and_saveexec_b64 s[28:29], s[6:7]
	v_cmp_eq_u32_e64 s[6:7], 0, v193
	s_orn2_b64 s[26:27], s[6:7], exec
	s_or_b64 exec, exec, s[28:29]
	v_cndmask_b32_e64 v186, v236, 0, s[4:5]
	v_cndmask_b32_e64 v187, v240, 0, s[4:5]
	v_pk_mul_f32 v[186:187], v[172:173], v[186:187]
	v_cndmask_b32_e32 v250, v182, v235, vcc
	v_cndmask_b32_e32 v251, v185, v239, vcc
	v_pk_fma_f32 v[186:187], v[116:117], v[180:181], v[186:187]
	v_cndmask_b32_e64 v185, v245, 0, vcc
	v_pk_fma_f32 v[186:187], v[174:175], v[250:251], v[186:187]
	v_cndmask_b32_e64 v250, v177, v244, s[4:5]
	v_cndmask_b32_e64 v251, v184, v246, s[4:5]
	v_pk_mul_f32 v[250:251], v[172:173], v[250:251]
	v_cndmask_b32_e64 v184, v243, 0, vcc
	v_pk_fma_f32 v[250:251], v[112:113], v[180:181], v[250:251]
	v_cndmask_b32_e32 v182, v183, v223, vcc
	v_pk_fma_f32 v[184:185], v[174:175], v[184:185], v[250:251]
	v_cndmask_b32_e64 v250, v224, 0, s[4:5]
	s_waitcnt lgkmcnt(0)
	v_cndmask_b32_e64 v251, v228, 0, s[4:5]
	s_waitcnt lgkmcnt(0)
	v_cndmask_b32_e32 v183, v248, v227, vcc
	v_pk_mul_f32 v[248:249], v[120:121], v[250:251]
	s_waitcnt lgkmcnt(0)
	v_cndmask_b32_e64 v177, v233, 0, vcc
	v_pk_fma_f32 v[248:249], v[118:119], v[126:127], v[248:249]
	v_pk_add_f32 v[186:187], v[178:179], v[186:187]
	v_pk_fma_f32 v[182:183], v[122:123], v[182:183], v[248:249]
	v_cndmask_b32_e64 v248, v247, v232, s[4:5]
	v_cndmask_b32_e64 v249, v176, v234, s[4:5]
	v_pk_mul_f32 v[248:249], v[120:121], v[248:249]
	v_cndmask_b32_e64 v176, v231, 0, vcc
	v_pk_fma_f32 v[248:249], v[114:115], v[126:127], v[248:249]
	v_pk_add_f32 v[184:185], v[178:179], v[184:185]
	v_pk_fma_f32 v[176:177], v[122:123], v[176:177], v[248:249]
	v_pk_add_f32 v[182:183], v[124:125], v[182:183]
	v_pk_add_f32 v[176:177], v[124:125], v[176:177]
	s_and_saveexec_b64 s[6:7], s[26:27]
	s_cbranch_execz .LBB0_827
	v_lshlrev_b64 v[170:171], 2, v[170:171]
	v_cndmask_b32_e64 v115, v115, v119, s[4:5]
	v_cndmask_b32_e64 v114, v114, v118, s[4:5]
	v_cndmask_b32_e64 v113, v113, v117, s[4:5]
	v_cndmask_b32_e64 v112, v112, v116, s[4:5]
	v_cndmask_b32_e64 v119, v177, v183, s[4:5]
	v_cndmask_b32_e64 v118, v176, v182, s[4:5]
	v_cndmask_b32_e64 v117, v185, v187, s[4:5]
	v_cndmask_b32_e64 v116, v184, v186, s[4:5]
	v_lshl_add_u64 v[248:249], s[10:11], 0, v[170:171]
	global_store_dwordx4 v[248:249], v[116:119], off sc1
	s_nop 1
	v_lshl_add_u64 v[116:117], s[14:15], 0, v[170:171]
	global_store_dwordx4 v[116:117], v[112:115], off sc1
;     __device__ __forceinline__ void operator()(f32x4 (&acc)[2][2][4][2], const pg8::Unit& u, int wr, int wc, int, int) const {
;     ...
;                 for (int j = 0; j < 4; ++j) {
;                     const int lc = 8 * fq + 4 * n + j; const float w0 = lwv[lc], w1 = lwv[32 + lc], w2 = lwv[64 + lc], bb = lwv[96 + lc];
;                     float gp[4], gn[4];
; #pragma unroll
;                     for (int m = 0; m < 4; ++m) { const int gi_ = __float_as_int(acc[ai][0][m][n][j]); gp[m] = __int_as_float(__builtin_amdgcn_ds_bpermute(lprev4, gi_)); gn[m] = __int_as_float(__builtin_amdgcn_ds_bpermute(lnext4, gi_)); }
;                     float pre0 = 0.f, pre3 = 0.f;
; #pragma unroll
;                     for (int m = 0; m < 4; ++m) {
;                         const float g = acc[ai][0][m][n][j], uv = acc[ai][1][m][n][j];
;                         const float pv = (fr == 0) ? (m > 0 ? gp[m > 0 ? m - 1 : 0] : 0.f) : gp[m];
;                         const float nv = (fr == 15) ? (m < 3 ? gn[m < 3 ? m + 1 : 3] : 0.f) : gn[m];
;                         const float pre = w0 * pv + w1 * g + w2 * nv + bb;
;                         if (m == 0) pre0 = pre;
;                         if (m == 3) pre3 = pre;
;                         acc[ai][1][m][n][j] = gelu_tanh(pre) * uv;
;                     }
.LBB0_827:
	s_or_b64 exec, exec, s[6:7]
	s_nop 0
	v_pk_mul_f32 v[112:113], v[186:187], v[186:187]
	v_cndmask_b32_e64 v117, v246, v242, s[4:5]
	v_fmamk_f32 v112, v112, 0x3dd2d3e8, v192
	v_fmamk_f32 v113, v113, 0x3dd2d3e8, v192
	v_cndmask_b32_e64 v116, v244, v238, s[4:5]
	v_mul_f32_e32 v112, v186, v112
	v_mul_f32_e32 v113, v187, v113
	v_pk_mul_f32 v[116:117], v[172:173], v[116:117]
	v_exp_f32_e32 v112, v112
	v_exp_f32_e32 v113, v113
	v_cndmask_b32_e32 v119, v241, v245, vcc
	v_cndmask_b32_e32 v118, v237, v243, vcc
	v_pk_fma_f32 v[108:109], v[108:109], v[180:181], v[116:117]
	v_add_f32_e32 v112, 1.0, v112
	v_pk_fma_f32 v[108:109], v[174:175], v[118:119], v[108:109]
	v_add_f32_e32 v113, 1.0, v113
	v_pk_add_f32 v[108:109], v[178:179], v[108:109]
	v_rcp_f32_e32 v112, v112
	v_pk_mul_f32 v[116:117], v[108:109], v[108:109]
	v_rcp_f32_e32 v113, v113
	v_fmamk_f32 v116, v116, 0x3dd2d3e8, v192
	v_fmamk_f32 v117, v117, 0x3dd2d3e8, v192
	v_mul_f32_e32 v116, v108, v116
	v_mul_f32_e32 v117, v109, v117
	v_exp_f32_e32 v116, v116
	v_exp_f32_e32 v117, v117
	v_pk_fma_f32 v[112:113], v[186:187], v[112:113], v[186:187] neg_lo:[1,0,0] neg_hi:[1,0,0]
	v_cndmask_b32_e32 v119, v239, v241, vcc
	v_pk_mul_f32 v[100:101], v[100:101], v[112:113]
	v_add_f32_e32 v112, 1.0, v116
	v_add_f32_e32 v113, 1.0, v117
	v_cndmask_b32_e64 v117, v242, v240, s[4:5]
	v_cndmask_b32_e64 v116, v238, v236, s[4:5]
	v_pk_mul_f32 v[116:117], v[172:173], v[116:117]
	v_cndmask_b32_e32 v118, v235, v237, vcc
	v_pk_fma_f32 v[104:105], v[104:105], v[180:181], v[116:117]
	v_pk_mul_f32 v[114:115], v[184:185], v[184:185]
	v_pk_fma_f32 v[104:105], v[174:175], v[118:119], v[104:105]
	v_fmamk_f32 v114, v114, 0x3dd2d3e8, v192
	v_pk_add_f32 v[104:105], v[178:179], v[104:105]
	v_fmamk_f32 v115, v115, 0x3dd2d3e8, v192
	v_pk_mul_f32 v[116:117], v[104:105], v[104:105]
	v_mul_f32_e32 v114, v184, v114
	v_fmamk_f32 v116, v116, 0x3dd2d3e8, v192
	v_fmamk_f32 v117, v117, 0x3dd2d3e8, v192
	v_mul_f32_e32 v116, v104, v116
	v_mul_f32_e32 v117, v105, v117
	v_rcp_f32_e32 v112, v112
	v_exp_f32_e32 v116, v116
	v_exp_f32_e32 v117, v117
	v_rcp_f32_e32 v113, v113
	v_mul_f32_e32 v115, v185, v115
	v_exp_f32_e32 v114, v114
	v_exp_f32_e32 v115, v115
	v_add_f32_e32 v116, 1.0, v116
	v_add_f32_e32 v117, 1.0, v117
	v_pk_fma_f32 v[108:109], v[108:109], v[112:113], v[108:109] neg_lo:[1,0,0] neg_hi:[1,0,0]
	v_add_f32_e32 v114, 1.0, v114
	v_rcp_f32_e32 v116, v116
	v_rcp_f32_e32 v117, v117
	v_pk_mul_f32 v[96:97], v[96:97], v[108:109]
	v_add_f32_e32 v108, 1.0, v115
	v_rcp_f32_e32 v114, v114
	v_rcp_f32_e32 v115, v108
	v_cndmask_b32_e64 v113, v234, v230, s[4:5]
	v_cndmask_b32_e64 v112, v232, v226, s[4:5]
	v_pk_fma_f32 v[104:105], v[104:105], v[116:117], v[104:105] neg_lo:[1,0,0] neg_hi:[1,0,0]
	v_pk_mul_f32 v[112:113], v[120:121], v[112:113]
	v_pk_mul_f32 v[92:93], v[92:93], v[104:105]
	v_pk_fma_f32 v[104:105], v[184:185], v[114:115], v[184:185] neg_lo:[1,0,0] neg_hi:[1,0,0]
	v_cndmask_b32_e32 v115, v229, v233, vcc
	v_cndmask_b32_e32 v114, v225, v231, vcc
	v_pk_fma_f32 v[110:111], v[110:111], v[126:127], v[112:113]
	v_pk_mul_f32 v[108:109], v[182:183], v[182:183]
	v_pk_fma_f32 v[110:111], v[122:123], v[114:115], v[110:111]
	v_fmamk_f32 v108, v108, 0x3dd2d3e8, v192
	v_pk_add_f32 v[110:111], v[124:125], v[110:111]
	v_fmamk_f32 v109, v109, 0x3dd2d3e8, v192
	v_pk_mul_f32 v[112:113], v[110:111], v[110:111]
	v_mul_f32_e32 v108, v182, v108
	v_mul_f32_e32 v109, v183, v109
	v_fmamk_f32 v112, v112, 0x3dd2d3e8, v192
	v_fmamk_f32 v113, v113, 0x3dd2d3e8, v192
	v_exp_f32_e32 v108, v108
	v_exp_f32_e32 v109, v109
	v_mul_f32_e32 v112, v110, v112
	v_mul_f32_e32 v113, v111, v113
	v_exp_f32_e32 v112, v112
	v_exp_f32_e32 v113, v113
	v_add_f32_e32 v108, 1.0, v108
	v_add_f32_e32 v109, 1.0, v109
	v_rcp_f32_e32 v108, v108
	v_rcp_f32_e32 v109, v109
	v_add_f32_e32 v112, 1.0, v112
	v_add_f32_e32 v113, 1.0, v113
	v_cndmask_b32_e64 v115, v230, v228, s[4:5]
	v_cndmask_b32_e64 v114, v226, v224, s[4:5]
	v_rcp_f32_e32 v112, v112
	v_rcp_f32_e32 v113, v113
	v_pk_mul_f32 v[114:115], v[120:121], v[114:115]
	v_cndmask_b32_e32 v117, v227, v229, vcc
	v_cndmask_b32_e32 v116, v223, v225, vcc
	v_pk_fma_f32 v[106:107], v[106:107], v[126:127], v[114:115]
	v_pk_fma_f32 v[108:109], v[182:183], v[108:109], v[182:183] neg_lo:[1,0,0] neg_hi:[1,0,0]
	v_pk_fma_f32 v[106:107], v[122:123], v[116:117], v[106:107]
	v_pk_mul_f32 v[102:103], v[102:103], v[108:109]
	v_pk_add_f32 v[106:107], v[124:125], v[106:107]
	v_pk_fma_f32 v[108:109], v[110:111], v[112:113], v[110:111] neg_lo:[1,0,0] neg_hi:[1,0,0]
	v_pk_mul_f32 v[114:115], v[106:107], v[106:107]
	v_pk_mul_f32 v[98:99], v[98:99], v[108:109]
	v_fmamk_f32 v114, v114, 0x3dd2d3e8, v192
	v_fmamk_f32 v109, v115, 0x3dd2d3e8, v192
	v_mul_f32_e32 v114, v106, v114
	v_mul_f32_e32 v109, v107, v109
	v_exp_f32_e32 v114, v114
	v_exp_f32_e32 v109, v109
	v_pk_mul_f32 v[88:89], v[88:89], v[104:105]
	v_pk_mul_f32 v[104:105], v[176:177], v[176:177]
	v_pk_mul_f32 v[110:111], v[168:169], v[168:169]
	v_fmamk_f32 v104, v104, 0x3dd2d3e8, v192
	v_add_f32_e32 v108, 1.0, v114
	v_fmamk_f32 v105, v105, 0x3dd2d3e8, v192
	v_add_f32_e32 v109, 1.0, v109
	v_fmamk_f32 v110, v110, 0x3dd2d3e8, v192
	v_mul_f32_e32 v104, v176, v104
	v_mul_f32_e32 v105, v177, v105
	v_rcp_f32_e32 v108, v108
	v_rcp_f32_e32 v109, v109
	v_mul_f32_e32 v110, v168, v110
	v_exp_f32_e32 v104, v104
	v_exp_f32_e32 v105, v105
	v_exp_f32_e32 v110, v110
	v_pk_fma_f32 v[106:107], v[106:107], v[108:109], v[106:107] neg_lo:[1,0,0] neg_hi:[1,0,0]
	v_pk_mul_f32 v[108:109], v[166:167], v[166:167]
	v_add_f32_e32 v104, 1.0, v104
	v_add_f32_e32 v105, 1.0, v105
	v_pk_mul_f32 v[94:95], v[94:95], v[106:107]
	v_add_f32_e32 v106, 1.0, v110
; __device__ __forceinline__ unsigned pk2(float lo, float hi) { return cvtpk(lo, hi); }
;     __device__ __forceinline__ void operator()(f32x4 (&acc)[2][2][4][2], const pg8::Unit& u, int wr, int wc, int, int) const {
;     ...
;                     for (int m = 0; m < 4; ++m) {
;                         const float g = acc[ai][0][m][n][j], uv = acc[ai][1][m][n][j];
;                         const float pv = (fr == 0) ? (m > 0 ? gp[m > 0 ? m - 1 : 0] : 0.f) : gp[m];
;                         const float nv = (fr == 15) ? (m < 3 ? gn[m < 3 ? m + 1 : 3] : 0.f) : gn[m];
;                         const float pre = w0 * pv + w1 * g + w2 * nv + bb;
;                         if (m == 0) pre0 = pre;
;                         if (m == 3) pre3 = pre;
;                         acc[ai][1][m][n][j] = gelu_tanh(pre) * uv;
;                     }
;                     eP[j] = efirst ? pre0 : pre3;
;                     __builtin_amdgcn_sched_barrier(0);
;                 }
; #pragma unroll
;                 for (int j = 0; j < 4; ++j) eG[j] = efirst ? acc[ai][0][0][n][j] : acc[ai][0][3][n][j];
;                 if (efirst || elast) { *(f32x4*)(sbp + eo) = eP; *(f32x4*)(sbg + eo) = eG; }
;             }
; #pragma unroll
;             for (int m = 0; m < 4; ++m) { bf16_t* rowp = act + (size_t)(rband + m * 16 + fr) * DFF + f0;
;                 const f32x4 v0 = acc[ai][1][m][0], v1 = acc[ai][1][m][1];
;                 u32x4 w; w.x = pk2(v0[0], v0[1]); w.y = pk2(v0[2], v0[3]); w.z = pk2(v1[0], v1[1]); w.w = pk2(v1[2], v1[3]);
;                 *(u32x4*)rowp = w; }
	v_fmamk_f32 v107, v111, 0x3dd2d3e8, v192
	v_fmamk_f32 v108, v108, 0x3dd2d3e8, v192
	v_cndmask_b32_e64 v111, v222, v218, s[4:5]
	v_cndmask_b32_e64 v110, v220, v214, s[4:5]
	v_rcp_f32_e32 v104, v104
	v_rcp_f32_e32 v105, v105
	v_mul_f32_e32 v107, v169, v107
	v_mul_f32_e32 v108, v166, v108
	v_pk_mul_f32 v[110:111], v[154:155], v[110:111]
	v_exp_f32_e32 v107, v107
	v_exp_f32_e32 v108, v108
	v_cndmask_b32_e32 v113, v217, v221, vcc
	v_cndmask_b32_e32 v112, v213, v219, vcc
	v_pk_fma_f32 v[84:85], v[84:85], v[162:163], v[110:111]
	v_pk_fma_f32 v[104:105], v[176:177], v[104:105], v[176:177] neg_lo:[1,0,0] neg_hi:[1,0,0]
	v_pk_fma_f32 v[84:85], v[156:157], v[112:113], v[84:85]
	v_add_f32_e32 v107, 1.0, v107
	v_pk_add_f32 v[84:85], v[160:161], v[84:85]
	v_pk_mul_f32 v[90:91], v[90:91], v[104:105]
	v_pk_mul_f32 v[110:111], v[84:85], v[84:85]
	v_add_f32_e32 v104, 1.0, v108
	v_fmamk_f32 v105, v110, 0x3dd2d3e8, v192
	v_fmamk_f32 v108, v111, 0x3dd2d3e8, v192
	v_cndmask_b32_e64 v111, v218, v216, s[4:5]
	v_cndmask_b32_e64 v110, v214, v212, s[4:5]
	v_rcp_f32_e32 v106, v106
	v_rcp_f32_e32 v107, v107
	v_pk_mul_f32 v[110:111], v[154:155], v[110:111]
	v_mul_f32_e32 v105, v84, v105
	v_cndmask_b32_e32 v113, v215, v217, vcc
	v_cndmask_b32_e32 v112, v211, v213, vcc
	v_pk_fma_f32 v[80:81], v[80:81], v[162:163], v[110:111]
	v_exp_f32_e32 v105, v105
	v_mul_f32_e32 v108, v85, v108
	v_pk_fma_f32 v[80:81], v[156:157], v[112:113], v[80:81]
	v_exp_f32_e32 v108, v108
	v_pk_add_f32 v[80:81], v[160:161], v[80:81]
	v_pk_fma_f32 v[106:107], v[168:169], v[106:107], v[168:169] neg_lo:[1,0,0] neg_hi:[1,0,0]
	v_pk_mul_f32 v[110:111], v[80:81], v[80:81]
	v_pk_mul_f32 v[76:77], v[76:77], v[106:107]
	v_fmamk_f32 v107, v110, 0x3dd2d3e8, v192
	v_add_f32_e32 v105, 1.0, v105
	v_mul_f32_e32 v107, v80, v107
	v_rcp_f32_e32 v106, v105
	v_add_f32_e32 v105, 1.0, v108
	v_exp_f32_e32 v108, v107
	v_fmamk_f32 v107, v111, 0x3dd2d3e8, v192
	v_mul_f32_e32 v107, v81, v107
	v_exp_f32_e32 v111, v107
	v_rcp_f32_e32 v107, v105
	v_add_f32_e32 v105, 1.0, v108
	v_rcp_f32_e32 v110, v105
	v_add_f32_e32 v105, 1.0, v111
	v_rcp_f32_e32 v111, v105
	v_fmamk_f32 v105, v109, 0x3dd2d3e8, v192
	v_mul_f32_e32 v105, v167, v105
	v_exp_f32_e32 v105, v105
	v_pk_fma_f32 v[84:85], v[84:85], v[106:107], v[84:85] neg_lo:[1,0,0] neg_hi:[1,0,0]
	v_rcp_f32_e32 v104, v104
	v_pk_mul_f32 v[84:85], v[68:69], v[84:85]
	v_pk_fma_f32 v[68:69], v[80:81], v[110:111], v[80:81] neg_lo:[1,0,0] neg_hi:[1,0,0]
	v_add_f32_e32 v80, 1.0, v105
	v_rcp_f32_e32 v105, v80
	v_pk_mul_f32 v[80:81], v[164:165], v[164:165]
	v_pk_mul_f32 v[72:73], v[72:73], v[68:69]
	v_fmamk_f32 v80, v80, 0x3dd2d3e8, v192
	v_mul_f32_e32 v80, v164, v80
	v_exp_f32_e32 v80, v80
	v_pk_fma_f32 v[68:69], v[166:167], v[104:105], v[166:167] neg_lo:[1,0,0] neg_hi:[1,0,0]
	v_cndmask_b32_e32 v107, v205, v209, vcc
	v_pk_mul_f32 v[104:105], v[64:65], v[68:69]
	v_add_f32_e32 v68, 1.0, v80
	v_fmamk_f32 v69, v81, 0x3dd2d3e8, v192
	v_cndmask_b32_e64 v81, v210, v206, s[4:5]
	v_cndmask_b32_e64 v80, v208, v202, s[4:5]
	v_pk_mul_f32 v[80:81], v[146:147], v[80:81]
	v_cndmask_b32_e32 v106, v201, v207, vcc
	v_pk_fma_f32 v[80:81], v[86:87], v[152:153], v[80:81]
	v_mul_f32_e32 v69, v165, v69
	v_pk_fma_f32 v[80:81], v[148:149], v[106:107], v[80:81]
	v_exp_f32_e32 v69, v69
	v_pk_add_f32 v[80:81], v[150:151], v[80:81]
	v_cndmask_b32_e64 v107, v206, v204, s[4:5]
	v_pk_mul_f32 v[86:87], v[80:81], v[80:81]
	v_add_f32_e32 v69, 1.0, v69
	v_fmamk_f32 v86, v86, 0x3dd2d3e8, v192
	v_fmamk_f32 v87, v87, 0x3dd2d3e8, v192
	v_mul_f32_e32 v86, v80, v86
	v_mul_f32_e32 v87, v81, v87
	v_exp_f32_e32 v86, v86
	v_exp_f32_e32 v87, v87
	v_cndmask_b32_e64 v106, v202, v200, s[4:5]
	v_rcp_f32_e32 v68, v68
	v_rcp_f32_e32 v69, v69
	v_add_f32_e32 v86, 1.0, v86
	v_add_f32_e32 v87, 1.0, v87
	v_pk_mul_f32 v[106:107], v[146:147], v[106:107]
	v_rcp_f32_e32 v86, v86
	v_rcp_f32_e32 v87, v87
	v_cndmask_b32_e32 v109, v203, v205, vcc
	v_cndmask_b32_e32 v108, v199, v201, vcc
	v_pk_fma_f32 v[82:83], v[82:83], v[152:153], v[106:107]
	v_pk_mul_f32 v[64:65], v[158:159], v[158:159]
	v_pk_fma_f32 v[82:83], v[148:149], v[108:109], v[82:83]
	v_pk_fma_f32 v[68:69], v[164:165], v[68:69], v[164:165] neg_lo:[1,0,0] neg_hi:[1,0,0]
	v_pk_add_f32 v[82:83], v[150:151], v[82:83]
	v_fmamk_f32 v64, v64, 0x3dd2d3e8, v192
	v_pk_mul_f32 v[106:107], v[82:83], v[82:83]
	v_pk_mul_f32 v[68:69], v[78:79], v[68:69]
	v_fmamk_f32 v106, v106, 0x3dd2d3e8, v192
	v_pk_fma_f32 v[78:79], v[80:81], v[86:87], v[80:81] neg_lo:[1,0,0] neg_hi:[1,0,0]
	v_fmamk_f32 v81, v107, 0x3dd2d3e8, v192
	v_fmamk_f32 v65, v65, 0x3dd2d3e8, v192
	v_mul_f32_e32 v64, v158, v64
	v_mul_f32_e32 v106, v82, v106
	v_mul_f32_e32 v81, v83, v81
	v_mul_f32_e32 v65, v159, v65
	v_exp_f32_e32 v64, v64
	v_exp_f32_e32 v106, v106
	v_exp_f32_e32 v81, v81
	v_exp_f32_e32 v65, v65
	v_add_f32_e32 v64, 1.0, v64
	v_add_f32_e32 v80, 1.0, v106
	v_add_f32_e32 v81, 1.0, v81
	v_add_f32_e32 v65, 1.0, v65
	v_rcp_f32_e32 v64, v64
	v_rcp_f32_e32 v80, v80
	v_rcp_f32_e32 v81, v81
	v_rcp_f32_e32 v65, v65
	v_pk_mul_f32 v[70:71], v[70:71], v[78:79]
	v_or_b32_e32 v86, s3, v193
	v_pk_fma_f32 v[78:79], v[82:83], v[80:81], v[82:83] neg_lo:[1,0,0] neg_hi:[1,0,0]
	v_pk_fma_f32 v[64:65], v[158:159], v[64:65], v[158:159] neg_lo:[1,0,0] neg_hi:[1,0,0]
	v_mov_b64_e32 v[80:81], s[96:97]
	v_pk_mul_f32 v[74:75], v[74:75], v[78:79]
	v_pk_mul_f32 v[78:79], v[66:67], v[64:65]
	v_mad_i64_i32 v[66:67], s[6:7], v86, s53, v[80:81]
	v_lshlrev_b64 v[64:65], 1, v[144:145]
	v_lshl_add_u64 v[82:83], v[66:67], 0, v[64:65]
	v_cvt_pk_bf16_f32 v66, v76, v77
	v_cvt_pk_bf16_f32 v67, v68, v69
	v_cvt_pk_bf16_f32 v68, v100, v101
	v_cvt_pk_bf16_f32 v69, v102, v103
	global_store_dwordx4 v[82:83], v[66:69], off sc1
	s_mov_b64 s[26:27], -1
	s_nop 0
	v_or_b32_e32 v66, 16, v86
	v_mad_i64_i32 v[66:67], s[6:7], v66, s53, v[80:81]
	v_lshl_add_u64 v[76:77], v[66:67], 0, v[64:65]
	v_cvt_pk_bf16_f32 v66, v72, v73
	v_cvt_pk_bf16_f32 v67, v74, v75
	v_cvt_pk_bf16_f32 v68, v92, v93
	v_cvt_pk_bf16_f32 v69, v94, v95
	global_store_dwordx4 v[76:77], v[66:69], off sc1
	s_nop 1
	v_or_b32_e32 v66, 32, v86
	v_mad_i64_i32 v[66:67], s[6:7], v66, s53, v[80:81]
	v_lshl_add_u64 v[72:73], v[66:67], 0, v[64:65]
	v_cvt_pk_bf16_f32 v66, v84, v85
	v_cvt_pk_bf16_f32 v67, v70, v71
	v_cvt_pk_bf16_f32 v68, v96, v97
	v_cvt_pk_bf16_f32 v69, v98, v99
	global_store_dwordx4 v[72:73], v[66:69], off sc1
	s_nop 1
	v_or_b32_e32 v66, 48, v86
	v_mad_i64_i32 v[66:67], s[6:7], v66, s53, v[80:81]
	v_lshl_add_u64 v[70:71], v[66:67], 0, v[64:65]
	v_cvt_pk_bf16_f32 v66, v104, v105
	v_cvt_pk_bf16_f32 v67, v78, v79
	v_cvt_pk_bf16_f32 v68, v88, v89
	v_cvt_pk_bf16_f32 v69, v90, v91
	v_cmp_gt_i32_e64 s[6:7], 15, v193
	global_store_dwordx4 v[70:71], v[66:69], off sc1
	s_and_saveexec_b64 s[28:29], s[6:7]
	v_cmp_eq_u32_e64 s[6:7], 0, v193
	s_orn2_b64 s[26:27], s[6:7], exec
	s_or_b64 exec, exec, s[28:29]
	s_addk_i32 s3, 0x80
	s_ashr_i32 s6, s3, 5
	v_or_b32_e32 v66, s6, v197
	v_mad_i64_i32 v[90:91], s[6:7], v66, s52, v[144:145]
	s_and_saveexec_b64 s[6:7], s[26:27]
	s_cbranch_execz .LBB0_831
;     __device__ __forceinline__ void operator()(f32x4 (&acc)[2][2][4][2], const pg8::Unit& u, int wr, int wc, int, int) const {
;     ...
;             for (int n = 0; n < 2; ++n) {
;                 const bool efirst = (fr == 0), elast = (fr == 15);
;                 f32x4 eP, eG;
;                 const size_t eo = (size_t)((rband >> 6) * 2 + (elast ? 1 : 0)) * DFF + f0 + 4 * n;
;                 if (efirst || elast) { f32x4 eU;
; #pragma unroll
;                     for (int j = 0; j < 4; ++j) eU[j] = efirst ? acc[ai][1][0][n][j] : acc[ai][1][3][n][j];
;                     *(f32x4*)(sbu + eo) = eU; }
; #pragma unroll
;                 for (int j = 0; j < 4; ++j) {
;                     const int lc = 8 * fq + 4 * n + j; const float w0 = lwv[lc], w1 = lwv[32 + lc], w2 = lwv[64 + lc], bb = lwv[96 + lc];
;                     float gp[4], gn[4];
; #pragma unroll
;                     for (int m = 0; m < 4; ++m) { const int gi_ = __float_as_int(acc[ai][0][m][n][j]); gp[m] = __int_as_float(__builtin_amdgcn_ds_bpermute(lprev4, gi_)); gn[m] = __int_as_float(__builtin_amdgcn_ds_bpermute(lnext4, gi_)); }
;                     float pre0 = 0.f, pre3 = 0.f;
; #pragma unroll
;                     for (int m = 0; m < 4; ++m) {
;                         const float g = acc[ai][0][m][n][j], uv = acc[ai][1][m][n][j];
;                         const float pv = (fr == 0) ? (m > 0 ? gp[m > 0 ? m - 1 : 0] : 0.f) : gp[m];
;                         const float nv = (fr == 15) ? (m < 3 ? gn[m < 3 ? m + 1 : 3] : 0.f) : gn[m];
;                         const float pre = w0 * pv + w1 * g + w2 * nv + bb;
;                         if (m == 0) pre0 = pre;
;                         if (m == 3) pre3 = pre;
;                         acc[ai][1][m][n][j] = gelu_tanh(pre) * uv;
;                     }
;                     eP[j] = efirst ? pre0 : pre3;
;                     __builtin_amdgcn_sched_barrier(0);
;                 }
; #pragma unroll
;                 for (int j = 0; j < 4; ++j) eG[j] = efirst ? acc[ai][0][0][n][j] : acc[ai][0][3][n][j];
;                 if (efirst || elast) { *(f32x4*)(sbp + eo) = eP; *(f32x4*)(sbg + eo) = eG; }
	v_cndmask_b32_e64 v69, v3, v15, s[4:5]
	v_cndmask_b32_e64 v68, v2, v14, s[4:5]
	v_cndmask_b32_e64 v67, v1, v13, s[4:5]
	v_cndmask_b32_e64 v66, v0, v12, s[4:5]
	v_lshl_add_u64 v[70:71], v[90:91], 2, s[12:13]
	global_store_dwordx4 v[70:71], v[66:69], off sc1
.LBB0_831:
	s_or_b64 exec, exec, s[6:7]
	ds_read2_b32 v[74:75], v196 offset1:32
	ds_read2_b32 v[76:77], v196 offset0:64 offset1:96
	v_mov_b32_dpp v121, v60 row_ror:1 row_mask:0xf bank_mask:0xf
	v_mov_b32_dpp v84, v60 row_ror:15 row_mask:0xf bank_mask:0xf
	v_mov_b32_dpp v123, v16 row_ror:1 row_mask:0xf bank_mask:0xf
	v_mov_b32_dpp v120, v16 row_ror:15 row_mask:0xf bank_mask:0xf
	v_mov_b32_dpp v145, v20 row_ror:1 row_mask:0xf bank_mask:0xf
	v_mov_b32_dpp v122, v20 row_ror:15 row_mask:0xf bank_mask:0xf
	v_mov_b32_dpp v78, v56 row_ror:1 row_mask:0xf bank_mask:0xf
	v_mov_b32_dpp v144, v56 row_ror:15 row_mask:0xf bank_mask:0xf
	s_waitcnt lgkmcnt(0)
	v_mov_b32_e32 v82, v75
	s_waitcnt lgkmcnt(0)
	v_mov_b32_e32 v80, v77
	ds_read2_b32 v[66:67], v196 offset0:1 offset1:33
	ds_read2_b32 v[68:69], v196 offset0:65 offset1:97
	v_mov_b32_dpp v125, v61 row_ror:1 row_mask:0xf bank_mask:0xf
	v_mov_b32_dpp v87, v61 row_ror:15 row_mask:0xf bank_mask:0xf
	v_mov_b32_dpp v127, v17 row_ror:1 row_mask:0xf bank_mask:0xf
	v_mov_b32_dpp v124, v17 row_ror:15 row_mask:0xf bank_mask:0xf
	v_mov_b32_dpp v147, v21 row_ror:1 row_mask:0xf bank_mask:0xf
	v_mov_b32_dpp v126, v21 row_ror:15 row_mask:0xf bank_mask:0xf
	v_mov_b32_dpp v86, v57 row_ror:1 row_mask:0xf bank_mask:0xf
	v_mov_b32_dpp v146, v57 row_ror:15 row_mask:0xf bank_mask:0xf
	s_waitcnt lgkmcnt(0)
	v_mov_b32_e32 v75, v66
	v_mov_b32_e32 v83, v67
	s_waitcnt lgkmcnt(0)
	v_mov_b32_e32 v77, v68
	v_mov_b32_e32 v81, v69
	ds_read2_b32 v[66:67], v196 offset0:2 offset1:34
	ds_read2_b32 v[68:69], v196 offset0:66 offset1:98
	v_mov_b32_dpp v109, v62 row_ror:1 row_mask:0xf bank_mask:0xf
	v_mov_b32_dpp v85, v62 row_ror:15 row_mask:0xf bank_mask:0xf
	v_mov_b32_dpp v111, v18 row_ror:1 row_mask:0xf bank_mask:0xf
	v_mov_b32_dpp v108, v18 row_ror:15 row_mask:0xf bank_mask:0xf
	v_mov_b32_dpp v117, v22 row_ror:1 row_mask:0xf bank_mask:0xf
	v_mov_b32_dpp v110, v22 row_ror:15 row_mask:0xf bank_mask:0xf
	v_mov_b32_dpp v79, v58 row_ror:1 row_mask:0xf bank_mask:0xf
	v_mov_b32_dpp v116, v58 row_ror:15 row_mask:0xf bank_mask:0xf
	ds_read2_b32 v[88:89], v196 offset0:3 offset1:35
	ds_read2_b32 v[94:95], v196 offset0:67 offset1:99
	v_mov_b32_dpp v113, v63 row_ror:1 row_mask:0xf bank_mask:0xf
	v_mov_b32_dpp v93, v63 row_ror:15 row_mask:0xf bank_mask:0xf
	v_mov_b32_dpp v115, v19 row_ror:1 row_mask:0xf bank_mask:0xf
	v_mov_b32_dpp v112, v19 row_ror:15 row_mask:0xf bank_mask:0xf
	v_mov_b32_dpp v119, v23 row_ror:1 row_mask:0xf bank_mask:0xf
	v_mov_b32_dpp v114, v23 row_ror:15 row_mask:0xf bank_mask:0xf
	v_mov_b32_dpp v92, v59 row_ror:1 row_mask:0xf bank_mask:0xf
	v_mov_b32_dpp v118, v59 row_ror:15 row_mask:0xf bank_mask:0xf
	s_waitcnt lgkmcnt(0)
	v_mov_b32_e32 v72, v67
	v_mov_b32_e32 v70, v69
	s_waitcnt lgkmcnt(0)
	v_mov_b32_e32 v67, v88
	v_mov_b32_e32 v73, v89
	s_waitcnt lgkmcnt(0)
	v_mov_b32_e32 v69, v94
	v_mov_b32_e32 v71, v95
	v_cmp_gt_i32_e64 s[6:7], 15, v193
	s_mov_b64 s[26:27], -1
	s_and_saveexec_b64 s[28:29], s[6:7]
	v_cmp_eq_u32_e64 s[6:7], 0, v193
	s_orn2_b64 s[26:27], s[6:7], exec
	s_or_b64 exec, exec, s[28:29]
	v_cndmask_b32_e64 v88, v121, 0, s[4:5]
	v_cndmask_b32_e64 v89, v125, 0, s[4:5]
	v_pk_mul_f32 v[88:89], v[74:75], v[88:89]
	v_cndmask_b32_e32 v94, v84, v120, vcc
	v_cndmask_b32_e32 v95, v87, v124, vcc
	v_pk_fma_f32 v[88:89], v[60:61], v[82:83], v[88:89]
	v_cndmask_b32_e64 v87, v146, 0, vcc
	v_pk_fma_f32 v[88:89], v[76:77], v[94:95], v[88:89]
	v_cndmask_b32_e64 v94, v78, v145, s[4:5]
	v_cndmask_b32_e64 v95, v86, v147, s[4:5]
	v_pk_mul_f32 v[94:95], v[74:75], v[94:95]
	v_cndmask_b32_e64 v86, v144, 0, vcc
	v_pk_fma_f32 v[94:95], v[56:57], v[82:83], v[94:95]
	v_cndmask_b32_e64 v78, v79, v117, s[4:5]
	v_pk_fma_f32 v[86:87], v[76:77], v[86:87], v[94:95]
	v_cndmask_b32_e64 v94, v109, 0, s[4:5]
	s_waitcnt lgkmcnt(0)
	v_cndmask_b32_e64 v95, v113, 0, s[4:5]
	s_waitcnt lgkmcnt(0)
	v_cndmask_b32_e64 v79, v92, v119, s[4:5]
	v_pk_mul_f32 v[94:95], v[66:67], v[94:95]
	v_pk_mul_f32 v[78:79], v[66:67], v[78:79]
	v_cndmask_b32_e32 v84, v85, v108, vcc
	v_cndmask_b32_e32 v85, v93, v112, vcc
	v_pk_fma_f32 v[94:95], v[62:63], v[72:73], v[94:95]
	v_cndmask_b32_e64 v92, v116, 0, vcc
	s_waitcnt lgkmcnt(0)
	v_cndmask_b32_e64 v93, v118, 0, vcc
	v_pk_fma_f32 v[78:79], v[58:59], v[72:73], v[78:79]
	v_pk_fma_f32 v[84:85], v[68:69], v[84:85], v[94:95]
	v_pk_fma_f32 v[78:79], v[68:69], v[92:93], v[78:79]
	v_pk_add_f32 v[88:89], v[80:81], v[88:89]
	v_pk_add_f32 v[86:87], v[80:81], v[86:87]
	v_pk_add_f32 v[84:85], v[70:71], v[84:85]
	v_pk_add_f32 v[78:79], v[70:71], v[78:79]
	s_and_saveexec_b64 s[6:7], s[26:27]
	s_cbranch_execz .LBB0_835
	v_lshlrev_b64 v[92:93], 2, v[90:91]
	v_cndmask_b32_e64 v59, v59, v63, s[4:5]
	v_cndmask_b32_e64 v58, v58, v62, s[4:5]
	v_cndmask_b32_e64 v57, v57, v61, s[4:5]
	v_cndmask_b32_e64 v56, v56, v60, s[4:5]
	v_cndmask_b32_e64 v63, v79, v85, s[4:5]
	v_cndmask_b32_e64 v62, v78, v84, s[4:5]
	v_cndmask_b32_e64 v61, v87, v89, s[4:5]
	v_cndmask_b32_e64 v60, v86, v88, s[4:5]
	v_lshl_add_u64 v[94:95], s[10:11], 0, v[92:93]
	global_store_dwordx4 v[94:95], v[60:63], off sc1
	s_nop 1
	v_lshl_add_u64 v[60:61], s[14:15], 0, v[92:93]
	global_store_dwordx4 v[60:61], v[56:59], off sc1
;     __device__ __forceinline__ void operator()(f32x4 (&acc)[2][2][4][2], const pg8::Unit& u, int wr, int wc, int, int) const {
;     ...
;             for (int n = 0; n < 2; ++n) {
;                 const bool efirst = (fr == 0), elast = (fr == 15);
;                 f32x4 eP, eG;
;                 const size_t eo = (size_t)((rband >> 6) * 2 + (elast ? 1 : 0)) * DFF + f0 + 4 * n;
;                 if (efirst || elast) { f32x4 eU;
; #pragma unroll
;                     for (int j = 0; j < 4; ++j) eU[j] = efirst ? acc[ai][1][0][n][j] : acc[ai][1][3][n][j];
;                     *(f32x4*)(sbu + eo) = eU; }
; #pragma unroll
;                 for (int j = 0; j < 4; ++j) {
;                     const int lc = 8 * fq + 4 * n + j; const float w0 = lwv[lc], w1 = lwv[32 + lc], w2 = lwv[64 + lc], bb = lwv[96 + lc];
;                     float gp[4], gn[4];
; #pragma unroll
;                     for (int m = 0; m < 4; ++m) { const int gi_ = __float_as_int(acc[ai][0][m][n][j]); gp[m] = __int_as_float(__builtin_amdgcn_ds_bpermute(lprev4, gi_)); gn[m] = __int_as_float(__builtin_amdgcn_ds_bpermute(lnext4, gi_)); }
;                     float pre0 = 0.f, pre3 = 0.f;
; #pragma unroll
;                     for (int m = 0; m < 4; ++m) {
;                         const float g = acc[ai][0][m][n][j], uv = acc[ai][1][m][n][j];
;                         const float pv = (fr == 0) ? (m > 0 ? gp[m > 0 ? m - 1 : 0] : 0.f) : gp[m];
;                         const float nv = (fr == 15) ? (m < 3 ? gn[m < 3 ? m + 1 : 3] : 0.f) : gn[m];
;                         const float pre = w0 * pv + w1 * g + w2 * nv + bb;
;                         if (m == 0) pre0 = pre;
;                         if (m == 3) pre3 = pre;
;                         acc[ai][1][m][n][j] = gelu_tanh(pre) * uv;
;                     }
;                     eP[j] = efirst ? pre0 : pre3;
;                     __builtin_amdgcn_sched_barrier(0);
;                 }
; #pragma unroll
;                 for (int j = 0; j < 4; ++j) eG[j] = efirst ? acc[ai][0][0][n][j] : acc[ai][0][3][n][j];
;                 if (efirst || elast) { *(f32x4*)(sbp + eo) = eP; *(f32x4*)(sbg + eo) = eG; }
.LBB0_835:
	s_or_b64 exec, exec, s[6:7]
	v_cmp_gt_i32_e64 s[6:7], 15, v193
	s_mov_b64 s[26:27], -1
	s_and_saveexec_b64 s[28:29], s[6:7]
	v_cmp_eq_u32_e64 s[6:7], 0, v193
	s_orn2_b64 s[26:27], s[6:7], exec
	s_or_b64 exec, exec, s[28:29]
	v_or_b32_e32 v90, 4, v90
	s_and_saveexec_b64 s[6:7], s[26:27]
	s_cbranch_execz .LBB0_839
	v_cndmask_b32_e64 v59, v27, v39, s[4:5]
	v_cndmask_b32_e64 v58, v26, v38, s[4:5]
	v_cndmask_b32_e64 v57, v25, v37, s[4:5]
	v_cndmask_b32_e64 v56, v24, v36, s[4:5]
	v_lshl_add_u64 v[60:61], v[90:91], 2, s[12:13]
	global_store_dwordx4 v[60:61], v[56:59], off sc1
.LBB0_839:
	s_or_b64 exec, exec, s[6:7]
	ds_read2_b32 v[92:93], v196 offset0:4 offset1:36
	ds_read2_b32 v[94:95], v196 offset0:68 offset1:100
	v_mov_b32_dpp v161, v52 row_ror:1 row_mask:0xf bank_mask:0xf
	v_mov_b32_dpp v102, v52 row_ror:15 row_mask:0xf bank_mask:0xf
	v_mov_b32_dpp v163, v40 row_ror:1 row_mask:0xf bank_mask:0xf
	v_mov_b32_dpp v160, v40 row_ror:15 row_mask:0xf bank_mask:0xf
	v_mov_b32_dpp v169, v44 row_ror:1 row_mask:0xf bank_mask:0xf
	v_mov_b32_dpp v162, v44 row_ror:15 row_mask:0xf bank_mask:0xf
	v_mov_b32_dpp v96, v48 row_ror:1 row_mask:0xf bank_mask:0xf
	v_mov_b32_dpp v168, v48 row_ror:15 row_mask:0xf bank_mask:0xf
	s_waitcnt lgkmcnt(0)
	v_mov_b32_e32 v100, v93
	s_waitcnt lgkmcnt(0)
	v_mov_b32_e32 v98, v95
	ds_read2_b32 v[56:57], v196 offset0:5 offset1:37
	ds_read2_b32 v[58:59], v196 offset0:69 offset1:101
	v_mov_b32_dpp v165, v53 row_ror:1 row_mask:0xf bank_mask:0xf
	v_mov_b32_dpp v105, v53 row_ror:15 row_mask:0xf bank_mask:0xf
	v_mov_b32_dpp v167, v41 row_ror:1 row_mask:0xf bank_mask:0xf
	v_mov_b32_dpp v164, v41 row_ror:15 row_mask:0xf bank_mask:0xf
	v_mov_b32_dpp v171, v45 row_ror:1 row_mask:0xf bank_mask:0xf
	v_mov_b32_dpp v166, v45 row_ror:15 row_mask:0xf bank_mask:0xf
	v_mov_b32_dpp v104, v49 row_ror:1 row_mask:0xf bank_mask:0xf
	v_mov_b32_dpp v170, v49 row_ror:15 row_mask:0xf bank_mask:0xf
	s_waitcnt lgkmcnt(0)
	v_mov_b32_e32 v93, v56
	v_mov_b32_e32 v101, v57
	s_waitcnt lgkmcnt(0)
	v_mov_b32_e32 v95, v58
	v_mov_b32_e32 v99, v59
	ds_read2_b32 v[56:57], v196 offset0:6 offset1:38
	ds_read2_b32 v[58:59], v196 offset0:70 offset1:102
	v_mov_b32_dpp v149, v54 row_ror:1 row_mask:0xf bank_mask:0xf
	v_mov_b32_dpp v103, v54 row_ror:15 row_mask:0xf bank_mask:0xf
	v_mov_b32_dpp v151, v42 row_ror:1 row_mask:0xf bank_mask:0xf
	v_mov_b32_dpp v148, v42 row_ror:15 row_mask:0xf bank_mask:0xf
	v_mov_b32_dpp v157, v46 row_ror:1 row_mask:0xf bank_mask:0xf
	v_mov_b32_dpp v150, v46 row_ror:15 row_mask:0xf bank_mask:0xf
	v_mov_b32_dpp v97, v50 row_ror:1 row_mask:0xf bank_mask:0xf
	v_mov_b32_dpp v156, v50 row_ror:15 row_mask:0xf bank_mask:0xf
	ds_read2_b32 v[106:107], v198 offset1:32
	ds_read2_b32 v[174:175], v198 offset0:64 offset1:96
	v_mov_b32_dpp v153, v55 row_ror:1 row_mask:0xf bank_mask:0xf
	v_mov_b32_dpp v173, v55 row_ror:15 row_mask:0xf bank_mask:0xf
	v_mov_b32_dpp v155, v43 row_ror:1 row_mask:0xf bank_mask:0xf
	v_mov_b32_dpp v152, v43 row_ror:15 row_mask:0xf bank_mask:0xf
	v_mov_b32_dpp v159, v47 row_ror:1 row_mask:0xf bank_mask:0xf
	v_mov_b32_dpp v154, v47 row_ror:15 row_mask:0xf bank_mask:0xf
	v_mov_b32_dpp v172, v51 row_ror:1 row_mask:0xf bank_mask:0xf
	v_mov_b32_dpp v158, v51 row_ror:15 row_mask:0xf bank_mask:0xf
	s_waitcnt lgkmcnt(0)
	v_mov_b32_e32 v62, v57
	v_mov_b32_e32 v60, v59
	s_waitcnt lgkmcnt(0)
	v_mov_b32_e32 v57, v106
	v_mov_b32_e32 v63, v107
	s_waitcnt lgkmcnt(0)
	v_mov_b32_e32 v59, v174
	v_mov_b32_e32 v61, v175
	v_cmp_gt_i32_e64 s[6:7], 15, v193
	s_mov_b64 s[26:27], -1
	s_and_saveexec_b64 s[28:29], s[6:7]
	v_cmp_eq_u32_e64 s[6:7], 0, v193
	s_orn2_b64 s[26:27], s[6:7], exec
	s_or_b64 exec, exec, s[28:29]
	v_cndmask_b32_e64 v106, v161, 0, s[4:5]
	v_cndmask_b32_e64 v107, v165, 0, s[4:5]
	v_pk_mul_f32 v[106:107], v[92:93], v[106:107]
	v_cndmask_b32_e32 v174, v102, v160, vcc
	v_cndmask_b32_e32 v175, v105, v164, vcc
	v_pk_fma_f32 v[106:107], v[52:53], v[100:101], v[106:107]
	v_cndmask_b32_e64 v105, v170, 0, vcc
	v_pk_fma_f32 v[106:107], v[94:95], v[174:175], v[106:107]
	v_cndmask_b32_e64 v174, v96, v169, s[4:5]
	v_cndmask_b32_e64 v175, v104, v171, s[4:5]
	v_pk_mul_f32 v[174:175], v[92:93], v[174:175]
	v_cndmask_b32_e64 v104, v168, 0, vcc
	v_pk_fma_f32 v[174:175], v[48:49], v[100:101], v[174:175]
	v_cndmask_b32_e64 v96, v97, v157, s[4:5]
	v_pk_fma_f32 v[104:105], v[94:95], v[104:105], v[174:175]
	v_cndmask_b32_e64 v174, v149, 0, s[4:5]
	s_waitcnt lgkmcnt(0)
	v_cndmask_b32_e64 v175, v153, 0, s[4:5]
	s_waitcnt lgkmcnt(0)
	v_cndmask_b32_e64 v97, v172, v159, s[4:5]
	v_pk_mul_f32 v[174:175], v[56:57], v[174:175]
	v_pk_mul_f32 v[96:97], v[56:57], v[96:97]
	v_cndmask_b32_e32 v102, v103, v148, vcc
	v_cndmask_b32_e32 v103, v173, v152, vcc
	v_pk_fma_f32 v[174:175], v[54:55], v[62:63], v[174:175]
	v_cndmask_b32_e64 v172, v156, 0, vcc
	s_waitcnt lgkmcnt(0)
	v_cndmask_b32_e64 v173, v158, 0, vcc
	v_pk_fma_f32 v[96:97], v[50:51], v[62:63], v[96:97]
	v_pk_fma_f32 v[102:103], v[58:59], v[102:103], v[174:175]
	v_pk_fma_f32 v[96:97], v[58:59], v[172:173], v[96:97]
	v_pk_add_f32 v[106:107], v[98:99], v[106:107]
	v_pk_add_f32 v[104:105], v[98:99], v[104:105]
	v_pk_add_f32 v[102:103], v[60:61], v[102:103]
	v_pk_add_f32 v[96:97], v[60:61], v[96:97]
	s_and_saveexec_b64 s[6:7], s[26:27]
	s_cbranch_execz .LBB0_806
	v_lshlrev_b64 v[90:91], 2, v[90:91]
	v_cndmask_b32_e64 v51, v51, v55, s[4:5]
	v_cndmask_b32_e64 v50, v50, v54, s[4:5]
	v_cndmask_b32_e64 v49, v49, v53, s[4:5]
	v_cndmask_b32_e64 v48, v48, v52, s[4:5]
	v_cndmask_b32_e64 v55, v97, v103, s[4:5]
	v_cndmask_b32_e64 v54, v96, v102, s[4:5]
	v_cndmask_b32_e64 v53, v105, v107, s[4:5]
	v_cndmask_b32_e64 v52, v104, v106, s[4:5]
	v_lshl_add_u64 v[172:173], s[10:11], 0, v[90:91]
	global_store_dwordx4 v[172:173], v[52:55], off sc1
	s_nop 1
	v_lshl_add_u64 v[52:53], s[14:15], 0, v[90:91]
	global_store_dwordx4 v[52:53], v[48:51], off sc1
	s_branch .LBB0_806

; #define PG8_STAGE(bufoff, gbase, voff) do { _Pragma("unroll") for (int _i = 0; _i < 2; ++_i) \
;         __builtin_amdgcn_global_load_lds((const unsigned*)((const char*)(gbase) + (voff)[_i]), (LAS unsigned*)(lds + (bufoff) + ldsw + _i * 8192), 16, 0, 0); } while (0)
; #define PG8_LDA(dst, b, h) do { _Pragma("unroll") for (int m = 0; m < 4; ++m) _Pragma("unroll") for (int k = 0; k < 2; ++k) dst[m][k] = *(const LAS bf16x8*)(lds + PG8_SA(b, h) + aoff + m * 2048 + k * 1024); } while (0)
; #define PG8_LDB(dst, b, h) do { _Pragma("unroll") for (int n = 0; n < 2; ++n) _Pragma("unroll") for (int k = 0; k < 2; ++k) dst[n][k] = *(const LAS bf16x8*)(lds + PG8_SB(b, h) + boff + n * 2048 + k * 1024); } while (0)
; #define PG8_MMA(ai, bj, At, Bt) do { __builtin_amdgcn_s_setprio(1); _Pragma("unroll") for (int m = 0; m < 4; ++m) _Pragma("unroll") for (int n = 0; n < 2; ++n) _Pragma("unroll") for (int k = 0; k < 2; ++k) \
;         acc[ai][bj][m][n] = __builtin_amdgcn_mfma_f32_16x16x32_bf16(Bt[n][k], At[m][k], acc[ai][bj][m][n], 0, 0, 0); __builtin_amdgcn_s_setprio(0); } while (0)
; #define PG8_WAIT_V(n) asm volatile("s_waitcnt vmcnt(" #n ")" ::: "memory")
; #define PG8_WAIT_L(n) asm volatile("s_waitcnt lgkmcnt(" #n ")" ::: "memory")
; #define PG8_BAR __builtin_amdgcn_s_barrier()
; #define PG8_SCHED __builtin_amdgcn_sched_barrier(0)
; template <class Epi>
; __device__ __forceinline__ void gemm_phase(LAS unsigned char* lds, const Gemm g, const StaticOrder& S, const Epi& E, int wave) {
;     ...
;             PG8_LDB(B0, 0, 0); PG8_SCHED; PG8_LDA(At, 0, 0); PG8_STAGE(PG8_SA(1, 1), a1 + hstep, voffA);
;             PG8_WAIT_L(8); PG8_BAR; PG8_WAIT_L(0); PG8_MMA(0, 0, At, B0); PG8_BAR; PG8_SCHED;
;             PG8_LDB(B1, 0, 1); PG8_STAGE(PG8_SB(0, 0), b2, voffB);
;             PG8_BAR; PG8_WAIT_L(0); PG8_MMA(0, 1, At, B1); PG8_BAR;
;             PG8_LDA(At, 0, 1); PG8_STAGE(PG8_SA(0, 0), a2, voffA);
;             PG8_BAR; PG8_WAIT_L(0); PG8_MMA(1, 0, At, B0); PG8_BAR; PG8_SCHED;
;             PG8_STAGE(PG8_SB(0, 1), b2 + hstep, voffB);
;             PG8_WAIT_V(6); PG8_BAR; PG8_MMA(1, 1, At, B1); PG8_BAR;
.LBB0_889:
	ds_read_b128 v[96:99], v163
	ds_read_b128 v[108:111], v163 offset:1024
	ds_read_b128 v[120:123], v163 offset:2048
	ds_read_b128 v[132:135], v163 offset:3072
	s_add_u32 s22, s20, 0x100
	s_addc_u32 s23, s21, 0
	s_cmp_eq_u32 s54, 40
	s_cselect_b32 s27, s7, s23
	s_cselect_b32 s26, s6, s22
	s_cselect_b32 s25, s5, s53
	s_cselect_b32 s24, s4, s52
	v_lshl_add_u64 v[160:161], s[20:21], 0, v[148:149]
	s_add_i32 m0, s34, 0xc000
	ds_read_b128 v[156:159], v164
	ds_read_b128 v[166:169], v164 offset:1024
	ds_read_b128 v[170:173], v164 offset:2048
	ds_read_b128 v[174:177], v164 offset:3072
	ds_read_b128 v[178:181], v164 offset:4096
	ds_read_b128 v[182:185], v164 offset:5120
	ds_read_b128 v[186:189], v164 offset:6144
	ds_read_b128 v[190:193], v164 offset:7168
	global_load_lds_dwordx4 v[160:161], off
	v_lshl_add_u64 v[160:161], s[20:21], 0, v[150:151]
	s_add_i32 m0, s34, 0xe000
	s_nop 0
	global_load_lds_dwordx4 v[160:161], off
	s_waitcnt lgkmcnt(8)
	s_barrier
	s_waitcnt lgkmcnt(0)
	s_setprio 1
	s_waitcnt lgkmcnt(0)
	v_mfma_f32_16x16x32_bf16 v[140:143], v[96:99], v[156:159], v[140:143]
	v_mfma_f32_16x16x32_bf16 v[136:139], v[120:123], v[156:159], v[136:139]
	v_mfma_f32_16x16x32_bf16 v[128:131], v[96:99], v[170:173], v[128:131]
	v_mfma_f32_16x16x32_bf16 v[124:127], v[120:123], v[170:173], v[124:127]
	v_mfma_f32_16x16x32_bf16 v[112:115], v[96:99], v[178:181], v[112:115]
	v_mfma_f32_16x16x32_bf16 v[100:103], v[120:123], v[178:181], v[100:103]
	v_mfma_f32_16x16x32_bf16 v[88:91], v[96:99], v[186:189], v[88:91]
	v_mfma_f32_16x16x32_bf16 v[80:83], v[120:123], v[186:189], v[80:83]
	v_mfma_f32_16x16x32_bf16 v[140:143], v[108:111], v[166:169], v[140:143]
	v_mfma_f32_16x16x32_bf16 v[136:139], v[132:135], v[166:169], v[136:139]
	v_mfma_f32_16x16x32_bf16 v[128:131], v[108:111], v[174:177], v[128:131]
	v_mfma_f32_16x16x32_bf16 v[124:127], v[132:135], v[174:177], v[124:127]
	v_mfma_f32_16x16x32_bf16 v[112:115], v[108:111], v[182:185], v[112:115]
	v_mfma_f32_16x16x32_bf16 v[100:103], v[132:135], v[182:185], v[100:103]
	v_mfma_f32_16x16x32_bf16 v[88:91], v[108:111], v[190:193], v[88:91]
	v_mfma_f32_16x16x32_bf16 v[80:83], v[132:135], v[190:193], v[80:83]
	s_setprio 0
	s_barrier
	s_add_i32 s20, s46, s30
	v_lshl_add_u64 v[160:161], s[24:25], 0, v[146:147]
	s_mov_b32 m0, s20
	ds_read_b128 v[194:197], v165
	ds_read_b128 v[198:201], v165 offset:1024
	ds_read_b128 v[202:205], v165 offset:2048
	ds_read_b128 v[206:209], v165 offset:3072
	global_load_lds_dwordx4 v[160:161], off
	v_lshl_add_u64 v[210:211], s[24:25], 0, v[144:145]
	s_add_i32 m0, s20, 0x2000
	s_nop 0
	global_load_lds_dwordx4 v[210:211], off
	s_barrier
	s_waitcnt lgkmcnt(0)
	s_setprio 1
	s_waitcnt lgkmcnt(0)
	v_mfma_f32_16x16x32_bf16 v[116:119], v[194:197], v[156:159], v[116:119]
	v_mfma_f32_16x16x32_bf16 v[104:107], v[202:205], v[156:159], v[104:107]
	v_mfma_f32_16x16x32_bf16 v[92:95], v[194:197], v[170:173], v[92:95]
	v_mfma_f32_16x16x32_bf16 v[84:87], v[202:205], v[170:173], v[84:87]
	v_mfma_f32_16x16x32_bf16 v[76:79], v[194:197], v[178:181], v[76:79]
	v_mfma_f32_16x16x32_bf16 v[72:75], v[202:205], v[178:181], v[72:75]
	v_mfma_f32_16x16x32_bf16 v[68:71], v[194:197], v[186:189], v[68:71]
	v_mfma_f32_16x16x32_bf16 v[64:67], v[202:205], v[186:189], v[64:67]
	v_mfma_f32_16x16x32_bf16 v[116:119], v[198:201], v[166:169], v[116:119]
	v_mfma_f32_16x16x32_bf16 v[104:107], v[206:209], v[166:169], v[104:107]
	v_mfma_f32_16x16x32_bf16 v[92:95], v[198:201], v[174:177], v[92:95]
	v_mfma_f32_16x16x32_bf16 v[84:87], v[206:209], v[174:177], v[84:87]
	v_mfma_f32_16x16x32_bf16 v[76:79], v[198:201], v[182:185], v[76:79]
	v_mfma_f32_16x16x32_bf16 v[72:75], v[206:209], v[182:185], v[72:75]
	v_mfma_f32_16x16x32_bf16 v[68:71], v[198:201], v[190:193], v[68:71]
	v_mfma_f32_16x16x32_bf16 v[64:67], v[206:209], v[190:193], v[64:67]
	s_setprio 0
	s_mov_b32 m0, s34
	v_lshl_add_u64 v[212:213], s[26:27], 0, v[146:147]
	s_barrier
	ds_read_b128 v[156:159], v164 offset:16384
	ds_read_b128 v[166:169], v164 offset:17408
	ds_read_b128 v[170:173], v164 offset:18432
	ds_read_b128 v[174:177], v164 offset:19456
	ds_read_b128 v[178:181], v164 offset:20480
	ds_read_b128 v[182:185], v164 offset:21504
	ds_read_b128 v[186:189], v164 offset:22528
	ds_read_b128 v[190:193], v164 offset:23552
	global_load_lds_dwordx4 v[212:213], off
	v_lshl_add_u64 v[214:215], s[26:27], 0, v[144:145]
	s_mov_b32 m0, s35
	s_nop 0
	global_load_lds_dwordx4 v[214:215], off
	s_barrier
	s_waitcnt lgkmcnt(0)
	s_setprio 1
	s_waitcnt lgkmcnt(0)
	v_mfma_f32_16x16x32_bf16 v[60:63], v[96:99], v[156:159], v[60:63]
	v_mfma_f32_16x16x32_bf16 v[56:59], v[120:123], v[156:159], v[56:59]
	v_mfma_f32_16x16x32_bf16 v[52:55], v[96:99], v[170:173], v[52:55]
	v_mfma_f32_16x16x32_bf16 v[44:47], v[120:123], v[170:173], v[44:47]
	v_mfma_f32_16x16x32_bf16 v[36:39], v[96:99], v[178:181], v[36:39]
	v_mfma_f32_16x16x32_bf16 v[28:31], v[120:123], v[178:181], v[28:31]
	v_mfma_f32_16x16x32_bf16 v[20:23], v[96:99], v[186:189], v[20:23]
	v_mfma_f32_16x16x32_bf16 v[8:11], v[120:123], v[186:189], v[8:11]
	v_mfma_f32_16x16x32_bf16 v[60:63], v[108:111], v[166:169], v[60:63]
	v_mfma_f32_16x16x32_bf16 v[56:59], v[132:135], v[166:169], v[56:59]
	v_mfma_f32_16x16x32_bf16 v[52:55], v[108:111], v[174:177], v[52:55]
	v_mfma_f32_16x16x32_bf16 v[44:47], v[132:135], v[174:177], v[44:47]
	v_mfma_f32_16x16x32_bf16 v[36:39], v[108:111], v[182:185], v[36:39]
	v_mfma_f32_16x16x32_bf16 v[28:31], v[132:135], v[182:185], v[28:31]
	v_mfma_f32_16x16x32_bf16 v[20:23], v[108:111], v[190:193], v[20:23]
	v_mfma_f32_16x16x32_bf16 v[8:11], v[132:135], v[190:193], v[8:11]
	s_setprio 0
	s_barrier
; #define PG8_STAGE(bufoff, gbase, voff) do { _Pragma("unroll") for (int _i = 0; _i < 2; ++_i) \
;         __builtin_amdgcn_global_load_lds((const unsigned*)((const char*)(gbase) + (voff)[_i]), (LAS unsigned*)(lds + (bufoff) + ldsw + _i * 8192), 16, 0, 0); } while (0)
; #define PG8_LDA(dst, b, h) do { _Pragma("unroll") for (int m = 0; m < 4; ++m) _Pragma("unroll") for (int k = 0; k < 2; ++k) dst[m][k] = *(const LAS bf16x8*)(lds + PG8_SA(b, h) + aoff + m * 2048 + k * 1024); } while (0)
; #define PG8_LDB(dst, b, h) do { _Pragma("unroll") for (int n = 0; n < 2; ++n) _Pragma("unroll") for (int k = 0; k < 2; ++k) dst[n][k] = *(const LAS bf16x8*)(lds + PG8_SB(b, h) + boff + n * 2048 + k * 1024); } while (0)
; #define PG8_MMA(ai, bj, At, Bt) do { __builtin_amdgcn_s_setprio(1); _Pragma("unroll") for (int m = 0; m < 4; ++m) _Pragma("unroll") for (int n = 0; n < 2; ++n) _Pragma("unroll") for (int k = 0; k < 2; ++k) \
;         acc[ai][bj][m][n] = __builtin_amdgcn_mfma_f32_16x16x32_bf16(Bt[n][k], At[m][k], acc[ai][bj][m][n], 0, 0, 0); __builtin_amdgcn_s_setprio(0); } while (0)
; #define PG8_WAIT_V(n) asm volatile("s_waitcnt vmcnt(" #n ")" ::: "memory")
; #define PG8_WAIT_L(n) asm volatile("s_waitcnt lgkmcnt(" #n ")" ::: "memory")
; #define PG8_BAR __builtin_amdgcn_s_barrier()
; #define PG8_SCHED __builtin_amdgcn_sched_barrier(0)
; template <class Epi>
; __device__ __forceinline__ void gemm_phase(LAS unsigned char* lds, const Gemm g, const StaticOrder& S, const Epi& E, int wave) {
;     ...
;             PG8_WAIT_V(6); PG8_BAR; PG8_MMA(1, 1, At, B1); PG8_BAR;
;             PG8_LDB(B0, 1, 0); PG8_SCHED; PG8_LDA(At, 1, 0); PG8_STAGE(PG8_SA(0, 1), a2 + hstep, voffA);
;             PG8_WAIT_L(8); PG8_BAR; PG8_WAIT_L(0); PG8_MMA(0, 0, At, B0); PG8_BAR; PG8_SCHED;
;             PG8_LDB(B1, 1, 1); PG8_STAGE(PG8_SB(1, 0), b3, voffB);
;             PG8_BAR; PG8_WAIT_L(0); PG8_MMA(0, 1, At, B1); PG8_BAR;
;             PG8_LDA(At, 1, 1); PG8_STAGE(PG8_SA(1, 0), a3, voffA);
;             PG8_BAR; PG8_WAIT_L(0); PG8_MMA(1, 0, At, B0); PG8_BAR; PG8_SCHED;
	s_add_u32 s20, s24, 0xb0000
	s_addc_u32 s21, s25, 0
	s_add_i32 s55, s47, s30
	v_lshl_add_u64 v[96:97], s[20:21], 0, v[146:147]
	s_mov_b32 m0, s55
	s_nop 0
	global_load_lds_dwordx4 v[96:97], off
	v_lshl_add_u64 v[96:97], s[20:21], 0, v[144:145]
	s_add_i32 m0, s55, 0x2000
	s_nop 0
	global_load_lds_dwordx4 v[96:97], off
	s_waitcnt vmcnt(6)
	s_barrier
	s_setprio 1
	v_mfma_f32_16x16x32_bf16 v[48:51], v[194:197], v[156:159], v[48:51]
	v_mfma_f32_16x16x32_bf16 v[40:43], v[202:205], v[156:159], v[40:43]
	v_mfma_f32_16x16x32_bf16 v[32:35], v[194:197], v[170:173], v[32:35]
	v_mfma_f32_16x16x32_bf16 v[24:27], v[202:205], v[170:173], v[24:27]
	v_mfma_f32_16x16x32_bf16 v[16:19], v[194:197], v[178:181], v[16:19]
	v_mfma_f32_16x16x32_bf16 v[12:15], v[202:205], v[178:181], v[12:15]
	v_mfma_f32_16x16x32_bf16 v[4:7], v[194:197], v[186:189], v[4:7]
	v_mfma_f32_16x16x32_bf16 v[0:3], v[202:205], v[186:189], v[0:3]
	v_mfma_f32_16x16x32_bf16 v[48:51], v[198:201], v[166:169], v[48:51]
	v_mfma_f32_16x16x32_bf16 v[40:43], v[206:209], v[166:169], v[40:43]
	v_mfma_f32_16x16x32_bf16 v[32:35], v[198:201], v[174:177], v[32:35]
	v_mfma_f32_16x16x32_bf16 v[24:27], v[206:209], v[174:177], v[24:27]
	v_mfma_f32_16x16x32_bf16 v[16:19], v[198:201], v[182:185], v[16:19]
	v_mfma_f32_16x16x32_bf16 v[12:15], v[206:209], v[182:185], v[12:15]
	v_mfma_f32_16x16x32_bf16 v[4:7], v[198:201], v[190:193], v[4:7]
	v_mfma_f32_16x16x32_bf16 v[0:3], v[206:209], v[190:193], v[0:3]
	s_setprio 0
	s_add_i32 s55, 0, 0x18000
	v_add_u32_e32 v132, s55, v162
	s_barrier
	ds_read_b128 v[96:99], v132
	ds_read_b128 v[108:111], v132 offset:1024
	ds_read_b128 v[120:123], v132 offset:2048
	ds_read_b128 v[132:135], v132 offset:3072
	s_add_u32 s20, s26, 0xb0000
	s_addc_u32 s21, s27, 0
	s_mov_b32 m0, s36
	v_lshl_add_u64 v[194:195], s[20:21], 0, v[146:147]
	ds_read_b128 v[156:159], v164 offset:32768
	ds_read_b128 v[166:169], v164 offset:33792
	ds_read_b128 v[170:173], v164 offset:34816
	ds_read_b128 v[174:177], v164 offset:35840
	ds_read_b128 v[178:181], v164 offset:36864
	ds_read_b128 v[182:185], v164 offset:37888
	ds_read_b128 v[186:189], v164 offset:38912
	ds_read_b128 v[190:193], v164 offset:39936
	global_load_lds_dwordx4 v[194:195], off
	v_lshl_add_u64 v[194:195], s[20:21], 0, v[144:145]
	s_mov_b32 m0, s37
	s_nop 0
	global_load_lds_dwordx4 v[194:195], off
	s_waitcnt lgkmcnt(8)
	s_barrier
	s_waitcnt lgkmcnt(0)
	s_setprio 1
	s_waitcnt lgkmcnt(0)
	v_mfma_f32_16x16x32_bf16 v[140:143], v[96:99], v[156:159], v[140:143]
	v_mfma_f32_16x16x32_bf16 v[136:139], v[120:123], v[156:159], v[136:139]
	v_mfma_f32_16x16x32_bf16 v[128:131], v[96:99], v[170:173], v[128:131]
	v_mfma_f32_16x16x32_bf16 v[124:127], v[120:123], v[170:173], v[124:127]
	v_mfma_f32_16x16x32_bf16 v[112:115], v[96:99], v[178:181], v[112:115]
	v_mfma_f32_16x16x32_bf16 v[100:103], v[120:123], v[178:181], v[100:103]
	v_mfma_f32_16x16x32_bf16 v[88:91], v[96:99], v[186:189], v[88:91]
	v_mfma_f32_16x16x32_bf16 v[80:83], v[120:123], v[186:189], v[80:83]
	v_mfma_f32_16x16x32_bf16 v[140:143], v[108:111], v[166:169], v[140:143]
	v_mfma_f32_16x16x32_bf16 v[136:139], v[132:135], v[166:169], v[136:139]
	v_mfma_f32_16x16x32_bf16 v[128:131], v[108:111], v[174:177], v[128:131]
	v_mfma_f32_16x16x32_bf16 v[124:127], v[132:135], v[174:177], v[124:127]
	v_mfma_f32_16x16x32_bf16 v[112:115], v[108:111], v[182:185], v[112:115]
	v_mfma_f32_16x16x32_bf16 v[100:103], v[132:135], v[182:185], v[100:103]
	v_mfma_f32_16x16x32_bf16 v[88:91], v[108:111], v[190:193], v[88:91]
	v_mfma_f32_16x16x32_bf16 v[80:83], v[132:135], v[190:193], v[80:83]
	s_setprio 0
	s_barrier
	s_add_i32 s26, 0, 0x1c000
	s_add_i32 s20, s55, s30
	v_add_u32_e32 v206, s26, v162
	v_lshl_add_u64 v[160:161], v[160:161], 0, s[12:13]
	s_mov_b32 m0, s20
	ds_read_b128 v[194:197], v206
	ds_read_b128 v[198:201], v206 offset:1024
	ds_read_b128 v[202:205], v206 offset:2048
	ds_read_b128 v[206:209], v206 offset:3072
	global_load_lds_dwordx4 v[160:161], off
	v_lshl_add_u64 v[160:161], v[210:211], 0, s[12:13]
	s_add_i32 m0, s20, 0x2000
	s_nop 0
	global_load_lds_dwordx4 v[160:161], off
	s_barrier
	s_waitcnt lgkmcnt(0)
	s_setprio 1
	s_waitcnt lgkmcnt(0)
	v_mfma_f32_16x16x32_bf16 v[116:119], v[194:197], v[156:159], v[116:119]
	v_mfma_f32_16x16x32_bf16 v[104:107], v[202:205], v[156:159], v[104:107]
	v_mfma_f32_16x16x32_bf16 v[92:95], v[194:197], v[170:173], v[92:95]
	v_mfma_f32_16x16x32_bf16 v[84:87], v[202:205], v[170:173], v[84:87]
	v_mfma_f32_16x16x32_bf16 v[76:79], v[194:197], v[178:181], v[76:79]
	v_mfma_f32_16x16x32_bf16 v[72:75], v[202:205], v[178:181], v[72:75]
	v_mfma_f32_16x16x32_bf16 v[68:71], v[194:197], v[186:189], v[68:71]
	v_mfma_f32_16x16x32_bf16 v[64:67], v[202:205], v[186:189], v[64:67]
	v_mfma_f32_16x16x32_bf16 v[116:119], v[198:201], v[166:169], v[116:119]
	v_mfma_f32_16x16x32_bf16 v[104:107], v[206:209], v[166:169], v[104:107]
	v_mfma_f32_16x16x32_bf16 v[92:95], v[198:201], v[174:177], v[92:95]
	v_mfma_f32_16x16x32_bf16 v[84:87], v[206:209], v[174:177], v[84:87]
	v_mfma_f32_16x16x32_bf16 v[76:79], v[198:201], v[182:185], v[76:79]
	v_mfma_f32_16x16x32_bf16 v[72:75], v[206:209], v[182:185], v[72:75]
	v_mfma_f32_16x16x32_bf16 v[68:71], v[198:201], v[190:193], v[68:71]
	v_mfma_f32_16x16x32_bf16 v[64:67], v[206:209], v[190:193], v[64:67]
	s_setprio 0
	s_mov_b32 m0, s44
	v_lshl_add_u64 v[160:161], v[212:213], 0, s[12:13]
	s_barrier
	ds_read_b128 v[156:159], v164 offset:49152
	ds_read_b128 v[166:169], v164 offset:50176
	ds_read_b128 v[170:173], v164 offset:51200
	ds_read_b128 v[174:177], v164 offset:52224
	ds_read_b128 v[178:181], v164 offset:53248
	ds_read_b128 v[182:185], v164 offset:54272
	ds_read_b128 v[186:189], v164 offset:55296
	ds_read_b128 v[190:193], v164 offset:56320
	global_load_lds_dwordx4 v[160:161], off
	v_lshl_add_u64 v[160:161], v[214:215], 0, s[12:13]
	s_mov_b32 m0, s45
	s_nop 0
	global_load_lds_dwordx4 v[160:161], off
	s_barrier
; #define PG8_STAGE(bufoff, gbase, voff) do { _Pragma("unroll") for (int _i = 0; _i < 2; ++_i) \
;         __builtin_amdgcn_global_load_lds((const unsigned*)((const char*)(gbase) + (voff)[_i]), (LAS unsigned*)(lds + (bufoff) + ldsw + _i * 8192), 16, 0, 0); } while (0)
; #define PG8_LDA(dst, b, h) do { _Pragma("unroll") for (int m = 0; m < 4; ++m) _Pragma("unroll") for (int k = 0; k < 2; ++k) dst[m][k] = *(const LAS bf16x8*)(lds + PG8_SA(b, h) + aoff + m * 2048 + k * 1024); } while (0)
; #define PG8_WAIT_V(n) asm volatile("s_waitcnt vmcnt(" #n ")" ::: "memory")
; #define PG8_WAIT_L(n) asm volatile("s_waitcnt lgkmcnt(" #n ")" ::: "memory")
; #define PG8_BAR __builtin_amdgcn_s_barrier()
; #define PG8_SCHED __builtin_amdgcn_sched_barrier(0)
; template <class Epi>
; __device__ __forceinline__ void gemm_phase(LAS unsigned char* lds, const Gemm g, const StaticOrder& S, const Epi& E, int wave) {
;     ...
;             PG8_BAR; PG8_WAIT_L(0); PG8_MMA(0, 1, At, B1); PG8_BAR;
;             PG8_LDA(At, 1, 1); PG8_STAGE(PG8_SA(1, 0), a3, voffA);
;             PG8_BAR; PG8_WAIT_L(0); PG8_MMA(1, 0, At, B0); PG8_BAR; PG8_SCHED;
;             PG8_STAGE(PG8_SB(1, 1), b3 + hstep, voffB);
;             PG8_WAIT_V(6); PG8_BAR; PG8_MMA(1, 1, At, B1); PG8_BAR;
;         }
;         E(acc, cur, wr, wc, fr, fq);
;     __device__ __forceinline__ void operator()(const f32x4 (&acc)[2][2][4][2], const pg8::Unit& u, int wr, int wc, int, int) const {
;     ...
;         const int row0 = u.pm * 256 + wr * 64 + fr, col0 = u.pn * 256 + wc * 32 + 4 * fq;
;         const int bi = batch_of(u.pm * 256);
;         const float* base = (u.pm * 256 < NPTOK) ? basep : bases - (size_t)NPTOK * D;
;         f32x4 gv[2][2];
; #pragma unroll
;         for (int bj = 0; bj < 2; ++bj)
; #pragma unroll
;             for (int n = 0; n < 2; ++n) gv[bj][n] = *(const f32x4*)(gate + (size_t)bi * MODW + col0 + bj * HALF + n * 16);
; #pragma unroll
;         for (int ai = 0; ai < 2; ++ai) {
;             f32x4 bv[4][2][2];
; #pragma unroll
;             for (int m = 0; m < 4; ++m) { const size_t off = (size_t)(row0 + ai * HALF + m * 16) * D + col0;
; #pragma unroll
;                 for (int bj = 0; bj < 2; ++bj)
; #pragma unroll
;                     for (int n = 0; n < 2; ++n) bv[m][bj][n] = *(const f32x4*)(base + off + bj * HALF + n * 16); }
	s_waitcnt lgkmcnt(0)
	s_setprio 1
	s_waitcnt lgkmcnt(0)
	v_mfma_f32_16x16x32_bf16 v[60:63], v[96:99], v[156:159], v[60:63]
	v_mfma_f32_16x16x32_bf16 v[56:59], v[120:123], v[156:159], v[56:59]
	v_mfma_f32_16x16x32_bf16 v[52:55], v[96:99], v[170:173], v[52:55]
	v_mfma_f32_16x16x32_bf16 v[44:47], v[120:123], v[170:173], v[44:47]
	v_mfma_f32_16x16x32_bf16 v[36:39], v[96:99], v[178:181], v[36:39]
	v_mfma_f32_16x16x32_bf16 v[28:31], v[120:123], v[178:181], v[28:31]
	v_mfma_f32_16x16x32_bf16 v[20:23], v[96:99], v[186:189], v[20:23]
	v_mfma_f32_16x16x32_bf16 v[8:11], v[120:123], v[186:189], v[8:11]
	v_mfma_f32_16x16x32_bf16 v[60:63], v[108:111], v[166:169], v[60:63]
	v_mfma_f32_16x16x32_bf16 v[56:59], v[132:135], v[166:169], v[56:59]
	v_mfma_f32_16x16x32_bf16 v[52:55], v[108:111], v[174:177], v[52:55]
	v_mfma_f32_16x16x32_bf16 v[44:47], v[132:135], v[174:177], v[44:47]
	v_mfma_f32_16x16x32_bf16 v[36:39], v[108:111], v[182:185], v[36:39]
	v_mfma_f32_16x16x32_bf16 v[28:31], v[132:135], v[182:185], v[28:31]
	v_mfma_f32_16x16x32_bf16 v[20:23], v[108:111], v[190:193], v[20:23]
	v_mfma_f32_16x16x32_bf16 v[8:11], v[132:135], v[190:193], v[8:11]
	s_setprio 0
	s_barrier
	s_add_u32 s20, s24, 0xb0080
	s_addc_u32 s21, s25, 0
	s_add_i32 s24, s26, s30
	v_lshl_add_u64 v[96:97], s[20:21], 0, v[146:147]
	s_mov_b32 m0, s24
	s_nop 0
	global_load_lds_dwordx4 v[96:97], off
	v_lshl_add_u64 v[96:97], s[20:21], 0, v[144:145]
	s_add_i32 m0, s24, 0x2000
	s_nop 0
	global_load_lds_dwordx4 v[96:97], off
	s_waitcnt vmcnt(6)
	s_barrier
	s_setprio 1
	v_mfma_f32_16x16x32_bf16 v[48:51], v[194:197], v[156:159], v[48:51]
	v_mfma_f32_16x16x32_bf16 v[40:43], v[202:205], v[156:159], v[40:43]
	v_mfma_f32_16x16x32_bf16 v[32:35], v[194:197], v[170:173], v[32:35]
	v_mfma_f32_16x16x32_bf16 v[24:27], v[202:205], v[170:173], v[24:27]
	v_mfma_f32_16x16x32_bf16 v[16:19], v[194:197], v[178:181], v[16:19]
	v_mfma_f32_16x16x32_bf16 v[12:15], v[202:205], v[178:181], v[12:15]
	v_mfma_f32_16x16x32_bf16 v[4:7], v[194:197], v[186:189], v[4:7]
	v_mfma_f32_16x16x32_bf16 v[0:3], v[202:205], v[186:189], v[0:3]
	v_mfma_f32_16x16x32_bf16 v[48:51], v[198:201], v[166:169], v[48:51]
	v_mfma_f32_16x16x32_bf16 v[40:43], v[206:209], v[166:169], v[40:43]
	v_mfma_f32_16x16x32_bf16 v[32:35], v[198:201], v[174:177], v[32:35]
	v_mfma_f32_16x16x32_bf16 v[24:27], v[206:209], v[174:177], v[24:27]
	v_mfma_f32_16x16x32_bf16 v[16:19], v[198:201], v[182:185], v[16:19]
	v_mfma_f32_16x16x32_bf16 v[12:15], v[206:209], v[182:185], v[12:15]
	v_mfma_f32_16x16x32_bf16 v[4:7], v[198:201], v[190:193], v[4:7]
	v_mfma_f32_16x16x32_bf16 v[0:3], v[206:209], v[190:193], v[0:3]
	s_setprio 0
	s_add_i32 s54, s54, 2
	s_add_u32 s52, s52, 0x100
	s_addc_u32 s53, s53, 0
	s_cmp_gt_u32 s54, 41
	s_mov_b64 s[20:21], s[22:23]
	s_barrier
	s_cbranch_scc0 .LBB0_889
	s_lshl_b32 s20, s50, 8
	v_mbcnt_lo_u32_b32 v158, -1, 0
	v_mbcnt_hi_u32_b32 v158, -1, v158
	s_add_i32 s22, s20, s42
	s_lshl_b32 s21, s51, 8
	v_ashrrev_i32_e32 v96, 2, v158
	s_min_i32 s20, s20, 0x10000
	s_or_b32 s21, s21, s43
	v_and_b32_e32 v96, -4, v96
	s_ashr_i32 s20, s20, 11
	v_add_u32_e32 v96, s21, v96
	s_mul_hi_i32 s21, s20, 0x6000
	s_mulk_i32 s20, 0x6000
	s_add_u32 s20, s39, s20
	v_ashrrev_i32_e32 v97, 31, v96
	s_addc_u32 s21, s40, s21
	v_lshlrev_b64 v[156:157], 2, v[96:97]
	v_lshl_add_u64 v[96:97], s[20:21], 0, v[156:157]
	v_and_or_b32 v214, v158, 15, s22
	v_readlane_b32 s20, v253, 8
	v_readlane_b32 s21, v253, 9
	v_ashrrev_i32_e32 v215, 31, v214
	v_lshlrev_b64 v[160:161], 12, v[214:215]
	v_lshl_add_u64 v[158:159], s[20:21], 0, v[156:157]
	v_or_b32_e32 v182, 16, v214
	v_lshl_add_u64 v[178:179], v[158:159], 0, v[160:161]
	v_ashrrev_i32_e32 v183, 31, v182
	global_load_dwordx4 v[132:135], v[96:97], off
	global_load_dwordx4 v[120:123], v[96:97], off offset:64
	global_load_dwordx4 v[108:111], v[96:97], off offset:512
	s_nop 0
	global_load_dwordx4 v[96:99], v[96:97], off offset:576
	s_nop 0
	global_load_dwordx4 v[166:169], v[178:179], off
	global_load_dwordx4 v[170:173], v[178:179], off offset:64
	global_load_dwordx4 v[174:177], v[178:179], off offset:512
	s_nop 0
	global_load_dwordx4 v[178:181], v[178:179], off offset:576
	v_lshlrev_b64 v[230:231], 12, v[182:183]
	v_or_b32_e32 v198, 32, v214
	v_lshl_add_u64 v[194:195], v[158:159], 0, v[230:231]
	v_ashrrev_i32_e32 v199, 31, v198
	global_load_dwordx4 v[182:185], v[194:195], off
	global_load_dwordx4 v[186:189], v[194:195], off offset:64
	global_load_dwordx4 v[190:193], v[194:195], off offset:512
	s_nop 0
	global_load_dwordx4 v[194:197], v[194:195], off offset:576
	v_lshlrev_b64 v[232:233], 12, v[198:199]
	v_or_b32_e32 v214, 48, v214
	v_lshl_add_u64 v[210:211], v[158:159], 0, v[232:233]
	v_ashrrev_i32_e32 v215, 31, v214
	global_load_dwordx4 v[198:201], v[210:211], off
	global_load_dwordx4 v[202:205], v[210:211], off offset:64
	global_load_dwordx4 v[206:209], v[210:211], off offset:512
	s_nop 0
	global_load_dwordx4 v[210:213], v[210:211], off offset:576
	v_lshlrev_b64 v[234:235], 12, v[214:215]
	v_lshl_add_u64 v[226:227], v[158:159], 0, v[234:235]
	global_load_dwordx4 v[214:217], v[226:227], off
	global_load_dwordx4 v[218:221], v[226:227], off offset:64
	global_load_dwordx4 v[222:225], v[226:227], off offset:512
	s_nop 0
	global_load_dwordx4 v[226:229], v[226:227], off offset:576
	v_readlane_b32 s22, v253, 10
	v_readlane_b32 s23, v253, 11
	s_and_b64 vcc, exec, s[0:1]
	s_mov_b32 s51, s48
	s_mov_b32 s50, s49
	s_mov_b64 s[22:23], s[4:5]
	s_waitcnt vmcnt(0)
;     __device__ __forceinline__ void operator()(const f32x4 (&acc)[2][2][4][2], const pg8::Unit& u, int wr, int wc, int, int) const {
;     ...
;         for (int ai = 0; ai < 2; ++ai) {
;             f32x4 bv[4][2][2];
; #pragma unroll
;             for (int m = 0; m < 4; ++m) { const size_t off = (size_t)(row0 + ai * HALF + m * 16) * D + col0;
; #pragma unroll
;                 for (int bj = 0; bj < 2; ++bj)
; #pragma unroll
;                     for (int n = 0; n < 2; ++n) bv[m][bj][n] = *(const f32x4*)(base + off + bj * HALF + n * 16); }
; #pragma unroll
;             for (int m = 0; m < 4; ++m) { const size_t off = (size_t)(row0 + ai * HALF + m * 16) * D + col0;
; #pragma unroll
;                 for (int bj = 0; bj < 2; ++bj)
; #pragma unroll
;                     for (int n = 0; n < 2; ++n) *(f32x4*)(out + off + bj * HALF + n * 16) = bv[m][bj][n] + gv[bj][n] * acc[ai][bj][m][n]; }
	v_pk_fma_f32 v[140:141], v[140:141], v[132:133], v[166:167]
	v_lshl_add_u64 v[166:167], s[20:21], 0, v[160:161]
	v_lshl_add_u64 v[166:167], v[166:167], 0, v[156:157]
	v_pk_fma_f32 v[118:119], v[118:119], v[110:111], v[176:177]
	v_pk_fma_f32 v[116:117], v[116:117], v[108:109], v[174:175]
	global_store_dwordx4 v[166:167], v[116:119], off offset:512 sc1
	v_pk_fma_f32 v[106:107], v[106:107], v[98:99], v[180:181]
	v_pk_fma_f32 v[94:95], v[94:95], v[110:111], v[192:193]
	v_lshl_add_u64 v[116:117], s[20:21], 0, v[230:231]
	v_lshl_add_u64 v[116:117], v[116:117], 0, v[156:157]
	v_pk_fma_f32 v[92:93], v[92:93], v[108:109], v[190:191]
	global_store_dwordx4 v[116:117], v[92:95], off offset:512 sc1
	v_pk_fma_f32 v[78:79], v[78:79], v[110:111], v[208:209]
	v_pk_fma_f32 v[76:77], v[76:77], v[108:109], v[206:207]
	v_lshl_add_u64 v[92:93], s[20:21], 0, v[232:233]
	v_lshl_add_u64 v[92:93], v[92:93], 0, v[156:157]
	v_pk_fma_f32 v[104:105], v[104:105], v[96:97], v[178:179]
	v_pk_fma_f32 v[86:87], v[86:87], v[98:99], v[196:197]
	v_pk_fma_f32 v[84:85], v[84:85], v[96:97], v[194:195]
	global_store_dwordx4 v[92:93], v[76:79], off offset:512 sc1
	v_pk_fma_f32 v[74:75], v[74:75], v[98:99], v[212:213]
	v_pk_fma_f32 v[72:73], v[72:73], v[96:97], v[210:211]
	v_lshl_add_u64 v[76:77], s[20:21], 0, v[234:235]
	global_store_dwordx4 v[166:167], v[104:107], off offset:576 sc1
	global_store_dwordx4 v[116:117], v[84:87], off offset:576 sc1
	global_store_dwordx4 v[92:93], v[72:75], off offset:576 sc1
	v_pk_fma_f32 v[106:107], v[130:131], v[134:135], v[184:185]
	v_pk_fma_f32 v[104:105], v[128:129], v[132:133], v[182:183]
	v_pk_fma_f32 v[86:87], v[114:115], v[134:135], v[200:201]
	v_pk_fma_f32 v[84:85], v[112:113], v[132:133], v[198:199]
	v_pk_fma_f32 v[74:75], v[90:91], v[134:135], v[216:217]
	v_pk_fma_f32 v[72:73], v[88:89], v[132:133], v[214:215]
	v_lshl_add_u64 v[76:77], v[76:77], 0, v[156:157]
	v_pk_fma_f32 v[142:143], v[142:143], v[134:135], v[168:169]
	v_pk_fma_f32 v[138:139], v[138:139], v[122:123], v[172:173]
	v_pk_fma_f32 v[136:137], v[136:137], v[120:121], v[170:171]
	global_store_dwordx4 v[116:117], v[104:107], off sc1
	global_store_dwordx4 v[92:93], v[84:87], off sc1
	global_store_dwordx4 v[76:77], v[72:75], off sc1
	v_pk_fma_f32 v[106:107], v[126:127], v[122:123], v[188:189]
	v_pk_fma_f32 v[104:105], v[124:125], v[120:121], v[186:187]
	v_pk_fma_f32 v[86:87], v[102:103], v[122:123], v[204:205]
	v_pk_fma_f32 v[84:85], v[100:101], v[120:121], v[202:203]
	v_pk_fma_f32 v[74:75], v[82:83], v[122:123], v[220:221]
	v_pk_fma_f32 v[72:73], v[80:81], v[120:121], v[218:219]
	v_pk_fma_f32 v[70:71], v[70:71], v[110:111], v[224:225]
	v_pk_fma_f32 v[68:69], v[68:69], v[108:109], v[222:223]
	v_pk_fma_f32 v[66:67], v[66:67], v[98:99], v[228:229]
	v_pk_fma_f32 v[64:65], v[64:65], v[96:97], v[226:227]
	v_lshl_add_u64 v[118:119], v[160:161], 0, s[14:15]
	global_store_dwordx4 v[166:167], v[140:143], off sc1
	global_store_dwordx4 v[166:167], v[136:139], off offset:64 sc1
	global_store_dwordx4 v[116:117], v[104:107], off offset:64 sc1
	global_store_dwordx4 v[92:93], v[84:87], off offset:64 sc1
	global_store_dwordx4 v[76:77], v[72:75], off offset:64 sc1
	global_store_dwordx4 v[76:77], v[68:71], off offset:512 sc1
	global_store_dwordx4 v[76:77], v[64:67], off offset:576 sc1
	v_lshl_add_u64 v[106:107], v[160:161], 0, s[16:17]
	v_lshl_add_u64 v[104:105], v[160:161], 0, s[18:19]
	v_lshl_add_u64 v[64:65], v[158:159], 0, v[118:119]
	global_load_dwordx4 v[114:117], v[64:65], off
	global_load_dwordx4 v[100:103], v[64:65], off offset:64
	global_load_dwordx4 v[84:87], v[64:65], off offset:512
	global_load_dwordx4 v[76:79], v[64:65], off offset:576
	v_lshl_add_u64 v[64:65], v[158:159], 0, v[106:107]
	global_load_dwordx4 v[80:83], v[64:65], off
	global_load_dwordx4 v[72:75], v[64:65], off offset:64
	global_load_dwordx4 v[68:71], v[64:65], off offset:512
	s_nop 0
	global_load_dwordx4 v[64:67], v[64:65], off offset:576
	v_lshl_add_u64 v[88:89], v[158:159], 0, v[104:105]
	v_lshl_add_u64 v[112:113], v[160:161], 0, s[10:11]
	global_load_dwordx4 v[124:127], v[88:89], off
	global_load_dwordx4 v[128:131], v[88:89], off offset:64
	global_load_dwordx4 v[136:139], v[88:89], off offset:512
	global_load_dwordx4 v[140:143], v[88:89], off offset:576
	v_lshl_add_u64 v[88:89], v[158:159], 0, v[112:113]
	global_load_dwordx4 v[158:161], v[88:89], off
	global_load_dwordx4 v[166:169], v[88:89], off offset:64
	global_load_dwordx4 v[92:95], v[88:89], off offset:512
	s_nop 0
	global_load_dwordx4 v[88:91], v[88:89], off offset:576
	s_waitcnt vmcnt(0)
; #define PG8_WAIT_V(n) asm volatile("s_waitcnt vmcnt(" #n ")" ::: "memory")
; #define PG8_BAR __builtin_amdgcn_s_barrier()
; template <class Epi>
; __device__ __forceinline__ void gemm_phase(LAS unsigned char* lds, const Gemm g, const StaticOrder& S, const Epi& E, int wave) {
;     ...
;         E(acc, cur, wr, wc, fr, fq);
;         if (!has_next) break;
; #pragma unroll
;         for (int a = 0; a < 2; ++a)
; #pragma unroll
;             for (int b = 0; b < 2; ++b)
; #pragma unroll
;                 for (int m = 0; m < 4; ++m)
; #pragma unroll
;                     for (int n = 0; n < 2; ++n) acc[a][b][m][n] = (f32x4){0.f, 0.f, 0.f, 0.f};
;         cur = nxt; cA = nA; cB = nB; ++ui;
;     }
;     PG8_WAIT_V(0);
;     if (wr == 0) PG8_BAR;
;     PG8_BAR;
;     __device__ __forceinline__ void operator()(const f32x4 (&acc)[2][2][4][2], const pg8::Unit& u, int wr, int wc, int, int) const {
;     ...
;             for (int m = 0; m < 4; ++m) { const size_t off = (size_t)(row0 + ai * HALF + m * 16) * D + col0;
; #pragma unroll
;                 for (int bj = 0; bj < 2; ++bj)
; #pragma unroll
;                     for (int n = 0; n < 2; ++n) *(f32x4*)(out + off + bj * HALF + n * 16) = bv[m][bj][n] + gv[bj][n] * acc[ai][bj][m][n]; }
	v_pk_fma_f32 v[60:61], v[60:61], v[132:133], v[114:115]
	v_lshl_add_u64 v[114:115], s[20:21], 0, v[118:119]
	v_lshl_add_u64 v[114:115], v[114:115], 0, v[156:157]
	v_pk_fma_f32 v[50:51], v[50:51], v[110:111], v[86:87]
	v_pk_fma_f32 v[48:49], v[48:49], v[108:109], v[84:85]
	global_store_dwordx4 v[114:115], v[48:51], off offset:512 sc1
	v_pk_fma_f32 v[34:35], v[34:35], v[110:111], v[70:71]
	v_pk_fma_f32 v[32:33], v[32:33], v[108:109], v[68:69]
	v_lshl_add_u64 v[48:49], s[20:21], 0, v[106:107]
	v_lshl_add_u64 v[48:49], v[48:49], 0, v[156:157]
	global_store_dwordx4 v[48:49], v[32:35], off offset:512 sc1
	v_pk_fma_f32 v[42:43], v[42:43], v[98:99], v[78:79]
	v_pk_fma_f32 v[40:41], v[40:41], v[96:97], v[76:77]
	v_lshl_add_u64 v[32:33], s[20:21], 0, v[104:105]
	v_pk_fma_f32 v[26:27], v[26:27], v[98:99], v[66:67]
	v_pk_fma_f32 v[24:25], v[24:25], v[96:97], v[64:65]
	v_lshl_add_u64 v[32:33], v[32:33], 0, v[156:157]
	v_pk_fma_f32 v[18:19], v[18:19], v[110:111], v[138:139]
	v_pk_fma_f32 v[16:17], v[16:17], v[108:109], v[136:137]
	global_store_dwordx4 v[114:115], v[40:43], off offset:576 sc1
	global_store_dwordx4 v[48:49], v[24:27], off offset:576 sc1
	global_store_dwordx4 v[32:33], v[16:19], off offset:512 sc1
	v_pk_fma_f32 v[42:43], v[54:55], v[134:135], v[82:83]
	v_pk_fma_f32 v[40:41], v[52:53], v[132:133], v[80:81]
	v_pk_fma_f32 v[26:27], v[38:39], v[134:135], v[126:127]
	v_pk_fma_f32 v[24:25], v[36:37], v[132:133], v[124:125]
	v_pk_fma_f32 v[14:15], v[14:15], v[98:99], v[142:143]
	v_pk_fma_f32 v[12:13], v[12:13], v[96:97], v[140:141]
	v_lshl_add_u64 v[16:17], s[20:21], 0, v[112:113]
	v_pk_fma_f32 v[62:63], v[62:63], v[134:135], v[116:117]
	v_pk_fma_f32 v[58:59], v[58:59], v[122:123], v[102:103]
	v_pk_fma_f32 v[56:57], v[56:57], v[120:121], v[100:101]
	global_store_dwordx4 v[48:49], v[40:43], off sc1
	global_store_dwordx4 v[32:33], v[24:27], off sc1
	global_store_dwordx4 v[32:33], v[12:15], off offset:576 sc1
	v_pk_fma_f32 v[42:43], v[46:47], v[122:123], v[74:75]
	v_pk_fma_f32 v[40:41], v[44:45], v[120:121], v[72:73]
	v_pk_fma_f32 v[26:27], v[30:31], v[122:123], v[130:131]
	v_pk_fma_f32 v[24:25], v[28:29], v[120:121], v[128:129]
	v_pk_fma_f32 v[14:15], v[22:23], v[134:135], v[160:161]
	v_pk_fma_f32 v[12:13], v[20:21], v[132:133], v[158:159]
	v_lshl_add_u64 v[16:17], v[16:17], 0, v[156:157]
	v_pk_fma_f32 v[10:11], v[10:11], v[122:123], v[168:169]
	v_pk_fma_f32 v[8:9], v[8:9], v[120:121], v[166:167]
	v_pk_fma_f32 v[6:7], v[6:7], v[110:111], v[94:95]
	v_pk_fma_f32 v[4:5], v[4:5], v[108:109], v[92:93]
	v_pk_fma_f32 v[2:3], v[2:3], v[98:99], v[90:91]
	v_pk_fma_f32 v[0:1], v[0:1], v[96:97], v[88:89]
	s_mov_b64 s[20:21], s[6:7]
	global_store_dwordx4 v[114:115], v[60:63], off sc1
	global_store_dwordx4 v[114:115], v[56:59], off offset:64 sc1
	global_store_dwordx4 v[48:49], v[40:43], off offset:64 sc1
	global_store_dwordx4 v[32:33], v[24:27], off offset:64 sc1
	global_store_dwordx4 v[16:17], v[12:15], off sc1
	global_store_dwordx4 v[16:17], v[8:11], off offset:64 sc1
	global_store_dwordx4 v[16:17], v[4:7], off offset:512 sc1
	global_store_dwordx4 v[16:17], v[0:3], off offset:576 sc1
	s_cbranch_vccz .LBB0_882
	s_waitcnt vmcnt(0)
	s_cmpk_gt_u32 s3, 0xff
	s_cbranch_scc1 .LBB0_893
	s_barrier
